# non-temporal (nt) policy on the read-once f32 weight loads of the conversion loops
# speedup vs baseline: 1.0174x; 1.0174x over previous
; #define LAS __attribute__((address_space(3)))
; template <int KIND>
; DI void transpose_item(const float* W, int K, int N, bf16_t* WT, int ldk, const float* g0, const float* g1, const float* g2, LAS float* scr, int item, int lane) {
;     const int nblk = N / 32, kb = item / nblk, nb = item % nblk, k0 = 64 * kb, n0 = 32 * nb;
;     f32x4 tv[8];
; #pragma unroll
;     for (int i = 0; i < 8; ++i) tv[i] = *(const f32x4*)(W + (size_t)(k0 + 8 * i + (lane >> 3)) * N + n0 + 4 * (lane & 7));
; #pragma unroll
;     for (int i = 0; i < 8; ++i) {
;         const int kk = 8 * i + (lane >> 3), k = k0 + kk;
;         float gn = 1.f;
;         if (KIND == 0 || KIND == 1 || KIND == 2 || KIND == 5 || KIND == 6) gn = g0[k];
;         if (KIND == 4) gn = k < 1024 ? g0[k] : (k < 1536 ? g1[k - 1024] : g2[k - 1536]);
;         LAS float* d = scr + kk * 33 + 4 * (lane & 7);
;         d[0] = tv[i][0] * gn; d[1] = tv[i][1] * gn; d[2] = tv[i][2] * gn; d[3] = tv[i][3] * gn;
;     }
;     asm volatile("s_waitcnt lgkmcnt(0)" ::: "memory");
;     int kd0 = k0;
;     if (KIND == 4) kd0 = k0 < 1024 ? k0 + 512 : (k0 < 1536 ? k0 - 1024 : k0);
;     const int c = lane & 7;
; #pragma unroll
;     for (int j = 0; j < 4; ++j) { const int n = (lane >> 3) + 8 * j; const LAS float* s = scr + (8 * c) * 33 + n;
;         u32x4 o; o.x = cvtpk(s[0 * 33], s[1 * 33]); o.y = cvtpk(s[2 * 33], s[3 * 33]); o.z = cvtpk(s[4 * 33], s[5 * 33]); o.w = cvtpk(s[6 * 33], s[7 * 33]);
;         *(u32x4*)(WT + (size_t)map_n<KIND>(n0 + n) * ldk + kd0 + 8 * c) = o; }
;     asm volatile("s_waitcnt lgkmcnt(0)" ::: "memory");
; }
; DI void convert_weights(PP p, LAS unsigned char* lds, int l, int worker, int nworkers) {
;     ...
;     for (int it = worker; it < I_LAYER; it += nworkers) {
;         int r = it;
;         if (r < I_IN) { transpose_item<0>(p->in[2] + (size_t)l * 2048 * 2880, 2048, 2880, (bf16_t*)(wl + W_IN), 2048, p->in[1] + l * 2048, nullptr, nullptr, scr, r, lane); continue; } r -= I_IN;
;         if (r < I_UQ) { transpose_item<1>(p->in[4] + (size_t)l * 512 * 1536, 512, 1536, (bf16_t*)(wl + W_UQ), 512, p->in[3] + l * 512, nullptr, nullptr, scr, r, lane); continue; } r -= I_UQ;
;         if (r < I_UKV) { transpose_item<2>(p->in[6] + (size_t)l * 256 * 2048, 256, 2048, (bf16_t*)(wl + W_UKV), 256, p->in[5] + l * 256, nullptr, nullptr, scr, r, lane); continue; } r -= I_UKV;
.LBB0_53:
	s_movk_i32 s6, 0xb3f
	v_cmp_lt_i32_e32 vcc, s6, v1
	s_and_saveexec_b64 s[6:7], vcc
	s_xor_b64 s[56:57], exec, s[6:7]
	s_cbranch_execz .LBB0_143
	s_movk_i32 s6, 0xcbf
	v_cmp_lt_u32_e32 vcc, s6, v1
	s_and_saveexec_b64 s[6:7], vcc
	s_xor_b64 s[58:59], exec, s[6:7]
	s_cbranch_execz .LBB0_140
	s_movk_i32 s6, 0xdbf
	v_cmp_lt_u32_e32 vcc, s6, v1
	s_and_saveexec_b64 s[6:7], vcc
	s_xor_b64 s[60:61], exec, s[6:7]
	s_cbranch_execz .LBB0_137
	s_movk_i32 s6, 0xebf
	v_cmp_lt_u32_e32 vcc, s6, v1
	s_and_saveexec_b64 s[6:7], vcc
	s_xor_b64 s[62:63], exec, s[6:7]
	s_cbranch_execz .LBB0_134
	s_movk_i32 s6, 0x16bf
	v_cmp_lt_u32_e32 vcc, s6, v1
	s_and_saveexec_b64 s[6:7], vcc
	s_xor_b64 s[6:7], exec, s[6:7]
	s_cbranch_execz .LBB0_67
	s_movk_i32 s8, 0x2cbf
	v_cmp_lt_u32_e32 vcc, s8, v1
	s_and_saveexec_b64 s[8:9], vcc
	s_xor_b64 s[8:9], exec, s[8:9]
	s_cbranch_execz .LBB0_64
	s_movk_i32 s10, 0x42bf
	v_cmp_lt_u32_e32 vcc, s10, v1
	s_and_saveexec_b64 s[10:11], vcc
	s_xor_b64 s[10:11], exec, s[10:11]
	s_cbranch_execz .LBB0_61
	s_load_dwordx2 s[12:13], s[4:5], 0xc0
	v_add_u32_e32 v2, 0xffffbd40, v1
	v_and_b32_e32 v55, 0x1fc0, v2
	v_add_u32_e32 v2, 0xfff7a800, v52
	v_and_b32_e32 v88, 0x7e0, v2
	v_lshlrev_b32_e32 v2, 2, v88
	v_mov_b32_e32 v3, v37
	v_or_b32_e32 v4, v55, v34
	s_waitcnt lgkmcnt(0)
	v_lshl_add_u64 v[2:3], s[12:13], 0, v[2:3]
	v_lshl_add_u64 v[2:3], v[2:3], 0, v[36:37]
	v_lshlrev_b32_e32 v4, 13, v4
	v_mov_b32_e32 v5, v37
	v_lshl_add_u64 v[30:31], v[2:3], 0, v[4:5]
	v_add_co_u32_e32 v6, vcc, s66, v30
	v_mov_b32_e32 v57, v37
	s_nop 0
	v_addc_co_u32_e32 v7, vcc, 0, v31, vcc
	v_add_co_u32_e32 v10, vcc, s67, v30
	global_load_dwordx4 v[2:5], v[30:31], off nt
	s_nop 0
	global_load_dwordx4 v[6:9], v[6:7], off nt
	v_addc_co_u32_e32 v11, vcc, 0, v31, vcc
	v_add_co_u32_e32 v14, vcc, s68, v30
	v_lshlrev_b32_e32 v56, 1, v55
	s_nop 0
	v_addc_co_u32_e32 v15, vcc, 0, v31, vcc
	v_add_co_u32_e32 v18, vcc, s69, v30
	global_load_dwordx4 v[10:13], v[10:11], off nt
	s_nop 0
	global_load_dwordx4 v[14:17], v[14:15], off nt
	v_addc_co_u32_e32 v19, vcc, 0, v31, vcc
	v_add_co_u32_e32 v22, vcc, s70, v30
	v_or_b32_e32 v55, v88, v34
	s_nop 0
	v_addc_co_u32_e32 v23, vcc, 0, v31, vcc
	global_load_dwordx4 v[18:21], v[18:19], off nt
	s_nop 0
	global_load_dwordx4 v[22:25], v[22:23], off nt
	v_add_co_u32_e32 v26, vcc, s71, v30
	v_mov_b32_e32 v85, v37
	s_nop 0
	v_addc_co_u32_e32 v27, vcc, 0, v31, vcc
	global_load_dwordx4 v[26:29], v[26:27], off nt
	v_add_co_u32_e32 v30, vcc, s72, v30
	v_lshl_add_u64 v[56:57], v[38:39], 0, v[56:57]
	s_nop 0
	v_addc_co_u32_e32 v31, vcc, 0, v31, vcc
	global_load_dwordx4 v[30:33], v[30:31], off nt
	v_mul_u32_u24_e32 v84, 0x2c00, v55
	v_lshl_add_u64 v[84:85], v[56:57], 0, v[84:85]
	v_or_b32_e32 v86, v88, v53
	v_mov_b32_e32 v87, v37
	v_mul_u32_u24_e32 v86, 0x2c00, v86
	v_lshl_add_u64 v[86:87], v[56:57], 0, v[86:87]
	s_waitcnt vmcnt(7)
	ds_write2_b32 v65, v2, v3 offset1:1
	ds_write2_b32 v65, v4, v5 offset0:2 offset1:3
	s_waitcnt vmcnt(6)
	ds_write2_b32 v66, v6, v7 offset1:1
	ds_write2_b32 v67, v8, v9 offset1:1
	s_waitcnt vmcnt(5)
	ds_write2_b32 v68, v10, v11 offset1:1
	ds_write2_b32 v69, v12, v13 offset1:1
	s_waitcnt vmcnt(4)
	ds_write2_b32 v70, v14, v15 offset1:1
	ds_write2_b32 v71, v16, v17 offset1:1
	s_waitcnt vmcnt(3)
	ds_write2_b32 v72, v18, v19 offset1:1
	ds_write2_b32 v73, v20, v21 offset1:1
	s_waitcnt vmcnt(2)
	ds_write2_b32 v74, v22, v23 offset1:1
	ds_write2_b32 v75, v24, v25 offset1:1
	s_waitcnt vmcnt(1)
	ds_write2_b32 v76, v26, v27 offset1:1
	ds_write2_b32 v77, v28, v29 offset1:1
	s_waitcnt vmcnt(0)
	ds_write2_b32 v78, v30, v31 offset1:1
	ds_write2_b32 v79, v32, v33 offset1:1
	s_waitcnt lgkmcnt(0)
	ds_read2_b32 v[6:7], v60 offset0:33 offset1:41
	ds_read2_b32 v[8:9], v60 offset1:8
	ds_read2_b32 v[10:11], v60 offset0:66 offset1:74
	ds_read2_b32 v[12:13], v60 offset0:99 offset1:107
	ds_read2_b32 v[14:15], v60 offset0:132 offset1:140
	ds_read2_b32 v[16:17], v60 offset0:165 offset1:173
	ds_read2_b32 v[18:19], v60 offset0:198 offset1:206
	ds_read2_b32 v[20:21], v60 offset0:231 offset1:239
	ds_read2_b32 v[22:23], v60 offset0:16 offset1:24
	ds_read2_b32 v[24:25], v60 offset0:49 offset1:57
	ds_read2_b32 v[26:27], v60 offset0:82 offset1:90
	ds_read2_b32 v[28:29], v60 offset0:115 offset1:123
	s_waitcnt lgkmcnt(10)
	v_cvt_pk_bf16_f32 v2, v8, v6
	s_waitcnt lgkmcnt(8)
	v_cvt_pk_bf16_f32 v3, v10, v12
	s_waitcnt lgkmcnt(6)
	v_cvt_pk_bf16_f32 v4, v14, v16
	s_waitcnt lgkmcnt(4)
	v_cvt_pk_bf16_f32 v5, v18, v20
	global_store_dwordx4 v[84:85], v[2:5], off
	v_cvt_pk_bf16_f32 v6, v9, v7
	v_cvt_pk_bf16_f32 v7, v11, v13
	v_cvt_pk_bf16_f32 v8, v15, v17
	ds_read2_b32 v[10:11], v60 offset0:148 offset1:156
	ds_read2_b32 v[12:13], v60 offset0:181 offset1:189
	ds_read2_b32 v[14:15], v60 offset0:214 offset1:222
	ds_read2_b32 v[16:17], v60 offset0:247 offset1:255
	v_cvt_pk_bf16_f32 v9, v19, v21
	global_store_dwordx4 v[86:87], v[6:9], off
	s_waitcnt lgkmcnt(6)
	v_cvt_pk_bf16_f32 v2, v22, v24
	s_waitcnt lgkmcnt(4)
	v_cvt_pk_bf16_f32 v3, v26, v28
	v_or_b32_e32 v6, v88, v58
	v_mul_u32_u24_e32 v6, 0x2c00, v6
	v_mov_b32_e32 v7, v37
	s_waitcnt lgkmcnt(2)
	v_cvt_pk_bf16_f32 v4, v10, v12
	s_waitcnt lgkmcnt(0)
	v_cvt_pk_bf16_f32 v5, v14, v16
	v_lshl_add_u64 v[6:7], v[56:57], 0, v[6:7]
	global_store_dwordx4 v[6:7], v[2:5], off
	v_or_b32_e32 v6, v88, v59
	v_mul_u32_u24_e32 v6, 0x2c00, v6
	v_mov_b32_e32 v7, v37
	v_cvt_pk_bf16_f32 v2, v23, v25
	v_cvt_pk_bf16_f32 v3, v27, v29
	v_cvt_pk_bf16_f32 v4, v11, v13
	v_cvt_pk_bf16_f32 v5, v15, v17
	v_lshl_add_u64 v[6:7], v[56:57], 0, v[6:7]
	global_store_dwordx4 v[6:7], v[2:5], off
	s_waitcnt lgkmcnt(0)
; #define LAS __attribute__((address_space(3)))
; DI unsigned cvtpk(float lo, float hi) { f32x2 v = {lo, hi}; bf16x2_t b = __builtin_convertvector(v, bf16x2_t); return __builtin_bit_cast(unsigned, b); }
; template <int KIND>
; DI void transpose_item(const float* W, int K, int N, bf16_t* WT, int ldk, const float* g0, const float* g1, const float* g2, LAS float* scr, int item, int lane) {
;     const int nblk = N / 32, kb = item / nblk, nb = item % nblk, k0 = 64 * kb, n0 = 32 * nb;
;     f32x4 tv[8];
; #pragma unroll
;     for (int i = 0; i < 8; ++i) tv[i] = *(const f32x4*)(W + (size_t)(k0 + 8 * i + (lane >> 3)) * N + n0 + 4 * (lane & 7));
; #pragma unroll
;     for (int i = 0; i < 8; ++i) {
;         const int kk = 8 * i + (lane >> 3), k = k0 + kk;
;         float gn = 1.f;
;         if (KIND == 0 || KIND == 1 || KIND == 2 || KIND == 5 || KIND == 6) gn = g0[k];
;         if (KIND == 4) gn = k < 1024 ? g0[k] : (k < 1536 ? g1[k - 1024] : g2[k - 1536]);
;         LAS float* d = scr + kk * 33 + 4 * (lane & 7);
;         d[0] = tv[i][0] * gn; d[1] = tv[i][1] * gn; d[2] = tv[i][2] * gn; d[3] = tv[i][3] * gn;
;     }
;     asm volatile("s_waitcnt lgkmcnt(0)" ::: "memory");
;     int kd0 = k0;
;     if (KIND == 4) kd0 = k0 < 1024 ? k0 + 512 : (k0 < 1536 ? k0 - 1024 : k0);
;     const int c = lane & 7;
; #pragma unroll
;     for (int j = 0; j < 4; ++j) { const int n = (lane >> 3) + 8 * j; const LAS float* s = scr + (8 * c) * 33 + n;
;         u32x4 o; o.x = cvtpk(s[0 * 33], s[1 * 33]); o.y = cvtpk(s[2 * 33], s[3 * 33]); o.z = cvtpk(s[4 * 33], s[5 * 33]); o.w = cvtpk(s[6 * 33], s[7 * 33]);
;         *(u32x4*)(WT + (size_t)map_n<KIND>(n0 + n) * ldk + kd0 + 8 * c) = o; }
;     asm volatile("s_waitcnt lgkmcnt(0)" ::: "memory");
; }
.LBB0_61:
	s_andn2_saveexec_b64 s[10:11], s[10:11]
	s_cbranch_execz .LBB0_63
	v_add_u16_e32 v2, 0xd340, v1
	v_mul_u32_u24_e32 v3, 0xba2f, v2
	s_load_dwordx2 s[12:13], s[4:5], 0xa8
	s_load_dwordx2 s[14:15], s[4:5], 0xb8
	v_lshrrev_b32_e32 v3, 23, v3
	v_mul_lo_u16_e32 v4, 0xb0, v3
	v_sub_u16_e32 v2, v2, v4
	v_lshlrev_b16_e32 v55, 6, v3
	v_lshlrev_b16_e32 v57, 5, v2
	v_or_b32_e32 v20, v34, v55
	v_lshlrev_b32_e32 v2, 2, v57
	v_mov_b32_e32 v3, v37
	s_waitcnt lgkmcnt(0)
	v_lshl_add_u64 v[2:3], s[14:15], 0, v[2:3]
	v_mul_u32_u24_e32 v4, 0x1600, v20
	v_lshl_add_u64 v[2:3], v[2:3], 0, v[36:37]
	v_lshlrev_b32_e32 v4, 2, v4
	v_mov_b32_e32 v5, v37
	v_lshl_add_u64 v[30:31], v[2:3], 0, v[4:5]
	v_add_co_u32_e32 v6, vcc, s73, v30
	v_lshlrev_b32_e32 v32, 2, v20
	s_nop 0
	v_addc_co_u32_e32 v7, vcc, 0, v31, vcc
	v_add_co_u32_e32 v10, vcc, s74, v30
	global_load_dwordx4 v[2:5], v[30:31], off nt
	s_nop 0
	global_load_dwordx4 v[6:9], v[6:7], off nt
	v_addc_co_u32_e32 v11, vcc, 0, v31, vcc
	v_add_co_u32_e32 v14, vcc, s75, v30
	v_add_u32_e32 v85, v35, v61
	s_nop 0
	v_addc_co_u32_e32 v15, vcc, 0, v31, vcc
	v_add_co_u32_e32 v18, vcc, s76, v30
	global_load_dwordx4 v[10:13], v[10:11], off nt
	s_nop 0
	global_load_dwordx4 v[14:17], v[14:15], off nt
	v_addc_co_u32_e32 v19, vcc, 0, v31, vcc
	v_add_co_u32_e32 v22, vcc, s77, v30
	global_load_dword v56, v32, s[12:13]
	s_nop 0
	v_addc_co_u32_e32 v23, vcc, 0, v31, vcc
	v_add_co_u32_e32 v26, vcc, s78, v30
	global_load_dwordx4 v[18:21], v[18:19], off nt
	s_nop 0
	global_load_dwordx4 v[22:25], v[22:23], off nt
	s_nop 0
	global_load_dword v84, v32, s[12:13] offset:32
	global_load_dword v86, v32, s[12:13] offset:64
	global_load_dword v88, v32, s[12:13] offset:96
	global_load_dword v90, v32, s[12:13] offset:128
	v_addc_co_u32_e32 v27, vcc, 0, v31, vcc
	v_add_co_u32_e32 v30, vcc, s79, v30
	global_load_dword v92, v32, s[12:13] offset:160
	s_nop 0
	global_load_dwordx4 v[26:29], v[26:27], off nt
	s_nop 0
	global_load_dword v94, v32, s[12:13] offset:192
	v_addc_co_u32_e32 v31, vcc, 0, v31, vcc
	global_load_dword v96, v32, s[12:13] offset:224
	s_nop 0
	global_load_dwordx4 v[30:33], v[30:31], off nt
	v_add_u32_e32 v87, 0x420, v85
	v_add_u32_e32 v89, 0x428, v85
	v_add_u32_e32 v91, 0x840, v85
	s_waitcnt vmcnt(11)
	v_pk_mul_f32 v[2:3], v[2:3], v[56:57] op_sel_hi:[1,0]
	v_pk_mul_f32 v[4:5], v[4:5], v[56:57] op_sel_hi:[1,0]
	ds_write2_b32 v65, v2, v3 offset1:1
	ds_write2_b32 v65, v4, v5 offset0:2 offset1:3
	s_waitcnt vmcnt(8)
	v_pk_mul_f32 v[2:3], v[6:7], v[84:85] op_sel_hi:[1,0]
	v_pk_mul_f32 v[4:5], v[8:9], v[84:85] op_sel_hi:[1,0]
	s_waitcnt vmcnt(7)
	v_pk_mul_f32 v[6:7], v[10:11], v[86:87] op_sel_hi:[1,0]
	v_pk_mul_f32 v[8:9], v[12:13], v[86:87] op_sel_hi:[1,0]
	s_waitcnt vmcnt(6)
	v_pk_mul_f32 v[10:11], v[14:15], v[88:89] op_sel_hi:[1,0]
	v_pk_mul_f32 v[12:13], v[16:17], v[88:89] op_sel_hi:[1,0]
	s_waitcnt vmcnt(5)
	v_pk_mul_f32 v[14:15], v[18:19], v[90:91] op_sel_hi:[1,0]
	v_pk_mul_f32 v[16:17], v[20:21], v[90:91] op_sel_hi:[1,0]
	s_waitcnt vmcnt(4)
	v_pk_mul_f32 v[18:19], v[22:23], v[92:93] op_sel_hi:[1,0]
	v_pk_mul_f32 v[20:21], v[24:25], v[92:93] op_sel_hi:[1,0]
	s_waitcnt vmcnt(2)
	v_pk_mul_f32 v[22:23], v[26:27], v[94:95] op_sel_hi:[1,0]
	ds_write2_b32 v66, v2, v3 offset1:1
	ds_write2_b32 v67, v4, v5 offset1:1
	ds_write2_b32 v68, v6, v7 offset1:1
	ds_write2_b32 v69, v8, v9 offset1:1
	ds_write2_b32 v70, v10, v11 offset1:1
	ds_write2_b32 v71, v12, v13 offset1:1
	ds_write2_b32 v85, v14, v15 offset1:1
	ds_write2_b32 v85, v16, v17 offset0:2 offset1:3
	ds_write2_b32 v87, v18, v19 offset1:1
	ds_write2_b32 v89, v20, v21 offset1:1
	ds_write2_b32 v91, v22, v23 offset1:1
	v_pk_mul_f32 v[2:3], v[28:29], v[94:95] op_sel_hi:[1,0]
	v_add_u32_e32 v4, 0x848, v85
	ds_write2_b32 v4, v2, v3 offset1:1
	s_waitcnt vmcnt(0)
	v_pk_mul_f32 v[2:3], v[30:31], v[96:97] op_sel_hi:[1,0]
	v_add_u32_e32 v4, 0xc60, v85
	ds_write2_b32 v4, v2, v3 offset1:1
	v_pk_mul_f32 v[2:3], v[32:33], v[96:97] op_sel_hi:[1,0]
	v_add_u32_e32 v4, 0xc68, v85
	ds_write2_b32 v4, v2, v3 offset1:1
	s_waitcnt lgkmcnt(0)
	ds_read2_b32 v[6:7], v60 offset0:33 offset1:41
	ds_read2_b32 v[8:9], v60 offset1:8
	ds_read2_b32 v[10:11], v60 offset0:66 offset1:74
	ds_read2_b32 v[12:13], v60 offset0:99 offset1:107
	ds_read2_b32 v[14:15], v60 offset0:132 offset1:140
	ds_read2_b32 v[16:17], v60 offset0:165 offset1:173
	ds_read2_b32 v[18:19], v60 offset0:198 offset1:206
	ds_read2_b32 v[20:21], v60 offset0:231 offset1:239
	s_waitcnt lgkmcnt(6)
	v_cvt_pk_bf16_f32 v2, v8, v6
	v_or_b32_e32 v6, v34, v57
	v_lshlrev_b32_e32 v22, 13, v6
	v_mov_b32_e32 v23, v37
	v_lshl_add_u64 v[22:23], s[22:23], 0, v[22:23]
	v_lshlrev_b32_e32 v24, 1, v55
	v_mov_b32_e32 v25, v37
	v_lshl_add_u64 v[22:23], v[22:23], 0, v[24:25]
	v_mov_b32_e32 v55, v37
	v_lshl_add_u64 v[22:23], v[22:23], 0, v[54:55]
	v_add_co_u32_e32 v22, vcc, s80, v22
	s_waitcnt lgkmcnt(4)
	v_cvt_pk_bf16_f32 v3, v10, v12
	s_waitcnt lgkmcnt(2)
	v_cvt_pk_bf16_f32 v4, v14, v16
	s_waitcnt lgkmcnt(0)
	v_cvt_pk_bf16_f32 v5, v18, v20
	v_addc_co_u32_e32 v23, vcc, 0, v23, vcc
	v_or_b32_e32 v6, v53, v57
	global_store_dwordx4 v[22:23], v[2:5], off
	v_lshlrev_b32_e32 v6, 13, v6
	s_nop 0
	v_cvt_pk_bf16_f32 v2, v9, v7
	v_mov_b32_e32 v7, v37
	v_lshl_add_u64 v[6:7], s[22:23], 0, v[6:7]
	v_lshl_add_u64 v[6:7], v[6:7], 0, v[24:25]
	v_lshl_add_u64 v[6:7], v[6:7], 0, v[54:55]
	v_add_co_u32_e32 v6, vcc, s80, v6
	v_cvt_pk_bf16_f32 v3, v11, v13
	v_cvt_pk_bf16_f32 v4, v15, v17
	v_cvt_pk_bf16_f32 v5, v19, v21
	v_addc_co_u32_e32 v7, vcc, 0, v7, vcc
	ds_read2_b32 v[8:9], v60 offset0:49 offset1:57
	ds_read2_b32 v[10:11], v60 offset0:16 offset1:24
	ds_read2_b32 v[12:13], v60 offset0:82 offset1:90
	ds_read2_b32 v[14:15], v60 offset0:115 offset1:123
	ds_read2_b32 v[16:17], v60 offset0:148 offset1:156
	ds_read2_b32 v[18:19], v60 offset0:181 offset1:189
	ds_read2_b32 v[20:21], v60 offset0:214 offset1:222
	ds_read2_b32 v[22:23], v60 offset0:247 offset1:255
	global_store_dwordx4 v[6:7], v[2:5], off
	v_or_b32_e32 v6, v58, v57
	v_lshlrev_b32_e32 v6, 13, v6
	v_mov_b32_e32 v7, v37
	v_lshl_add_u64 v[6:7], s[22:23], 0, v[6:7]
	v_lshl_add_u64 v[6:7], v[6:7], 0, v[24:25]
	v_lshl_add_u64 v[6:7], v[6:7], 0, v[54:55]
	v_add_co_u32_e32 v6, vcc, s80, v6
	s_waitcnt lgkmcnt(6)
	v_cvt_pk_bf16_f32 v2, v10, v8
	s_waitcnt lgkmcnt(4)
	v_cvt_pk_bf16_f32 v3, v12, v14
	s_waitcnt lgkmcnt(2)
	v_cvt_pk_bf16_f32 v4, v16, v18
	s_waitcnt lgkmcnt(0)
	v_cvt_pk_bf16_f32 v5, v20, v22
	v_addc_co_u32_e32 v7, vcc, 0, v7, vcc
	global_store_dwordx4 v[6:7], v[2:5], off
	v_or_b32_e32 v6, v59, v57
	v_lshlrev_b32_e32 v6, 13, v6
	v_mov_b32_e32 v7, v37
	v_lshl_add_u64 v[6:7], s[22:23], 0, v[6:7]
	v_lshl_add_u64 v[6:7], v[6:7], 0, v[24:25]
	v_lshl_add_u64 v[6:7], v[6:7], 0, v[54:55]
	v_add_co_u32_e32 v6, vcc, 0x1000, v6
	v_cvt_pk_bf16_f32 v2, v11, v9
	v_cvt_pk_bf16_f32 v3, v13, v15
	v_cvt_pk_bf16_f32 v4, v17, v19
	v_cvt_pk_bf16_f32 v5, v21, v23
	v_addc_co_u32_e32 v7, vcc, 0, v7, vcc
	global_store_dwordx4 v[6:7], v[2:5], off
	s_waitcnt lgkmcnt(0)

; #define LAS __attribute__((address_space(3)))
; DI unsigned cvtpk(float lo, float hi) { f32x2 v = {lo, hi}; bf16x2_t b = __builtin_convertvector(v, bf16x2_t); return __builtin_bit_cast(unsigned, b); }
; template <int KIND>
; DI void transpose_item(const float* W, int K, int N, bf16_t* WT, int ldk, const float* g0, const float* g1, const float* g2, LAS float* scr, int item, int lane) {
;     const int nblk = N / 32, kb = item / nblk, nb = item % nblk, k0 = 64 * kb, n0 = 32 * nb;
;     f32x4 tv[8];
; #pragma unroll
;     for (int i = 0; i < 8; ++i) tv[i] = *(const f32x4*)(W + (size_t)(k0 + 8 * i + (lane >> 3)) * N + n0 + 4 * (lane & 7));
; #pragma unroll
;     for (int i = 0; i < 8; ++i) {
;         const int kk = 8 * i + (lane >> 3), k = k0 + kk;
;         float gn = 1.f;
;         if (KIND == 0 || KIND == 1 || KIND == 2 || KIND == 5 || KIND == 6) gn = g0[k];
;         if (KIND == 4) gn = k < 1024 ? g0[k] : (k < 1536 ? g1[k - 1024] : g2[k - 1536]);
;         LAS float* d = scr + kk * 33 + 4 * (lane & 7);
;         d[0] = tv[i][0] * gn; d[1] = tv[i][1] * gn; d[2] = tv[i][2] * gn; d[3] = tv[i][3] * gn;
;     }
;     asm volatile("s_waitcnt lgkmcnt(0)" ::: "memory");
;     int kd0 = k0;
;     if (KIND == 4) kd0 = k0 < 1024 ? k0 + 512 : (k0 < 1536 ? k0 - 1024 : k0);
;     const int c = lane & 7;
; #pragma unroll
;     for (int j = 0; j < 4; ++j) { const int n = (lane >> 3) + 8 * j; const LAS float* s = scr + (8 * c) * 33 + n;
;         u32x4 o; o.x = cvtpk(s[0 * 33], s[1 * 33]); o.y = cvtpk(s[2 * 33], s[3 * 33]); o.z = cvtpk(s[4 * 33], s[5 * 33]); o.w = cvtpk(s[6 * 33], s[7 * 33]);
;         *(u32x4*)(WT + (size_t)map_n<KIND>(n0 + n) * ldk + kd0 + 8 * c) = o; }
;     asm volatile("s_waitcnt lgkmcnt(0)" ::: "memory");
; }
.LBB0_64:
	s_andn2_saveexec_b64 s[12:13], s[8:9]
	s_cbranch_execz .LBB0_66
	v_add_u16_e32 v2, 0xe940, v1
	v_mul_u32_u24_e32 v3, 0xba2f, v2
	s_load_dwordx4 s[8:11], s[4:5], 0xa8
	v_lshrrev_b32_e32 v3, 23, v3
	v_mul_lo_u16_e32 v4, 0xb0, v3
	v_sub_u16_e32 v2, v2, v4
	v_lshlrev_b16_e32 v55, 6, v3
	v_lshlrev_b16_e32 v57, 5, v2
	v_or_b32_e32 v20, v34, v55
	v_lshlrev_b32_e32 v2, 2, v57
	v_mov_b32_e32 v3, v37
	s_waitcnt lgkmcnt(0)
	v_lshl_add_u64 v[2:3], s[10:11], 0, v[2:3]
	v_mul_u32_u24_e32 v4, 0x1600, v20
	v_lshl_add_u64 v[2:3], v[2:3], 0, v[36:37]
	v_lshlrev_b32_e32 v4, 2, v4
	v_mov_b32_e32 v5, v37
	v_lshl_add_u64 v[30:31], v[2:3], 0, v[4:5]
	v_add_co_u32_e32 v6, vcc, s73, v30
	v_lshlrev_b32_e32 v32, 2, v20
	s_nop 0
	v_addc_co_u32_e32 v7, vcc, 0, v31, vcc
	v_add_co_u32_e32 v10, vcc, s74, v30
	global_load_dwordx4 v[2:5], v[30:31], off nt
	s_nop 0
	global_load_dwordx4 v[6:9], v[6:7], off nt
	v_addc_co_u32_e32 v11, vcc, 0, v31, vcc
	v_add_co_u32_e32 v14, vcc, s75, v30
	v_add_u32_e32 v85, v35, v61
	s_nop 0
	v_addc_co_u32_e32 v15, vcc, 0, v31, vcc
	v_add_co_u32_e32 v18, vcc, s76, v30
	global_load_dwordx4 v[10:13], v[10:11], off nt
	s_nop 0
	global_load_dwordx4 v[14:17], v[14:15], off nt
	v_addc_co_u32_e32 v19, vcc, 0, v31, vcc
	v_add_co_u32_e32 v22, vcc, s77, v30
	global_load_dword v56, v32, s[8:9]
	s_nop 0
	v_addc_co_u32_e32 v23, vcc, 0, v31, vcc
	v_add_co_u32_e32 v26, vcc, s78, v30
	global_load_dwordx4 v[18:21], v[18:19], off nt
	s_nop 0
	global_load_dwordx4 v[22:25], v[22:23], off nt
	s_nop 0
	global_load_dword v84, v32, s[8:9] offset:32
	global_load_dword v86, v32, s[8:9] offset:64
	global_load_dword v88, v32, s[8:9] offset:96
	global_load_dword v90, v32, s[8:9] offset:128
	v_addc_co_u32_e32 v27, vcc, 0, v31, vcc
	v_add_co_u32_e32 v30, vcc, s79, v30
	global_load_dword v92, v32, s[8:9] offset:160
	s_nop 0
	global_load_dwordx4 v[26:29], v[26:27], off nt
	s_nop 0
	global_load_dword v94, v32, s[8:9] offset:192
	v_addc_co_u32_e32 v31, vcc, 0, v31, vcc
	global_load_dword v96, v32, s[8:9] offset:224
	s_nop 0
	global_load_dwordx4 v[30:33], v[30:31], off nt
	v_add_u32_e32 v87, 0x420, v85
	v_add_u32_e32 v89, 0x428, v85
	v_add_u32_e32 v91, 0x840, v85
	s_waitcnt vmcnt(11)
	v_pk_mul_f32 v[2:3], v[2:3], v[56:57] op_sel_hi:[1,0]
	v_pk_mul_f32 v[4:5], v[4:5], v[56:57] op_sel_hi:[1,0]
	ds_write2_b32 v65, v2, v3 offset1:1
	ds_write2_b32 v65, v4, v5 offset0:2 offset1:3
	s_waitcnt vmcnt(8)
	v_pk_mul_f32 v[2:3], v[6:7], v[84:85] op_sel_hi:[1,0]
	v_pk_mul_f32 v[4:5], v[8:9], v[84:85] op_sel_hi:[1,0]
	s_waitcnt vmcnt(7)
	v_pk_mul_f32 v[6:7], v[10:11], v[86:87] op_sel_hi:[1,0]
	v_pk_mul_f32 v[8:9], v[12:13], v[86:87] op_sel_hi:[1,0]
	s_waitcnt vmcnt(6)
	v_pk_mul_f32 v[10:11], v[14:15], v[88:89] op_sel_hi:[1,0]
	v_pk_mul_f32 v[12:13], v[16:17], v[88:89] op_sel_hi:[1,0]
	s_waitcnt vmcnt(5)
	v_pk_mul_f32 v[14:15], v[18:19], v[90:91] op_sel_hi:[1,0]
	v_pk_mul_f32 v[16:17], v[20:21], v[90:91] op_sel_hi:[1,0]
	s_waitcnt vmcnt(4)
	v_pk_mul_f32 v[18:19], v[22:23], v[92:93] op_sel_hi:[1,0]
	v_pk_mul_f32 v[20:21], v[24:25], v[92:93] op_sel_hi:[1,0]
	s_waitcnt vmcnt(2)
	v_pk_mul_f32 v[22:23], v[26:27], v[94:95] op_sel_hi:[1,0]
	v_pk_mul_f32 v[24:25], v[28:29], v[94:95] op_sel_hi:[1,0]
	ds_write2_b32 v66, v2, v3 offset1:1
	ds_write2_b32 v67, v4, v5 offset1:1
	ds_write2_b32 v68, v6, v7 offset1:1
	ds_write2_b32 v69, v8, v9 offset1:1
	ds_write2_b32 v70, v10, v11 offset1:1
	ds_write2_b32 v71, v12, v13 offset1:1
	ds_write2_b32 v85, v14, v15 offset1:1
	ds_write2_b32 v85, v16, v17 offset0:2 offset1:3
	ds_write2_b32 v87, v18, v19 offset1:1
	ds_write2_b32 v89, v20, v21 offset1:1
	ds_write2_b32 v91, v22, v23 offset1:1
	v_add_u32_e32 v2, 0x848, v85
	ds_write2_b32 v2, v24, v25 offset1:1
	s_waitcnt vmcnt(0)
	v_pk_mul_f32 v[2:3], v[30:31], v[96:97] op_sel_hi:[1,0]
	v_add_u32_e32 v4, 0xc60, v85
	ds_write2_b32 v4, v2, v3 offset1:1
	v_pk_mul_f32 v[2:3], v[32:33], v[96:97] op_sel_hi:[1,0]
	v_add_u32_e32 v4, 0xc68, v85
	ds_write2_b32 v4, v2, v3 offset1:1
	s_waitcnt lgkmcnt(0)
	ds_read2_b32 v[6:7], v60 offset0:33 offset1:41
	ds_read2_b32 v[8:9], v60 offset1:8
	ds_read2_b32 v[10:11], v60 offset0:66 offset1:74
	ds_read2_b32 v[12:13], v60 offset0:99 offset1:107
	ds_read2_b32 v[14:15], v60 offset0:132 offset1:140
	ds_read2_b32 v[16:17], v60 offset0:165 offset1:173
	ds_read2_b32 v[18:19], v60 offset0:198 offset1:206
	ds_read2_b32 v[20:21], v60 offset0:231 offset1:239
	v_lshlrev_b32_e32 v2, 1, v55
	v_mov_b32_e32 v3, v37
	v_lshl_add_u64 v[22:23], v[40:41], 0, v[2:3]
	s_waitcnt lgkmcnt(6)
	v_cvt_pk_bf16_f32 v2, v8, v6
	v_or_b32_e32 v6, v34, v57
	v_lshlrev_b32_e32 v24, 13, v6
	v_mov_b32_e32 v25, v37
	s_waitcnt lgkmcnt(4)
	v_cvt_pk_bf16_f32 v3, v10, v12
	s_waitcnt lgkmcnt(2)
	v_cvt_pk_bf16_f32 v4, v14, v16
	s_waitcnt lgkmcnt(0)
	v_cvt_pk_bf16_f32 v5, v18, v20
	v_lshl_add_u64 v[24:25], v[22:23], 0, v[24:25]
	global_store_dwordx4 v[24:25], v[2:5], off
	v_or_b32_e32 v6, v53, v57
	v_lshlrev_b32_e32 v6, 13, v6
	v_cvt_pk_bf16_f32 v2, v9, v7
	v_cvt_pk_bf16_f32 v3, v11, v13
	v_cvt_pk_bf16_f32 v4, v15, v17
	v_cvt_pk_bf16_f32 v5, v19, v21
	ds_read2_b32 v[8:9], v60 offset0:49 offset1:57
	ds_read2_b32 v[10:11], v60 offset0:16 offset1:24
	ds_read2_b32 v[12:13], v60 offset0:82 offset1:90
	ds_read2_b32 v[14:15], v60 offset0:115 offset1:123
	ds_read2_b32 v[16:17], v60 offset0:148 offset1:156
	ds_read2_b32 v[18:19], v60 offset0:181 offset1:189
	ds_read2_b32 v[20:21], v60 offset0:214 offset1:222
	ds_read2_b32 v[24:25], v60 offset0:247 offset1:255
	v_mov_b32_e32 v7, v37
	v_lshl_add_u64 v[6:7], v[22:23], 0, v[6:7]
	global_store_dwordx4 v[6:7], v[2:5], off
	v_or_b32_e32 v6, v58, v57
	v_lshlrev_b32_e32 v6, 13, v6
	v_mov_b32_e32 v7, v37
	s_waitcnt lgkmcnt(6)
	v_cvt_pk_bf16_f32 v2, v10, v8
	s_waitcnt lgkmcnt(4)
	v_cvt_pk_bf16_f32 v3, v12, v14
	s_waitcnt lgkmcnt(2)
	v_cvt_pk_bf16_f32 v4, v16, v18
	s_waitcnt lgkmcnt(0)
	v_cvt_pk_bf16_f32 v5, v20, v24
	v_lshl_add_u64 v[6:7], v[22:23], 0, v[6:7]
	global_store_dwordx4 v[6:7], v[2:5], off
	v_or_b32_e32 v6, v59, v57
	v_lshlrev_b32_e32 v6, 13, v6
	v_mov_b32_e32 v7, v37
	v_cvt_pk_bf16_f32 v2, v11, v9
	v_cvt_pk_bf16_f32 v3, v13, v15
	v_cvt_pk_bf16_f32 v4, v17, v19
	v_cvt_pk_bf16_f32 v5, v21, v25
	v_lshl_add_u64 v[6:7], v[22:23], 0, v[6:7]
	global_store_dwordx4 v[6:7], v[2:5], off
	s_waitcnt lgkmcnt(0)

; #define LAS __attribute__((address_space(3)))
; DI unsigned cvtpk(float lo, float hi) { f32x2 v = {lo, hi}; bf16x2_t b = __builtin_convertvector(v, bf16x2_t); return __builtin_bit_cast(unsigned, b); }
; template <int KIND>
; DI void transpose_item(const float* W, int K, int N, bf16_t* WT, int ldk, const float* g0, const float* g1, const float* g2, LAS float* scr, int item, int lane) {
;     const int nblk = N / 32, kb = item / nblk, nb = item % nblk, k0 = 64 * kb, n0 = 32 * nb;
;     f32x4 tv[8];
; #pragma unroll
;     for (int i = 0; i < 8; ++i) tv[i] = *(const f32x4*)(W + (size_t)(k0 + 8 * i + (lane >> 3)) * N + n0 + 4 * (lane & 7));
; #pragma unroll
;     for (int i = 0; i < 8; ++i) {
;         const int kk = 8 * i + (lane >> 3), k = k0 + kk;
;         float gn = 1.f;
;         if (KIND == 0 || KIND == 1 || KIND == 2 || KIND == 5 || KIND == 6) gn = g0[k];
;         if (KIND == 4) gn = k < 1024 ? g0[k] : (k < 1536 ? g1[k - 1024] : g2[k - 1536]);
;         LAS float* d = scr + kk * 33 + 4 * (lane & 7);
;         d[0] = tv[i][0] * gn; d[1] = tv[i][1] * gn; d[2] = tv[i][2] * gn; d[3] = tv[i][3] * gn;
;     }
;     asm volatile("s_waitcnt lgkmcnt(0)" ::: "memory");
;     int kd0 = k0;
;     if (KIND == 4) kd0 = k0 < 1024 ? k0 + 512 : (k0 < 1536 ? k0 - 1024 : k0);
;     const int c = lane & 7;
; #pragma unroll
;     for (int j = 0; j < 4; ++j) { const int n = (lane >> 3) + 8 * j; const LAS float* s = scr + (8 * c) * 33 + n;
;         u32x4 o; o.x = cvtpk(s[0 * 33], s[1 * 33]); o.y = cvtpk(s[2 * 33], s[3 * 33]); o.z = cvtpk(s[4 * 33], s[5 * 33]); o.w = cvtpk(s[6 * 33], s[7 * 33]);
;         *(u32x4*)(WT + (size_t)map_n<KIND>(n0 + n) * ldk + kd0 + 8 * c) = o; }
;     asm volatile("s_waitcnt lgkmcnt(0)" ::: "memory");
; }
.LBB0_67:
	s_andn2_saveexec_b64 s[10:11], s[6:7]
	s_cbranch_execz .LBB0_133
	s_load_dwordx8 s[12:19], s[4:5], 0x88
	v_add_u32_e32 v2, 0xfffe2800, v52
	v_add_u32_e32 v55, 0xfffff140, v1
	v_and_b32_e32 v85, 0x7e0, v2
	v_and_b32_e32 v84, 0x7c0, v55
	v_lshlrev_b32_e32 v2, 2, v85
	v_mov_b32_e32 v3, v37
	v_or_b32_e32 v86, v84, v34
	s_waitcnt lgkmcnt(0)
	v_lshl_add_u64 v[2:3], s[18:19], 0, v[2:3]
	v_lshl_add_u64 v[2:3], v[2:3], 0, v[36:37]
	v_lshlrev_b32_e32 v4, 13, v86
	v_mov_b32_e32 v5, v37
	v_lshl_add_u64 v[2:3], v[2:3], 0, v[4:5]
	v_add_co_u32_e32 v4, vcc, s66, v2
	s_movk_i32 s6, 0x400
	s_nop 0
	v_addc_co_u32_e32 v5, vcc, 0, v3, vcc
	global_load_dwordx4 v[30:33], v[2:3], off nt
	global_load_dwordx4 v[26:29], v[4:5], off nt
	v_add_co_u32_e32 v4, vcc, s67, v2
	s_nop 1
	v_addc_co_u32_e32 v5, vcc, 0, v3, vcc
	v_add_co_u32_e32 v6, vcc, s68, v2
	s_nop 1
	v_addc_co_u32_e32 v7, vcc, 0, v3, vcc
	global_load_dwordx4 v[22:25], v[4:5], off nt
	global_load_dwordx4 v[18:21], v[6:7], off nt
	v_add_co_u32_e32 v4, vcc, s69, v2
	s_nop 1
	v_addc_co_u32_e32 v5, vcc, 0, v3, vcc
	v_add_co_u32_e32 v6, vcc, 0x50000, v2
	s_nop 1
	v_addc_co_u32_e32 v7, vcc, 0, v3, vcc
	global_load_dwordx4 v[14:17], v[4:5], off nt
	global_load_dwordx4 v[10:13], v[6:7], off nt
	v_add_co_u32_e32 v4, vcc, 0x60000, v2
	s_nop 1
	v_addc_co_u32_e32 v5, vcc, 0, v3, vcc
	v_add_co_u32_e32 v2, vcc, 0x70000, v2
	s_nop 1
	v_addc_co_u32_e32 v3, vcc, 0, v3, vcc
	global_load_dwordx4 v[6:9], v[4:5], off nt
	s_nop 0
	global_load_dwordx4 v[2:5], v[2:3], off nt
	v_cmp_gt_u32_e32 vcc, s6, v55
	s_movk_i32 s6, 0x3ff
	v_cmp_lt_u32_e64 s[6:7], s6, v55
	s_and_saveexec_b64 s[8:9], s[6:7]
	s_xor_b64 s[18:19], exec, s[8:9]
	s_cbranch_execz .LBB0_74
	v_cmp_lt_u32_e64 s[8:9], s81, v55
	s_and_saveexec_b64 s[90:91], s[8:9]
	s_xor_b64 s[8:9], exec, s[90:91]
	v_lshlrev_b32_e32 v56, 2, v86
	v_mov_b32_e32 v57, v37
	s_movk_i32 s90, 0xe800
	v_lshl_add_u64 v[56:57], s[16:17], 0, v[56:57]
	s_mov_b32 s91, -1
	v_lshl_add_u64 v[56:57], v[56:57], 0, s[90:91]
	s_andn2_saveexec_b64 s[8:9], s[8:9]
	v_lshlrev_b32_e32 v56, 2, v86
	v_mov_b32_e32 v57, v37
	s_movk_i32 s90, 0xf000
	v_lshl_add_u64 v[56:57], s[14:15], 0, v[56:57]
	s_mov_b32 s91, -1
	v_lshl_add_u64 v[56:57], v[56:57], 0, s[90:91]
	s_or_b64 exec, exec, s[8:9]

; #define LAS __attribute__((address_space(3)))
; DI unsigned cvtpk(float lo, float hi) { f32x2 v = {lo, hi}; bf16x2_t b = __builtin_convertvector(v, bf16x2_t); return __builtin_bit_cast(unsigned, b); }
; template <int KIND>
; DI void transpose_item(const float* W, int K, int N, bf16_t* WT, int ldk, const float* g0, const float* g1, const float* g2, LAS float* scr, int item, int lane) {
;     const int nblk = N / 32, kb = item / nblk, nb = item % nblk, k0 = 64 * kb, n0 = 32 * nb;
;     f32x4 tv[8];
; #pragma unroll
;     for (int i = 0; i < 8; ++i) tv[i] = *(const f32x4*)(W + (size_t)(k0 + 8 * i + (lane >> 3)) * N + n0 + 4 * (lane & 7));
; #pragma unroll
;     for (int i = 0; i < 8; ++i) {
;         const int kk = 8 * i + (lane >> 3), k = k0 + kk;
;         float gn = 1.f;
;         if (KIND == 0 || KIND == 1 || KIND == 2 || KIND == 5 || KIND == 6) gn = g0[k];
;         if (KIND == 4) gn = k < 1024 ? g0[k] : (k < 1536 ? g1[k - 1024] : g2[k - 1536]);
;         LAS float* d = scr + kk * 33 + 4 * (lane & 7);
;         d[0] = tv[i][0] * gn; d[1] = tv[i][1] * gn; d[2] = tv[i][2] * gn; d[3] = tv[i][3] * gn;
;     }
;     asm volatile("s_waitcnt lgkmcnt(0)" ::: "memory");
;     int kd0 = k0;
;     if (KIND == 4) kd0 = k0 < 1024 ? k0 + 512 : (k0 < 1536 ? k0 - 1024 : k0);
;     const int c = lane & 7;
; #pragma unroll
;     for (int j = 0; j < 4; ++j) { const int n = (lane >> 3) + 8 * j; const LAS float* s = scr + (8 * c) * 33 + n;
;         u32x4 o; o.x = cvtpk(s[0 * 33], s[1 * 33]); o.y = cvtpk(s[2 * 33], s[3 * 33]); o.z = cvtpk(s[4 * 33], s[5 * 33]); o.w = cvtpk(s[6 * 33], s[7 * 33]);
;         *(u32x4*)(WT + (size_t)map_n<KIND>(n0 + n) * ldk + kd0 + 8 * c) = o; }
;     asm volatile("s_waitcnt lgkmcnt(0)" ::: "memory");
; }
.LBB0_134:
	s_andn2_saveexec_b64 s[8:9], s[62:63]
	s_cbranch_execz .LBB0_136
	s_load_dwordx2 s[6:7], s[4:5], 0x78
	v_add_u32_e32 v2, 0xfffe4800, v52
	v_and_b32_e32 v88, 0x3e0, v2
	v_and_b32_e32 v55, 0x1c0, v64
	v_lshlrev_b32_e32 v2, 2, v88
	v_mov_b32_e32 v3, v37
	v_or_b32_e32 v4, v55, v34
	s_waitcnt lgkmcnt(0)
	v_lshl_add_u64 v[2:3], s[6:7], 0, v[2:3]
	v_lshl_add_u64 v[2:3], v[2:3], 0, v[36:37]
	v_lshlrev_b32_e32 v4, 12, v4
	v_mov_b32_e32 v5, v37
	v_lshl_add_u64 v[30:31], v[2:3], 0, v[4:5]
	s_mov_b32 s6, 0x8000
	v_add_co_u32_e32 v6, vcc, s6, v30
	s_mov_b32 s6, 0x28000
	s_nop 0
	v_addc_co_u32_e32 v7, vcc, 0, v31, vcc
	v_add_co_u32_e32 v10, vcc, s66, v30
	global_load_dwordx4 v[2:5], v[30:31], off nt
	s_nop 0
	global_load_dwordx4 v[6:9], v[6:7], off nt
	v_addc_co_u32_e32 v11, vcc, 0, v31, vcc
	v_add_co_u32_e32 v14, vcc, s82, v30
	v_lshlrev_b32_e32 v56, 1, v55
	s_nop 0
	v_addc_co_u32_e32 v15, vcc, 0, v31, vcc
	global_load_dwordx4 v[10:13], v[10:11], off nt
	s_nop 0
	global_load_dwordx4 v[14:17], v[14:15], off nt
	v_add_co_u32_e32 v18, vcc, s67, v30
	v_or_b32_e32 v55, v88, v34
	s_nop 0
	v_addc_co_u32_e32 v19, vcc, 0, v31, vcc
	global_load_dwordx4 v[18:21], v[18:19], off nt
	v_add_co_u32_e32 v26, vcc, s6, v30
	v_add_co_u32_e64 v22, s[6:7], s68, v30
	s_nop 0
	v_addc_co_u32_e32 v27, vcc, 0, v31, vcc
	v_addc_co_u32_e64 v23, s[6:7], 0, v31, s[6:7]
	global_load_dwordx4 v[22:25], v[22:23], off nt
	s_mov_b32 s6, 0x38000
	global_load_dwordx4 v[26:29], v[26:27], off nt
	v_add_co_u32_e32 v30, vcc, s6, v30
	s_movk_i32 s6, 0x200
	s_nop 0
	v_addc_co_u32_e32 v31, vcc, 0, v31, vcc
	global_load_dwordx4 v[30:33], v[30:31], off nt
	v_or_b32_e32 v84, v88, v53
	v_lshlrev_b32_e32 v55, 1, v55
	v_lshlrev_b32_e32 v85, 1, v84
	v_add_u32_e32 v84, 0xfffffc01, v55
	v_cmp_gt_u32_e32 vcc, s6, v88
	v_add_u32_e32 v86, 0xfffffc01, v85
	v_mov_b32_e32 v57, v37
	v_cndmask_b32_e32 v84, v84, v55, vcc
	v_cndmask_b32_e32 v86, v86, v85, vcc
	v_ashrrev_i32_e32 v85, 31, v84
	v_lshl_add_u64 v[56:57], v[44:45], 0, v[56:57]
	v_lshlrev_b64 v[84:85], 10, v[84:85]
	v_ashrrev_i32_e32 v87, 31, v86
	s_waitcnt vmcnt(7)
	ds_write2_b32 v65, v2, v3 offset1:1
	ds_write2_b32 v65, v4, v5 offset0:2 offset1:3
	s_waitcnt vmcnt(5)
	ds_write2_b32 v68, v10, v11 offset1:1
	ds_write2_b32 v69, v12, v13 offset1:1
	s_waitcnt vmcnt(3)
	ds_write2_b32 v72, v18, v19 offset1:1
	ds_write2_b32 v73, v20, v21 offset1:1
	s_waitcnt vmcnt(2)
	ds_write2_b32 v76, v22, v23 offset1:1
	ds_write2_b32 v77, v24, v25 offset1:1
	ds_write2_b32 v66, v6, v7 offset1:1
	ds_write2_b32 v67, v8, v9 offset1:1
	ds_write2_b32 v70, v14, v15 offset1:1
	ds_write2_b32 v71, v16, v17 offset1:1
	s_waitcnt vmcnt(1)
	ds_write2_b32 v74, v26, v27 offset1:1
	ds_write2_b32 v75, v28, v29 offset1:1
	s_waitcnt vmcnt(0)
	ds_write2_b32 v78, v30, v31 offset1:1
	ds_write2_b32 v79, v32, v33 offset1:1
	s_waitcnt lgkmcnt(0)
	ds_read2_b32 v[6:7], v60 offset0:33 offset1:41
	ds_read2_b32 v[8:9], v60 offset1:8
	ds_read2_b32 v[10:11], v60 offset0:66 offset1:74
	ds_read2_b32 v[12:13], v60 offset0:99 offset1:107
	ds_read2_b32 v[14:15], v60 offset0:132 offset1:140
	ds_read2_b32 v[16:17], v60 offset0:165 offset1:173
	ds_read2_b32 v[18:19], v60 offset0:198 offset1:206
	ds_read2_b32 v[20:21], v60 offset0:231 offset1:239
	v_lshl_add_u64 v[22:23], v[56:57], 0, v[84:85]
	s_waitcnt lgkmcnt(6)
	v_cvt_pk_bf16_f32 v2, v8, v6
	s_waitcnt lgkmcnt(4)
	v_cvt_pk_bf16_f32 v3, v10, v12
	s_waitcnt lgkmcnt(2)
	v_cvt_pk_bf16_f32 v4, v14, v16
	s_waitcnt lgkmcnt(0)
	v_cvt_pk_bf16_f32 v5, v18, v20
	global_store_dwordx4 v[22:23], v[2:5], off
	v_cvt_pk_bf16_f32 v6, v9, v7
	v_cvt_pk_bf16_f32 v7, v11, v13
	v_lshlrev_b64 v[2:3], 10, v[86:87]
	v_cvt_pk_bf16_f32 v8, v15, v17
	v_cvt_pk_bf16_f32 v9, v19, v21
	v_lshl_add_u64 v[2:3], v[56:57], 0, v[2:3]
	ds_read2_b32 v[10:11], v60 offset0:49 offset1:57
	ds_read2_b32 v[12:13], v60 offset0:16 offset1:24
	ds_read2_b32 v[14:15], v60 offset0:82 offset1:90
	ds_read2_b32 v[16:17], v60 offset0:115 offset1:123
	ds_read2_b32 v[18:19], v60 offset0:148 offset1:156
	ds_read2_b32 v[20:21], v60 offset0:181 offset1:189
	ds_read2_b32 v[22:23], v60 offset0:214 offset1:222
	ds_read2_b32 v[24:25], v60 offset0:247 offset1:255
	global_store_dwordx4 v[2:3], v[6:9], off
	s_waitcnt lgkmcnt(6)
	v_cvt_pk_bf16_f32 v2, v12, v10
	s_waitcnt lgkmcnt(4)
	v_cvt_pk_bf16_f32 v3, v14, v16
	v_or_b32_e32 v6, v88, v58
	v_lshlrev_b32_e32 v6, 1, v6
	v_add_u32_e32 v7, 0xfffffc01, v6
	v_cndmask_b32_e32 v6, v7, v6, vcc
	v_ashrrev_i32_e32 v7, 31, v6
	v_lshlrev_b64 v[6:7], 10, v[6:7]
	s_waitcnt lgkmcnt(2)
	v_cvt_pk_bf16_f32 v4, v18, v20
	s_waitcnt lgkmcnt(0)
	v_cvt_pk_bf16_f32 v5, v22, v24
	v_lshl_add_u64 v[6:7], v[56:57], 0, v[6:7]
	global_store_dwordx4 v[6:7], v[2:5], off
	v_or_b32_e32 v6, v88, v59
	v_lshlrev_b32_e32 v6, 1, v6
	v_add_u32_e32 v7, 0xfffffc01, v6
	v_cndmask_b32_e32 v6, v7, v6, vcc
	v_ashrrev_i32_e32 v7, 31, v6
	v_lshlrev_b64 v[6:7], 10, v[6:7]
	v_cvt_pk_bf16_f32 v2, v13, v11
	v_cvt_pk_bf16_f32 v3, v15, v17
	v_cvt_pk_bf16_f32 v4, v19, v21
	v_cvt_pk_bf16_f32 v5, v23, v25
	v_lshl_add_u64 v[6:7], v[56:57], 0, v[6:7]
	global_store_dwordx4 v[6:7], v[2:5], off
	s_waitcnt lgkmcnt(0)

; #define LAS __attribute__((address_space(3)))
; DI unsigned cvtpk(float lo, float hi) { f32x2 v = {lo, hi}; bf16x2_t b = __builtin_convertvector(v, bf16x2_t); return __builtin_bit_cast(unsigned, b); }
; template <int KIND>
; DI void transpose_item(const float* W, int K, int N, bf16_t* WT, int ldk, const float* g0, const float* g1, const float* g2, LAS float* scr, int item, int lane) {
;     const int nblk = N / 32, kb = item / nblk, nb = item % nblk, k0 = 64 * kb, n0 = 32 * nb;
;     f32x4 tv[8];
; #pragma unroll
;     for (int i = 0; i < 8; ++i) tv[i] = *(const f32x4*)(W + (size_t)(k0 + 8 * i + (lane >> 3)) * N + n0 + 4 * (lane & 7));
; #pragma unroll
;     for (int i = 0; i < 8; ++i) {
;         const int kk = 8 * i + (lane >> 3), k = k0 + kk;
;         float gn = 1.f;
;         if (KIND == 0 || KIND == 1 || KIND == 2 || KIND == 5 || KIND == 6) gn = g0[k];
;         if (KIND == 4) gn = k < 1024 ? g0[k] : (k < 1536 ? g1[k - 1024] : g2[k - 1536]);
;         LAS float* d = scr + kk * 33 + 4 * (lane & 7);
;         d[0] = tv[i][0] * gn; d[1] = tv[i][1] * gn; d[2] = tv[i][2] * gn; d[3] = tv[i][3] * gn;
;     }
;     asm volatile("s_waitcnt lgkmcnt(0)" ::: "memory");
;     int kd0 = k0;
;     if (KIND == 4) kd0 = k0 < 1024 ? k0 + 512 : (k0 < 1536 ? k0 - 1024 : k0);
;     const int c = lane & 7;
; #pragma unroll
;     for (int j = 0; j < 4; ++j) { const int n = (lane >> 3) + 8 * j; const LAS float* s = scr + (8 * c) * 33 + n;
;         u32x4 o; o.x = cvtpk(s[0 * 33], s[1 * 33]); o.y = cvtpk(s[2 * 33], s[3 * 33]); o.z = cvtpk(s[4 * 33], s[5 * 33]); o.w = cvtpk(s[6 * 33], s[7 * 33]);
;         *(u32x4*)(WT + (size_t)map_n<KIND>(n0 + n) * ldk + kd0 + 8 * c) = o; }
;     asm volatile("s_waitcnt lgkmcnt(0)" ::: "memory");
; }
.LBB0_137:
	s_andn2_saveexec_b64 s[6:7], s[60:61]
	s_cbranch_execz .LBB0_139
	s_load_dwordx4 s[8:11], s[4:5], 0x28
	v_add_u32_e32 v2, 0xfffff340, v1
	v_and_b32_e32 v55, 0xc0, v2
	v_add_u32_e32 v2, 0xfffe6800, v52
	v_and_b32_e32 v57, 0x7e0, v2
	v_lshlrev_b32_e32 v2, 2, v57
	v_mov_b32_e32 v3, v37
	v_or_b32_e32 v20, v55, v34
	s_waitcnt lgkmcnt(0)
	v_lshl_add_u64 v[2:3], s[10:11], 0, v[2:3]
	v_lshl_add_u64 v[2:3], v[2:3], 0, v[36:37]
	v_lshlrev_b32_e32 v4, 13, v20
	v_mov_b32_e32 v5, v37
	v_lshl_add_u64 v[30:31], v[2:3], 0, v[4:5]
	v_add_co_u32_e32 v6, vcc, s66, v30
	v_lshlrev_b32_e32 v32, 2, v20
	s_nop 0
	v_addc_co_u32_e32 v7, vcc, 0, v31, vcc
	v_add_co_u32_e32 v10, vcc, s67, v30
	global_load_dwordx4 v[2:5], v[30:31], off nt
	s_nop 0
	global_load_dwordx4 v[6:9], v[6:7], off nt
	v_addc_co_u32_e32 v11, vcc, 0, v31, vcc
	v_add_co_u32_e32 v14, vcc, s68, v30
	v_add_u32_e32 v85, v35, v61
	s_nop 0
	v_addc_co_u32_e32 v15, vcc, 0, v31, vcc
	v_add_co_u32_e32 v18, vcc, s69, v30
	global_load_dwordx4 v[10:13], v[10:11], off nt
	s_nop 0
	global_load_dwordx4 v[14:17], v[14:15], off nt
	v_addc_co_u32_e32 v19, vcc, 0, v31, vcc
	v_add_co_u32_e32 v22, vcc, s70, v30
	global_load_dword v56, v32, s[8:9]
	s_nop 0
	v_addc_co_u32_e32 v23, vcc, 0, v31, vcc
	v_add_co_u32_e32 v26, vcc, s71, v30
	global_load_dwordx4 v[18:21], v[18:19], off nt
	s_nop 0
	global_load_dwordx4 v[22:25], v[22:23], off nt
	s_nop 0
	global_load_dword v84, v32, s[8:9] offset:32
	global_load_dword v86, v32, s[8:9] offset:64
	global_load_dword v88, v32, s[8:9] offset:96
	global_load_dword v90, v32, s[8:9] offset:128
	v_addc_co_u32_e32 v27, vcc, 0, v31, vcc
	v_add_co_u32_e32 v30, vcc, s72, v30
	global_load_dword v92, v32, s[8:9] offset:160
	s_nop 0
	global_load_dwordx4 v[26:29], v[26:27], off nt
	s_nop 0
	global_load_dword v94, v32, s[8:9] offset:192
	v_addc_co_u32_e32 v31, vcc, 0, v31, vcc
	global_load_dword v96, v32, s[8:9] offset:224
	s_nop 0
	global_load_dwordx4 v[30:33], v[30:31], off nt
	v_add_u32_e32 v87, 0x420, v85
	v_add_u32_e32 v89, 0x428, v85
	v_add_u32_e32 v91, 0x840, v85
	v_add_u32_e32 v93, 0x848, v85
	s_waitcnt vmcnt(11)
	v_pk_mul_f32 v[2:3], v[2:3], v[56:57] op_sel_hi:[1,0]
	v_pk_mul_f32 v[4:5], v[4:5], v[56:57] op_sel_hi:[1,0]
	ds_write2_b32 v65, v2, v3 offset1:1
	ds_write2_b32 v65, v4, v5 offset0:2 offset1:3
	s_waitcnt vmcnt(8)
	v_pk_mul_f32 v[2:3], v[6:7], v[84:85] op_sel_hi:[1,0]
	v_pk_mul_f32 v[4:5], v[8:9], v[84:85] op_sel_hi:[1,0]
	s_waitcnt vmcnt(7)
	v_pk_mul_f32 v[6:7], v[10:11], v[86:87] op_sel_hi:[1,0]
	v_pk_mul_f32 v[8:9], v[12:13], v[86:87] op_sel_hi:[1,0]
	s_waitcnt vmcnt(6)
	v_pk_mul_f32 v[10:11], v[14:15], v[88:89] op_sel_hi:[1,0]
	v_pk_mul_f32 v[12:13], v[16:17], v[88:89] op_sel_hi:[1,0]
	s_waitcnt vmcnt(5)
	v_pk_mul_f32 v[14:15], v[18:19], v[90:91] op_sel_hi:[1,0]
	v_pk_mul_f32 v[16:17], v[20:21], v[90:91] op_sel_hi:[1,0]
	s_waitcnt vmcnt(4)
	v_pk_mul_f32 v[18:19], v[22:23], v[92:93] op_sel_hi:[1,0]
	v_pk_mul_f32 v[20:21], v[24:25], v[92:93] op_sel_hi:[1,0]
	s_waitcnt vmcnt(2)
	v_pk_mul_f32 v[22:23], v[26:27], v[94:95] op_sel_hi:[1,0]
	v_pk_mul_f32 v[24:25], v[28:29], v[94:95] op_sel_hi:[1,0]
	ds_write2_b32 v66, v2, v3 offset1:1
	ds_write2_b32 v67, v4, v5 offset1:1
	ds_write2_b32 v68, v6, v7 offset1:1
	ds_write2_b32 v69, v8, v9 offset1:1
	ds_write2_b32 v70, v10, v11 offset1:1
	ds_write2_b32 v71, v12, v13 offset1:1
	ds_write2_b32 v85, v14, v15 offset1:1
	ds_write2_b32 v85, v16, v17 offset0:2 offset1:3
	ds_write2_b32 v87, v18, v19 offset1:1
	ds_write2_b32 v89, v20, v21 offset1:1
	ds_write2_b32 v91, v22, v23 offset1:1
	ds_write2_b32 v93, v24, v25 offset1:1
	s_waitcnt vmcnt(0)
	v_pk_mul_f32 v[2:3], v[30:31], v[96:97] op_sel_hi:[1,0]
	v_add_u32_e32 v4, 0xc60, v85
	ds_write2_b32 v4, v2, v3 offset1:1
	v_pk_mul_f32 v[2:3], v[32:33], v[96:97] op_sel_hi:[1,0]
	v_add_u32_e32 v4, 0xc68, v85
	ds_write2_b32 v4, v2, v3 offset1:1
	s_waitcnt lgkmcnt(0)
	ds_read2_b32 v[6:7], v60 offset0:33 offset1:41
	ds_read2_b32 v[8:9], v60 offset1:8
	ds_read2_b32 v[10:11], v60 offset0:66 offset1:74
	ds_read2_b32 v[12:13], v60 offset0:99 offset1:107
	ds_read2_b32 v[14:15], v60 offset0:132 offset1:140
	ds_read2_b32 v[16:17], v60 offset0:165 offset1:173
	ds_read2_b32 v[18:19], v60 offset0:198 offset1:206
	ds_read2_b32 v[20:21], v60 offset0:231 offset1:239
	v_lshlrev_b32_e32 v2, 1, v55
	v_mov_b32_e32 v3, v37
	v_lshl_add_u64 v[22:23], v[46:47], 0, v[2:3]
	s_waitcnt lgkmcnt(6)
	v_cvt_pk_bf16_f32 v2, v8, v6
	v_or_b32_e32 v6, v57, v34
	v_lshlrev_b32_e32 v24, 9, v6
	v_mov_b32_e32 v25, v37
	s_waitcnt lgkmcnt(4)
	v_cvt_pk_bf16_f32 v3, v10, v12
	s_waitcnt lgkmcnt(2)
	v_cvt_pk_bf16_f32 v4, v14, v16
	s_waitcnt lgkmcnt(0)
	v_cvt_pk_bf16_f32 v5, v18, v20
	v_lshl_add_u64 v[24:25], v[22:23], 0, v[24:25]
	global_store_dwordx4 v[24:25], v[2:5], off
	v_or_b32_e32 v6, v57, v53
	v_lshlrev_b32_e32 v6, 9, v6
	v_cvt_pk_bf16_f32 v2, v9, v7
	v_cvt_pk_bf16_f32 v3, v11, v13
	v_cvt_pk_bf16_f32 v4, v15, v17
	v_cvt_pk_bf16_f32 v5, v19, v21
	ds_read2_b32 v[8:9], v60 offset0:49 offset1:57
	ds_read2_b32 v[10:11], v60 offset0:16 offset1:24
	ds_read2_b32 v[12:13], v60 offset0:82 offset1:90
	ds_read2_b32 v[14:15], v60 offset0:115 offset1:123
	ds_read2_b32 v[16:17], v60 offset0:148 offset1:156
	ds_read2_b32 v[18:19], v60 offset0:181 offset1:189
	ds_read2_b32 v[20:21], v60 offset0:214 offset1:222
	ds_read2_b32 v[24:25], v60 offset0:247 offset1:255
	v_mov_b32_e32 v7, v37
	v_lshl_add_u64 v[6:7], v[22:23], 0, v[6:7]
	global_store_dwordx4 v[6:7], v[2:5], off
	v_or_b32_e32 v6, v57, v58
	v_lshlrev_b32_e32 v6, 9, v6
	v_mov_b32_e32 v7, v37
	s_waitcnt lgkmcnt(6)
	v_cvt_pk_bf16_f32 v2, v10, v8
	s_waitcnt lgkmcnt(4)
	v_cvt_pk_bf16_f32 v3, v12, v14
	s_waitcnt lgkmcnt(2)
	v_cvt_pk_bf16_f32 v4, v16, v18
	s_waitcnt lgkmcnt(0)
	v_cvt_pk_bf16_f32 v5, v20, v24
	v_lshl_add_u64 v[6:7], v[22:23], 0, v[6:7]
	global_store_dwordx4 v[6:7], v[2:5], off
	v_or_b32_e32 v6, v57, v59
	v_lshlrev_b32_e32 v6, 9, v6
	v_mov_b32_e32 v7, v37
	v_cvt_pk_bf16_f32 v2, v11, v9
	v_cvt_pk_bf16_f32 v3, v13, v15
	v_cvt_pk_bf16_f32 v4, v17, v19
	v_cvt_pk_bf16_f32 v5, v21, v25
	v_lshl_add_u64 v[6:7], v[22:23], 0, v[6:7]
	global_store_dwordx4 v[6:7], v[2:5], off
	s_waitcnt lgkmcnt(0)

; #define LAS __attribute__((address_space(3)))
; template <int KIND>
; DI void transpose_item(const float* W, int K, int N, bf16_t* WT, int ldk, const float* g0, const float* g1, const float* g2, LAS float* scr, int item, int lane) {
;     const int nblk = N / 32, kb = item / nblk, nb = item % nblk, k0 = 64 * kb, n0 = 32 * nb;
;     f32x4 tv[8];
; #pragma unroll
;     for (int i = 0; i < 8; ++i) tv[i] = *(const f32x4*)(W + (size_t)(k0 + 8 * i + (lane >> 3)) * N + n0 + 4 * (lane & 7));
; #pragma unroll
;     for (int i = 0; i < 8; ++i) {
;         const int kk = 8 * i + (lane >> 3), k = k0 + kk;
;         float gn = 1.f;
;         if (KIND == 0 || KIND == 1 || KIND == 2 || KIND == 5 || KIND == 6) gn = g0[k];
;         if (KIND == 4) gn = k < 1024 ? g0[k] : (k < 1536 ? g1[k - 1024] : g2[k - 1536]);
;         LAS float* d = scr + kk * 33 + 4 * (lane & 7);
;         d[0] = tv[i][0] * gn; d[1] = tv[i][1] * gn; d[2] = tv[i][2] * gn; d[3] = tv[i][3] * gn;
;     }
;     asm volatile("s_waitcnt lgkmcnt(0)" ::: "memory");
;     int kd0 = k0;
;     if (KIND == 4) kd0 = k0 < 1024 ? k0 + 512 : (k0 < 1536 ? k0 - 1024 : k0);
.LBB0_140:
	s_andn2_saveexec_b64 s[6:7], s[58:59]
	s_cbranch_execz .LBB0_142
	v_add_u16_e32 v2, 0xf4c0, v1
	v_mul_u32_u24_e32 v3, 0xaaab, v2
	s_load_dwordx4 s[8:11], s[4:5], 0x18
	v_lshrrev_b32_e32 v3, 21, v3
	v_mul_lo_u16_e32 v4, 48, v3
	v_sub_u16_e32 v2, v2, v4
	v_lshlrev_b16_e32 v55, 6, v3
	v_lshlrev_b16_e32 v57, 5, v2
	v_or_b32_e32 v20, v34, v55
	v_lshlrev_b32_e32 v2, 2, v57
	v_mov_b32_e32 v3, v37
	s_waitcnt lgkmcnt(0)
	v_lshl_add_u64 v[2:3], s[10:11], 0, v[2:3]
	v_mul_u32_u24_e32 v4, 0x600, v20
	v_lshl_add_u64 v[2:3], v[2:3], 0, v[36:37]
	v_lshlrev_b32_e32 v4, 2, v4
	v_mov_b32_e32 v5, v37
	v_lshl_add_u64 v[30:31], v[2:3], 0, v[4:5]
	s_mov_b32 s10, 0xc000
	v_add_co_u32_e32 v6, vcc, s10, v30
	s_mov_b32 s10, 0x24000
	s_nop 0
	v_addc_co_u32_e32 v7, vcc, 0, v31, vcc
	v_add_co_u32_e32 v10, vcc, s82, v30
	v_lshlrev_b32_e32 v32, 2, v20
	s_nop 0
	v_addc_co_u32_e32 v11, vcc, 0, v31, vcc
	v_add_co_u32_e32 v14, vcc, s10, v30
	s_mov_b32 s10, 0x3c000
	s_nop 0
	v_addc_co_u32_e32 v15, vcc, 0, v31, vcc
	v_add_co_u32_e32 v18, vcc, s68, v30
	global_load_dwordx4 v[2:5], v[30:31], off nt
	s_nop 0
	global_load_dwordx4 v[6:9], v[6:7], off nt
	v_addc_co_u32_e32 v19, vcc, 0, v31, vcc
	v_add_co_u32_e32 v22, vcc, s10, v30
	s_mov_b32 s10, 0x48000
	s_nop 0
	v_addc_co_u32_e32 v23, vcc, 0, v31, vcc
	v_add_co_u32_e32 v26, vcc, s10, v30
	global_load_dwordx4 v[10:13], v[10:11], off nt
	s_nop 0
	global_load_dwordx4 v[14:17], v[14:15], off nt
	v_addc_co_u32_e32 v27, vcc, 0, v31, vcc
	global_load_dword v56, v32, s[8:9]
	s_mov_b32 s10, 0x54000
	v_add_co_u32_e32 v30, vcc, s10, v30
	global_load_dwordx4 v[18:21], v[18:19], off nt
	s_nop 0
	global_load_dwordx4 v[22:25], v[22:23], off nt
	s_nop 0
	global_load_dword v84, v32, s[8:9] offset:32
	global_load_dword v86, v32, s[8:9] offset:64
	global_load_dword v88, v32, s[8:9] offset:96
	global_load_dword v90, v32, s[8:9] offset:128
	global_load_dword v92, v32, s[8:9] offset:160
	s_nop 0
	global_load_dwordx4 v[26:29], v[26:27], off nt
	s_nop 0
	global_load_dword v94, v32, s[8:9] offset:192
	v_addc_co_u32_e32 v31, vcc, 0, v31, vcc
	global_load_dword v96, v32, s[8:9] offset:224
	s_nop 0
	global_load_dwordx4 v[30:33], v[30:31], off nt
	v_add_u32_e32 v85, v35, v61
	v_add_u32_e32 v87, 0x420, v85
	v_add_u32_e32 v89, 0x428, v85
	v_add_u32_e32 v91, 0x840, v85
	s_waitcnt vmcnt(11)
	v_pk_mul_f32 v[2:3], v[2:3], v[56:57] op_sel_hi:[1,0]
	v_pk_mul_f32 v[4:5], v[4:5], v[56:57] op_sel_hi:[1,0]
	ds_write2_b32 v65, v2, v3 offset1:1
	ds_write2_b32 v65, v4, v5 offset0:2 offset1:3
	s_waitcnt vmcnt(8)
	v_pk_mul_f32 v[2:3], v[6:7], v[84:85] op_sel_hi:[1,0]
	v_pk_mul_f32 v[4:5], v[8:9], v[84:85] op_sel_hi:[1,0]
	s_waitcnt vmcnt(7)
	v_pk_mul_f32 v[6:7], v[10:11], v[86:87] op_sel_hi:[1,0]
	v_pk_mul_f32 v[8:9], v[12:13], v[86:87] op_sel_hi:[1,0]
	s_waitcnt vmcnt(6)
	v_pk_mul_f32 v[10:11], v[14:15], v[88:89] op_sel_hi:[1,0]
	v_pk_mul_f32 v[12:13], v[16:17], v[88:89] op_sel_hi:[1,0]
	s_waitcnt vmcnt(5)
	v_pk_mul_f32 v[14:15], v[18:19], v[90:91] op_sel_hi:[1,0]
	v_pk_mul_f32 v[16:17], v[20:21], v[90:91] op_sel_hi:[1,0]
	s_waitcnt vmcnt(4)
	v_pk_mul_f32 v[18:19], v[22:23], v[92:93] op_sel_hi:[1,0]
	v_pk_mul_f32 v[20:21], v[24:25], v[92:93] op_sel_hi:[1,0]
	s_waitcnt vmcnt(2)
	v_pk_mul_f32 v[22:23], v[26:27], v[94:95] op_sel_hi:[1,0]
	v_pk_mul_f32 v[24:25], v[28:29], v[94:95] op_sel_hi:[1,0]
	ds_write2_b32 v66, v2, v3 offset1:1
	ds_write2_b32 v67, v4, v5 offset1:1
	ds_write2_b32 v68, v6, v7 offset1:1
	ds_write2_b32 v69, v8, v9 offset1:1
	ds_write2_b32 v70, v10, v11 offset1:1
	ds_write2_b32 v71, v12, v13 offset1:1
	ds_write2_b32 v85, v14, v15 offset1:1
	ds_write2_b32 v85, v16, v17 offset0:2 offset1:3
	ds_write2_b32 v87, v18, v19 offset1:1
	ds_write2_b32 v89, v20, v21 offset1:1
	ds_write2_b32 v91, v22, v23 offset1:1
	v_add_u32_e32 v2, 0x848, v85
	ds_write2_b32 v2, v24, v25 offset1:1
	s_waitcnt vmcnt(0)
; #define LAS __attribute__((address_space(3)))
; DI unsigned cvtpk(float lo, float hi) { f32x2 v = {lo, hi}; bf16x2_t b = __builtin_convertvector(v, bf16x2_t); return __builtin_bit_cast(unsigned, b); }
; template <int KIND> DI int map_n(int n) {
;     ...
;     if (KIND == 1) {
;         const int hd = n / 192, w = n % 192;
;         if (w < 128) return n;
;         const int j = w - 128; return hd * 192 + 128 + (j < 32 ? 2 * j : 2 * (j - 32) + 1);
;     }
; template <int KIND>
; DI void transpose_item(const float* W, int K, int N, bf16_t* WT, int ldk, const float* g0, const float* g1, const float* g2, LAS float* scr, int item, int lane) {
;     ...
;     for (int j = 0; j < 4; ++j) { const int n = (lane >> 3) + 8 * j; const LAS float* s = scr + (8 * c) * 33 + n;
;         u32x4 o; o.x = cvtpk(s[0 * 33], s[1 * 33]); o.y = cvtpk(s[2 * 33], s[3 * 33]); o.z = cvtpk(s[4 * 33], s[5 * 33]); o.w = cvtpk(s[6 * 33], s[7 * 33]);
;         *(u32x4*)(WT + (size_t)map_n<KIND>(n0 + n) * ldk + kd0 + 8 * c) = o; }
	v_pk_mul_f32 v[2:3], v[30:31], v[96:97] op_sel_hi:[1,0]
	v_add_u32_e32 v4, 0xc60, v85
	ds_write2_b32 v4, v2, v3 offset1:1
	v_pk_mul_f32 v[2:3], v[32:33], v[96:97] op_sel_hi:[1,0]
	v_add_u32_e32 v4, 0xc68, v85
	ds_write2_b32 v4, v2, v3 offset1:1
	s_waitcnt lgkmcnt(0)
	v_lshlrev_b32_e32 v2, 1, v55
	v_mov_b32_e32 v3, v37
	ds_read2_b32 v[6:7], v60 offset0:33 offset1:41
	ds_read2_b32 v[8:9], v60 offset1:8
	ds_read2_b32 v[10:11], v60 offset0:66 offset1:74
	ds_read2_b32 v[12:13], v60 offset0:99 offset1:107
	ds_read2_b32 v[14:15], v60 offset0:132 offset1:140
	ds_read2_b32 v[16:17], v60 offset0:165 offset1:173
	ds_read2_b32 v[18:19], v60 offset0:198 offset1:206
	ds_read2_b32 v[20:21], v60 offset0:231 offset1:239
	v_lshl_add_u64 v[22:23], v[48:49], 0, v[2:3]
	s_waitcnt lgkmcnt(6)
	v_cvt_pk_bf16_f32 v2, v8, v6
	v_or_b32_e32 v6, v34, v57
	v_mul_u32_u24_e32 v8, 0x2aab, v6
	v_lshrrev_b32_e32 v8, 21, v8
	v_mul_lo_u16_e32 v8, 0xc0, v8
	v_sub_u16_e32 v8, v6, v8
	s_waitcnt lgkmcnt(4)
	v_cvt_pk_bf16_f32 v3, v10, v12
	v_cmp_gt_u16_e32 vcc, s84, v8
	v_sub_u32_e32 v12, v6, v8
	v_lshl_add_u32 v12, v8, 1, v12
	v_cndmask_b32_e32 v10, v80, v81, vcc
	v_add3_u32 v10, v12, v10, s83
	v_cmp_gt_u16_e32 vcc, s83, v8
	s_waitcnt lgkmcnt(2)
	v_cvt_pk_bf16_f32 v4, v14, v16
	s_waitcnt lgkmcnt(0)
	v_cvt_pk_bf16_f32 v5, v18, v20
	v_cndmask_b32_e32 v24, v10, v6, vcc
	v_ashrrev_i32_e32 v25, 31, v24
	v_lshlrev_b64 v[24:25], 10, v[24:25]
	v_lshl_add_u64 v[24:25], v[22:23], 0, v[24:25]
	v_or_b32_e32 v6, v53, v57
	global_store_dwordx4 v[24:25], v[2:5], off
	s_nop 1
	v_cvt_pk_bf16_f32 v2, v9, v7
	v_mul_u32_u24_e32 v7, 0x2aab, v6
	v_lshrrev_b32_e32 v7, 21, v7
	v_mul_lo_u16_e32 v7, 0xc0, v7
	v_sub_u16_e32 v7, v6, v7
	v_cmp_gt_u16_e32 vcc, s84, v7
	v_sub_u32_e32 v9, v6, v7
	v_lshl_add_u32 v9, v7, 1, v9
	v_cndmask_b32_e32 v8, v80, v81, vcc
	v_add3_u32 v8, v9, v8, s83
	v_cmp_gt_u16_e32 vcc, s83, v7
	v_cvt_pk_bf16_f32 v3, v11, v13
	v_cvt_pk_bf16_f32 v4, v15, v17
	v_cndmask_b32_e32 v6, v8, v6, vcc
	v_ashrrev_i32_e32 v7, 31, v6
	v_lshlrev_b64 v[6:7], 10, v[6:7]
	v_cvt_pk_bf16_f32 v5, v19, v21
	v_lshl_add_u64 v[6:7], v[22:23], 0, v[6:7]
	ds_read2_b32 v[8:9], v60 offset0:16 offset1:24
	ds_read2_b32 v[10:11], v60 offset0:49 offset1:57
	ds_read2_b32 v[12:13], v60 offset0:82 offset1:90
	ds_read2_b32 v[14:15], v60 offset0:115 offset1:123
	ds_read2_b32 v[16:17], v60 offset0:148 offset1:156
	ds_read2_b32 v[18:19], v60 offset0:181 offset1:189
	ds_read2_b32 v[20:21], v60 offset0:214 offset1:222
	ds_read2_b32 v[24:25], v60 offset0:247 offset1:255
	global_store_dwordx4 v[6:7], v[2:5], off
	v_or_b32_e32 v6, v58, v57
	v_mul_u32_u24_e32 v7, 0x2aab, v6
	v_lshrrev_b32_e32 v7, 21, v7
	v_mul_lo_u16_e32 v7, 0xc0, v7
	v_sub_u16_e32 v7, v6, v7
	s_waitcnt lgkmcnt(6)
	v_cvt_pk_bf16_f32 v2, v8, v10
	v_cmp_gt_u16_e32 vcc, s84, v7
	v_sub_u32_e32 v10, v6, v7
	v_lshl_add_u32 v10, v7, 1, v10
	v_cndmask_b32_e32 v8, v80, v81, vcc
	v_add3_u32 v8, v10, v8, s83
	v_cmp_gt_u16_e32 vcc, s83, v7
	s_waitcnt lgkmcnt(4)
	v_cvt_pk_bf16_f32 v3, v12, v14
	s_waitcnt lgkmcnt(2)
	v_cvt_pk_bf16_f32 v4, v16, v18
	v_cndmask_b32_e32 v6, v8, v6, vcc
	v_ashrrev_i32_e32 v7, 31, v6
	v_lshlrev_b64 v[6:7], 10, v[6:7]
	s_waitcnt lgkmcnt(0)
	v_cvt_pk_bf16_f32 v5, v20, v24
	v_lshl_add_u64 v[6:7], v[22:23], 0, v[6:7]
	global_store_dwordx4 v[6:7], v[2:5], off
	v_or_b32_e32 v6, v59, v57
	v_mul_u32_u24_e32 v7, 0x2aab, v6
	v_lshrrev_b32_e32 v7, 21, v7
	v_mul_lo_u16_e32 v7, 0xc0, v7
	v_sub_u16_e32 v7, v6, v7
	v_cvt_pk_bf16_f32 v2, v9, v11
	v_cmp_gt_u16_e32 vcc, s84, v7
	v_sub_u32_e32 v9, v6, v7
	v_lshl_add_u32 v9, v7, 1, v9
	v_cndmask_b32_e32 v8, v80, v81, vcc
	v_add3_u32 v8, v9, v8, s83
	v_cmp_gt_u16_e32 vcc, s83, v7
	v_cvt_pk_bf16_f32 v3, v13, v15
	v_cvt_pk_bf16_f32 v4, v17, v19
	v_cndmask_b32_e32 v6, v8, v6, vcc
	v_ashrrev_i32_e32 v7, 31, v6
	v_lshlrev_b64 v[6:7], 10, v[6:7]
	v_cvt_pk_bf16_f32 v5, v21, v25
	v_lshl_add_u64 v[6:7], v[22:23], 0, v[6:7]
	global_store_dwordx4 v[6:7], v[2:5], off
	s_waitcnt lgkmcnt(0)

; #define LAS __attribute__((address_space(3)))
; DI unsigned cvtpk(float lo, float hi) { f32x2 v = {lo, hi}; bf16x2_t b = __builtin_convertvector(v, bf16x2_t); return __builtin_bit_cast(unsigned, b); }
; template <int KIND>
; DI void transpose_item(const float* W, int K, int N, bf16_t* WT, int ldk, const float* g0, const float* g1, const float* g2, LAS float* scr, int item, int lane) {
;     const int nblk = N / 32, kb = item / nblk, nb = item % nblk, k0 = 64 * kb, n0 = 32 * nb;
;     f32x4 tv[8];
; #pragma unroll
;     for (int i = 0; i < 8; ++i) tv[i] = *(const f32x4*)(W + (size_t)(k0 + 8 * i + (lane >> 3)) * N + n0 + 4 * (lane & 7));
; #pragma unroll
;     for (int i = 0; i < 8; ++i) {
;         const int kk = 8 * i + (lane >> 3), k = k0 + kk;
;         float gn = 1.f;
;         if (KIND == 0 || KIND == 1 || KIND == 2 || KIND == 5 || KIND == 6) gn = g0[k];
;         if (KIND == 4) gn = k < 1024 ? g0[k] : (k < 1536 ? g1[k - 1024] : g2[k - 1536]);
;         LAS float* d = scr + kk * 33 + 4 * (lane & 7);
;         d[0] = tv[i][0] * gn; d[1] = tv[i][1] * gn; d[2] = tv[i][2] * gn; d[3] = tv[i][3] * gn;
;     }
;     asm volatile("s_waitcnt lgkmcnt(0)" ::: "memory");
;     int kd0 = k0;
;     if (KIND == 4) kd0 = k0 < 1024 ? k0 + 512 : (k0 < 1536 ? k0 - 1024 : k0);
;     const int c = lane & 7;
; #pragma unroll
;     for (int j = 0; j < 4; ++j) { const int n = (lane >> 3) + 8 * j; const LAS float* s = scr + (8 * c) * 33 + n;
;         u32x4 o; o.x = cvtpk(s[0 * 33], s[1 * 33]); o.y = cvtpk(s[2 * 33], s[3 * 33]); o.z = cvtpk(s[4 * 33], s[5 * 33]); o.w = cvtpk(s[6 * 33], s[7 * 33]);
;         *(u32x4*)(WT + (size_t)map_n<KIND>(n0 + n) * ldk + kd0 + 8 * c) = o; }
;     asm volatile("s_waitcnt lgkmcnt(0)" ::: "memory");
; }
.LBB0_143:
	s_andn2_saveexec_b64 s[6:7], s[56:57]
	s_cbranch_execz .LBB0_52
	s_load_dwordx4 s[8:11], s[4:5], 0x8
	s_mov_b32 s12, 0xb60b60b7
	v_mul_hi_i32 v2, v1, s12
	v_add_u32_e32 v2, v2, v1
	v_lshrrev_b32_e32 v3, 31, v2
	v_ashrrev_i32_e32 v2, 6, v2
	s_waitcnt lgkmcnt(0)
	v_mov_b32_e32 v6, s10
	v_add_u32_e32 v16, v2, v3
	s_movk_i32 s10, 0xf4c0
	v_mov_b32_e32 v7, s11
	v_lshlrev_b32_e32 v4, 6, v16
	v_mad_u64_u32 v[2:3], s[10:11], v16, s10, v[52:53]
	v_or_b32_e32 v14, v4, v34
	v_ashrrev_i32_e32 v3, 31, v2
	v_lshl_add_u64 v[6:7], v[2:3], 2, v[6:7]
	v_ashrrev_i32_e32 v15, 31, v14
	v_ashrrev_i32_e32 v5, 31, v4
	v_lshl_add_u64 v[56:57], v[6:7], 0, v[36:37]
	v_lshl_add_u64 v[8:9], v[14:15], 2, s[8:9]
	v_or_b32_e32 v3, 8, v14
	v_mov_b32_e32 v15, v5
	v_mad_i64_i32 v[10:11], s[10:11], v3, s85, v[56:57]
	v_lshl_add_u64 v[88:89], v[14:15], 2, s[8:9]
	v_or_b32_e32 v3, 16, v14
	v_or_b32_e32 v15, 24, v14
	v_or_b32_e32 v17, 32, v14
	v_or_b32_e32 v20, 40, v14
	v_mad_i64_i32 v[6:7], s[10:11], v14, s85, v[56:57]
	global_load_dword v92, v[8:9], off
	v_or_b32_e32 v55, 48, v14
	v_mad_i64_i32 v[18:19], s[8:9], v3, s85, v[56:57]
	v_mad_i64_i32 v[22:23], s[8:9], v15, s85, v[56:57]
	v_mad_i64_i32 v[26:27], s[8:9], v17, s85, v[56:57]
	v_mad_i64_i32 v[30:31], s[8:9], v20, s85, v[56:57]
	v_or_b32_e32 v3, 56, v14
	global_load_dwordx4 v[6:9], v[6:7], off nt
	s_nop 0
	global_load_dwordx4 v[10:13], v[10:11], off nt
	s_nop 0
	global_load_dwordx4 v[18:21], v[18:19], off nt
	s_nop 0
	global_load_dwordx4 v[22:25], v[22:23], off nt
	s_nop 0
	global_load_dword v94, v[88:89], off offset:32
	global_load_dword v96, v[88:89], off offset:64
	global_load_dword v98, v[88:89], off offset:96
	global_load_dword v100, v[88:89], off offset:128
	global_load_dword v102, v[88:89], off offset:160
	s_nop 0
	global_load_dwordx4 v[26:29], v[26:27], off nt
	s_nop 0
	global_load_dwordx4 v[30:33], v[30:31], off nt
	v_mad_i64_i32 v[84:85], s[8:9], v55, s85, v[56:57]
	v_mad_i64_i32 v[14:15], s[8:9], v3, s85, v[56:57]
	global_load_dwordx4 v[84:87], v[84:85], off nt
	s_nop 0
	global_load_dword v104, v[88:89], off offset:192
	global_load_dword v106, v[88:89], off offset:224
	s_movk_i32 s8, 0x5a
	global_load_dwordx4 v[88:91], v[14:15], off nt
	v_add_u32_e32 v3, v35, v61
	v_mul_lo_u32 v14, v16, s8
	v_add_u32_e32 v17, 0x420, v3
	v_add_u32_e32 v55, 0x428, v3
	v_add_u32_e32 v56, 0x840, v3
	v_sub_u32_e32 v57, v1, v14
	s_waitcnt vmcnt(9)
	v_pk_mul_f32 v[14:15], v[18:19], v[96:97] op_sel_hi:[1,0]
	v_pk_mul_f32 v[18:19], v[20:21], v[96:97] op_sel_hi:[1,0]
	s_waitcnt vmcnt(8)
	v_pk_mul_f32 v[20:21], v[22:23], v[98:99] op_sel_hi:[1,0]
	v_pk_mul_f32 v[6:7], v[6:7], v[92:93] op_sel_hi:[1,0]
	v_pk_mul_f32 v[8:9], v[8:9], v[92:93] op_sel_hi:[1,0]
	v_pk_mul_f32 v[10:11], v[10:11], v[94:95] op_sel_hi:[1,0]
	v_pk_mul_f32 v[12:13], v[12:13], v[94:95] op_sel_hi:[1,0]
	v_pk_mul_f32 v[22:23], v[24:25], v[98:99] op_sel_hi:[1,0]
	s_waitcnt vmcnt(5)
	v_pk_mul_f32 v[24:25], v[26:27], v[100:101] op_sel_hi:[1,0]
	v_pk_mul_f32 v[26:27], v[28:29], v[100:101] op_sel_hi:[1,0]
	s_waitcnt vmcnt(4)
	v_pk_mul_f32 v[28:29], v[30:31], v[102:103] op_sel_hi:[1,0]
	v_pk_mul_f32 v[30:31], v[32:33], v[102:103] op_sel_hi:[1,0]
	s_waitcnt vmcnt(2)
	v_pk_mul_f32 v[32:33], v[84:85], v[104:105] op_sel_hi:[1,0]
	ds_write2_b32 v65, v6, v7 offset1:1
	ds_write2_b32 v65, v8, v9 offset0:2 offset1:3
	ds_write2_b32 v66, v10, v11 offset1:1
	ds_write2_b32 v67, v12, v13 offset1:1
	ds_write2_b32 v68, v14, v15 offset1:1
	ds_write2_b32 v69, v18, v19 offset1:1
	ds_write2_b32 v70, v20, v21 offset1:1
	ds_write2_b32 v71, v22, v23 offset1:1
	ds_write2_b32 v3, v24, v25 offset1:1
	ds_write2_b32 v3, v26, v27 offset0:2 offset1:3
	ds_write2_b32 v17, v28, v29 offset1:1
	ds_write2_b32 v55, v30, v31 offset1:1
	ds_write2_b32 v56, v32, v33 offset1:1
	v_pk_mul_f32 v[6:7], v[86:87], v[104:105] op_sel_hi:[1,0]
	v_add_u32_e32 v8, 0x848, v3
	ds_write2_b32 v8, v6, v7 offset1:1
	s_waitcnt vmcnt(0)
	v_pk_mul_f32 v[6:7], v[88:89], v[106:107] op_sel_hi:[1,0]
	v_add_u32_e32 v8, 0xc60, v3
	ds_write2_b32 v8, v6, v7 offset1:1
	v_pk_mul_f32 v[6:7], v[90:91], v[106:107] op_sel_hi:[1,0]
	v_add_u32_e32 v3, 0xc68, v3
	ds_write2_b32 v3, v6, v7 offset1:1
	s_waitcnt lgkmcnt(0)
	ds_read2_b32 v[6:7], v60 offset1:33
	ds_read2_b32 v[8:9], v60 offset0:66 offset1:99
	ds_read2_b32 v[10:11], v60 offset0:132 offset1:165
	ds_read2_b32 v[12:13], v60 offset0:198 offset1:231
	v_lshlrev_b32_e32 v3, 5, v57
	v_add_u32_e32 v17, v2, v34
	v_or_b32_e32 v14, v3, v34
	v_cmp_lt_i32_e32 vcc, s86, v17
	s_and_saveexec_b64 s[8:9], vcc
	s_cbranch_execz .LBB0_150
	v_cmp_lt_u32_e32 vcc, s87, v2
	s_and_saveexec_b64 s[10:11], vcc
	s_xor_b64 s[10:11], exec, s[10:11]
	v_subrev_u32_e32 v14, 64, v14
	s_andn2_saveexec_b64 s[10:11], s[10:11]
	v_cmp_gt_u32_e32 vcc, s88, v2
	v_mul_lo_u32 v15, v16, s89
	s_movk_i32 s12, 0xb00
	v_cndmask_b32_e32 v14, v82, v83, vcc
	v_sub_u32_e32 v14, v14, v15
	v_add_u32_e32 v15, v62, v63
	v_add3_u32 v14, v15, v14, s12
	s_or_b64 exec, exec, s[10:11]

; #define LAS __attribute__((address_space(3)))
; template <int KIND>
; DI void transpose_item(const float* W, int K, int N, bf16_t* WT, int ldk, const float* g0, const float* g1, const float* g2, LAS float* scr, int item, int lane) {
;     const int nblk = N / 32, kb = item / nblk, nb = item % nblk, k0 = 64 * kb, n0 = 32 * nb;
;     f32x4 tv[8];
; #pragma unroll
;     for (int i = 0; i < 8; ++i) tv[i] = *(const f32x4*)(W + (size_t)(k0 + 8 * i + (lane >> 3)) * N + n0 + 4 * (lane & 7));
; #pragma unroll
;     for (int i = 0; i < 8; ++i) {
;         const int kk = 8 * i + (lane >> 3), k = k0 + kk;
;         float gn = 1.f;
;         if (KIND == 0 || KIND == 1 || KIND == 2 || KIND == 5 || KIND == 6) gn = g0[k];
;         if (KIND == 4) gn = k < 1024 ? g0[k] : (k < 1536 ? g1[k - 1024] : g2[k - 1536]);
;         LAS float* d = scr + kk * 33 + 4 * (lane & 7);
;         d[0] = tv[i][0] * gn; d[1] = tv[i][1] * gn; d[2] = tv[i][2] * gn; d[3] = tv[i][3] * gn;
;     }
;     asm volatile("s_waitcnt lgkmcnt(0)" ::: "memory");
;     int kd0 = k0;
;     if (KIND == 4) kd0 = k0 < 1024 ? k0 + 512 : (k0 < 1536 ? k0 - 1024 : k0);
;     const int c = lane & 7;
; #pragma unroll
;     for (int j = 0; j < 4; ++j) { const int n = (lane >> 3) + 8 * j; const LAS float* s = scr + (8 * c) * 33 + n;
;         u32x4 o; o.x = cvtpk(s[0 * 33], s[1 * 33]); o.y = cvtpk(s[2 * 33], s[3 * 33]); o.z = cvtpk(s[4 * 33], s[5 * 33]); o.w = cvtpk(s[6 * 33], s[7 * 33]);
;         *(u32x4*)(WT + (size_t)map_n<KIND>(n0 + n) * ldk + kd0 + 8 * c) = o; }
;     asm volatile("s_waitcnt lgkmcnt(0)" ::: "memory");
; }
; DI void convert_weights(PP p, LAS unsigned char* lds, int l, int worker, int nworkers) {
;     ...
;     for (int it = worker; it < I_LAYER; it += nworkers) {
;         int r = it;
;         if (r < I_IN) { transpose_item<0>(p->in[2] + (size_t)l * 2048 * 2880, 2048, 2880, (bf16_t*)(wl + W_IN), 2048, p->in[1] + l * 2048, nullptr, nullptr, scr, r, lane); continue; } r -= I_IN;
;         if (r < I_UQ) { transpose_item<1>(p->in[4] + (size_t)l * 512 * 1536, 512, 1536, (bf16_t*)(wl + W_UQ), 512, p->in[3] + l * 512, nullptr, nullptr, scr, r, lane); continue; } r -= I_UQ;
;         if (r < I_UKV) { transpose_item<2>(p->in[6] + (size_t)l * 256 * 2048, 256, 2048, (bf16_t*)(wl + W_UKV), 256, p->in[5] + l * 256, nullptr, nullptr, scr, r, lane); continue; } r -= I_UKV;
.LBB0_624:
	s_movk_i32 s4, 0xb3f
	v_cmp_lt_i32_e32 vcc, s4, v62
	s_and_saveexec_b64 s[6:7], vcc
	s_xor_b64 s[62:63], exec, s[6:7]
	s_cbranch_execz .LBB0_714
	s_movk_i32 s4, 0xcbf
	v_cmp_lt_u32_e32 vcc, s4, v62
	s_and_saveexec_b64 s[6:7], vcc
	s_xor_b64 s[64:65], exec, s[6:7]
	s_cbranch_execz .LBB0_711
	s_movk_i32 s4, 0xdbf
	v_cmp_lt_u32_e32 vcc, s4, v62
	s_and_saveexec_b64 s[6:7], vcc
	s_xor_b64 s[66:67], exec, s[6:7]
	s_cbranch_execz .LBB0_708
	s_movk_i32 s4, 0xebf
	v_cmp_lt_u32_e32 vcc, s4, v62
	s_and_saveexec_b64 s[6:7], vcc
	s_xor_b64 s[68:69], exec, s[6:7]
	s_cbranch_execz .LBB0_705
	s_movk_i32 s4, 0x16bf
	v_cmp_lt_u32_e32 vcc, s4, v62
	s_and_saveexec_b64 s[6:7], vcc
	s_xor_b64 s[6:7], exec, s[6:7]
	s_cbranch_execz .LBB0_638
	s_movk_i32 s4, 0x2cbf
	v_cmp_lt_u32_e32 vcc, s4, v62
	s_and_saveexec_b64 s[14:15], vcc
	s_xor_b64 s[14:15], exec, s[14:15]
	s_cbranch_execz .LBB0_635
	s_movk_i32 s4, 0x42bf
	v_cmp_lt_u32_e32 vcc, s4, v62
	s_and_saveexec_b64 s[16:17], vcc
	s_xor_b64 s[16:17], exec, s[16:17]
	s_cbranch_execz .LBB0_632
	s_load_dwordx2 s[18:19], s[8:9], 0xc0
	v_add_u32_e32 v0, 0xffffbd40, v62
	v_and_b32_e32 v53, 0x1fc0, v0
	v_add_u32_e32 v0, 0xfff7a800, v50
	v_and_b32_e32 v54, 0x7c0, v0
	s_waitcnt lgkmcnt(0)
	s_add_u32 s18, s18, s1
	s_addc_u32 s19, s19, s0
	v_lshlrev_b32_e32 v128, 2, v54
	v_or_b32_e32 v2, v53, v32
	v_lshl_add_u64 v[0:1], s[18:19], 0, v[128:129]
	v_lshlrev_b32_e32 v128, 2, v34
	v_lshl_add_u64 v[0:1], v[0:1], 0, v[128:129]
	v_lshlrev_b32_e32 v128, 13, v2
	v_lshl_add_u64 v[28:29], v[0:1], 0, v[128:129]
	s_mov_b32 s4, 0x10000
	v_add_co_u32_e32 v4, vcc, s4, v28
	global_load_dwordx4 v[0:3], v[28:29], off nt
	s_nop 0
	v_addc_co_u32_e32 v5, vcc, 0, v29, vcc
	s_mov_b32 s4, 0x20000
	global_load_dwordx4 v[4:7], v[4:5], off nt
	v_add_co_u32_e32 v8, vcc, s4, v28
	s_mov_b32 s4, 0x30000
	s_nop 0
	v_addc_co_u32_e32 v9, vcc, 0, v29, vcc
	global_load_dwordx4 v[8:11], v[8:9], off nt
	v_add_co_u32_e32 v12, vcc, s4, v28
	s_mov_b32 s4, 0x50000
	s_nop 0
	v_addc_co_u32_e32 v13, vcc, 0, v29, vcc
	global_load_dwordx4 v[12:15], v[12:13], off nt
	v_add_co_u32_e32 v16, vcc, s89, v28
	v_add_u32_e32 v55, v33, v35
	s_nop 0
	v_addc_co_u32_e32 v17, vcc, 0, v29, vcc
	global_load_dwordx4 v[16:19], v[16:17], off nt
	v_add_co_u32_e32 v20, vcc, s4, v28
	s_mov_b32 s4, 0x60000
	s_nop 0
	v_addc_co_u32_e32 v21, vcc, 0, v29, vcc
	global_load_dwordx4 v[20:23], v[20:21], off nt
	v_add_co_u32_e32 v24, vcc, s4, v28
	s_mov_b32 s4, 0x70000
	s_nop 0
	v_addc_co_u32_e32 v25, vcc, 0, v29, vcc
	global_load_dwordx4 v[24:27], v[24:25], off nt
	v_add_co_u32_e32 v28, vcc, s4, v28
	v_lshlrev_b32_e32 v128, 1, v53
	s_nop 0
	v_addc_co_u32_e32 v29, vcc, 0, v29, vcc
	global_load_dwordx4 v[28:31], v[28:29], off nt
	s_waitcnt vmcnt(7)
	ds_write2_b32 v55, v0, v1 offset1:1
	ds_write2_b32 v55, v2, v3 offset0:2 offset1:3
	v_add_u32_e32 v0, 0x420, v55
	s_waitcnt vmcnt(6)
	ds_write2_b32 v0, v4, v5 offset1:1
	v_add_u32_e32 v0, 0x428, v55
	ds_write2_b32 v0, v6, v7 offset1:1
	v_add_u32_e32 v0, 0x840, v55
	s_waitcnt vmcnt(5)
	ds_write2_b32 v0, v8, v9 offset1:1
	v_add_u32_e32 v0, 0x848, v55
	ds_write2_b32 v0, v10, v11 offset1:1
	v_add_u32_e32 v0, 0xc60, v55
	s_waitcnt vmcnt(4)
	ds_write2_b32 v0, v12, v13 offset1:1
	v_add_u32_e32 v0, 0xc68, v55
	ds_write2_b32 v0, v14, v15 offset1:1
	v_add_u32_e32 v0, 0x1080, v55
	s_waitcnt vmcnt(3)
	ds_write2_b32 v0, v16, v17 offset1:1
	v_add_u32_e32 v0, 0x1088, v55
	ds_write2_b32 v0, v18, v19 offset1:1
	v_add_u32_e32 v0, 0x14a0, v55
	s_waitcnt vmcnt(2)
	ds_write2_b32 v0, v20, v21 offset1:1
	v_add_u32_e32 v0, 0x14a8, v55
	ds_write2_b32 v0, v22, v23 offset1:1
	v_add_u32_e32 v0, 0x18c0, v55
	s_waitcnt vmcnt(1)
	ds_write2_b32 v0, v24, v25 offset1:1
	v_add_u32_e32 v0, 0x18c8, v55
	ds_write2_b32 v0, v26, v27 offset1:1
	v_add_u32_e32 v0, 0x1ce0, v55
	s_waitcnt vmcnt(0)
	ds_write2_b32 v0, v28, v29 offset1:1
	v_add_u32_e32 v0, 0x1ce8, v55
	ds_write2_b32 v0, v30, v31 offset1:1
	s_waitcnt lgkmcnt(0)
	ds_read2_b32 v[6:7], v58 offset0:33 offset1:41
	ds_read2_b32 v[8:9], v58 offset1:8
	ds_read2_b32 v[10:11], v58 offset0:66 offset1:74
	ds_read2_b32 v[12:13], v58 offset0:99 offset1:107
	ds_read2_b32 v[14:15], v58 offset0:132 offset1:140
	ds_read2_b32 v[16:17], v58 offset0:165 offset1:173
	ds_read2_b32 v[18:19], v58 offset0:198 offset1:206
	ds_read2_b32 v[20:21], v58 offset0:231 offset1:239
	v_lshl_add_u64 v[0:1], v[36:37], 0, v[128:129]
	s_waitcnt lgkmcnt(6)
	v_cvt_pk_bf16_f32 v2, v8, v6
	v_or_b32_e32 v6, v54, v32
	v_mul_u32_u24_e32 v128, 0x2c00, v6
	v_or_b32_e32 v6, v54, v51
	s_waitcnt lgkmcnt(4)
	v_cvt_pk_bf16_f32 v3, v10, v12
	s_waitcnt lgkmcnt(2)
	v_cvt_pk_bf16_f32 v4, v14, v16
	s_waitcnt lgkmcnt(0)
	v_cvt_pk_bf16_f32 v5, v18, v20
	v_lshl_add_u64 v[22:23], v[0:1], 0, v[128:129]
	v_mul_u32_u24_e32 v128, 0x2c00, v6
	global_store_dwordx4 v[22:23], v[2:5], off
	s_nop 1
	v_cvt_pk_bf16_f32 v2, v9, v7
	v_cvt_pk_bf16_f32 v3, v11, v13
	v_cvt_pk_bf16_f32 v4, v15, v17
	v_cvt_pk_bf16_f32 v5, v19, v21
	v_lshl_add_u64 v[6:7], v[0:1], 0, v[128:129]
	global_store_dwordx4 v[6:7], v[2:5], off
	ds_read2_b32 v[6:7], v58 offset0:16 offset1:24
	ds_read2_b32 v[8:9], v58 offset0:49 offset1:57
	ds_read2_b32 v[10:11], v58 offset0:82 offset1:90
	ds_read2_b32 v[12:13], v58 offset0:115 offset1:123
	ds_read2_b32 v[14:15], v58 offset0:148 offset1:156
	ds_read2_b32 v[16:17], v58 offset0:181 offset1:189
	ds_read2_b32 v[18:19], v58 offset0:214 offset1:222
	ds_read2_b32 v[20:21], v58 offset0:247 offset1:255
	s_waitcnt lgkmcnt(6)
	v_cvt_pk_bf16_f32 v2, v6, v8
	v_or_b32_e32 v6, v54, v56
	v_mul_u32_u24_e32 v128, 0x2c00, v6
	v_or_b32_e32 v6, v54, v57
	s_waitcnt lgkmcnt(4)
	v_cvt_pk_bf16_f32 v3, v10, v12
	s_waitcnt lgkmcnt(2)
	v_cvt_pk_bf16_f32 v4, v14, v16
	s_waitcnt lgkmcnt(0)
	v_cvt_pk_bf16_f32 v5, v18, v20
	v_lshl_add_u64 v[22:23], v[0:1], 0, v[128:129]
	v_mul_u32_u24_e32 v128, 0x2c00, v6
	global_store_dwordx4 v[22:23], v[2:5], off
	v_lshl_add_u64 v[0:1], v[0:1], 0, v[128:129]
	s_nop 0
	v_cvt_pk_bf16_f32 v2, v7, v9
	v_cvt_pk_bf16_f32 v3, v11, v13
	v_cvt_pk_bf16_f32 v4, v15, v17
	v_cvt_pk_bf16_f32 v5, v19, v21
	global_store_dwordx4 v[0:1], v[2:5], off
	s_waitcnt lgkmcnt(0)
; #define LAS __attribute__((address_space(3)))
; template <int KIND>
; DI void transpose_item(const float* W, int K, int N, bf16_t* WT, int ldk, const float* g0, const float* g1, const float* g2, LAS float* scr, int item, int lane) {
;     const int nblk = N / 32, kb = item / nblk, nb = item % nblk, k0 = 64 * kb, n0 = 32 * nb;
;     f32x4 tv[8];
; #pragma unroll
;     for (int i = 0; i < 8; ++i) tv[i] = *(const f32x4*)(W + (size_t)(k0 + 8 * i + (lane >> 3)) * N + n0 + 4 * (lane & 7));
; #pragma unroll
;     for (int i = 0; i < 8; ++i) {
;         const int kk = 8 * i + (lane >> 3), k = k0 + kk;
;         float gn = 1.f;
;         if (KIND == 0 || KIND == 1 || KIND == 2 || KIND == 5 || KIND == 6) gn = g0[k];
;         if (KIND == 4) gn = k < 1024 ? g0[k] : (k < 1536 ? g1[k - 1024] : g2[k - 1536]);
;         LAS float* d = scr + kk * 33 + 4 * (lane & 7);
;         d[0] = tv[i][0] * gn; d[1] = tv[i][1] * gn; d[2] = tv[i][2] * gn; d[3] = tv[i][3] * gn;
;     }
;     asm volatile("s_waitcnt lgkmcnt(0)" ::: "memory");
;     int kd0 = k0;
;     if (KIND == 4) kd0 = k0 < 1024 ? k0 + 512 : (k0 < 1536 ? k0 - 1024 : k0);
.LBB0_632:
	s_andn2_saveexec_b64 s[16:17], s[16:17]
	s_cbranch_execz .LBB0_634
	s_load_dwordx2 s[18:19], s[8:9], 0xa8
	s_load_dwordx2 s[22:23], s[8:9], 0xb8
	v_add_u16_e32 v0, 0xd340, v62
	v_mul_u32_u24_e32 v1, 0xba2f, v0
	v_lshrrev_b32_e32 v1, 23, v1
	v_mul_lo_u16_e32 v2, 0xb0, v1
	v_sub_u16_e32 v0, v0, v2
	s_waitcnt lgkmcnt(0)
	s_add_u32 s22, s22, s1
	v_lshlrev_b16_e32 v13, 6, v1
	v_lshlrev_b16_e32 v12, 5, v0
	s_addc_u32 s23, s23, s0
	v_or_b32_e32 v30, v32, v13
	v_lshlrev_b32_e32 v128, 2, v12
	s_lshl_b64 s[34:35], s[38:39], 2
	v_lshl_add_u64 v[0:1], s[22:23], 0, v[128:129]
	v_lshlrev_b32_e32 v128, 2, v34
	v_mul_u32_u24_e32 v2, 0x1600, v30
	s_add_u32 s18, s18, s34
	v_lshl_add_u64 v[0:1], v[0:1], 0, v[128:129]
	v_lshlrev_b32_e32 v128, 2, v2
	s_addc_u32 s19, s19, s35
	v_lshl_add_u64 v[0:1], v[0:1], 0, v[128:129]
	v_lshlrev_b32_e32 v31, 2, v30
	global_load_dwordx4 v[14:17], v[0:1], off nt
	global_load_dword v30, v31, s[18:19]
	s_mov_b32 s4, 0x2c000
	v_add_co_u32_e32 v2, vcc, s4, v0
	v_add_u32_e32 v53, v33, v35
	s_nop 0
	v_addc_co_u32_e32 v3, vcc, 0, v1, vcc
	global_load_dwordx4 v[18:21], v[2:3], off nt
	s_mov_b32 s4, 0x58000
	v_add_co_u32_e32 v2, vcc, s4, v0
	s_mov_b32 s4, 0x84000
	s_nop 0
	v_addc_co_u32_e32 v3, vcc, 0, v1, vcc
	global_load_dwordx4 v[22:25], v[2:3], off nt
	v_add_co_u32_e32 v2, vcc, s4, v0
	s_mov_b32 s4, 0xb0000
	s_nop 0
	v_addc_co_u32_e32 v3, vcc, 0, v1, vcc
	global_load_dwordx4 v[26:29], v[2:3], off nt
	v_add_co_u32_e32 v2, vcc, s4, v0
	s_mov_b32 s4, 0xdc000
	s_nop 0
	v_addc_co_u32_e32 v3, vcc, 0, v1, vcc
	global_load_dwordx4 v[64:67], v[2:3], off nt
	v_add_co_u32_e32 v2, vcc, s4, v0
	s_mov_b32 s4, 0x108000
	s_nop 0
	v_addc_co_u32_e32 v3, vcc, 0, v1, vcc
	global_load_dwordx4 v[8:11], v[2:3], off nt
	v_add_co_u32_e32 v2, vcc, s4, v0
	s_mov_b32 s4, 0x134000
	s_nop 0
	v_addc_co_u32_e32 v3, vcc, 0, v1, vcc
	global_load_dwordx4 v[4:7], v[2:3], off nt
	v_add_co_u32_e32 v0, vcc, s4, v0
	s_movk_i32 s4, 0x1000
	s_nop 0
	v_addc_co_u32_e32 v1, vcc, 0, v1, vcc
	global_load_dwordx4 v[0:3], v[0:1], off nt
	s_waitcnt vmcnt(7)
	v_pk_mul_f32 v[14:15], v[14:15], v[30:31] op_sel_hi:[1,0]
	ds_write2_b32 v53, v14, v15 offset1:1
	v_pk_mul_f32 v[14:15], v[16:17], v[30:31] op_sel_hi:[1,0]
	ds_write2_b32 v53, v14, v15 offset0:2 offset1:3
	global_load_dword v14, v31, s[18:19] offset:32
	s_waitcnt vmcnt(0)
	v_pk_mul_f32 v[16:17], v[18:19], v[14:15] op_sel_hi:[1,0]
	v_add_u32_e32 v15, 0x420, v53
	ds_write2_b32 v15, v16, v17 offset1:1
	v_pk_mul_f32 v[14:15], v[20:21], v[14:15] op_sel_hi:[1,0]
	v_add_u32_e32 v16, 0x428, v53
	ds_write2_b32 v16, v14, v15 offset1:1
	global_load_dword v14, v31, s[18:19] offset:64
	v_add_u32_e32 v18, v33, v59
	s_waitcnt vmcnt(0)
	v_pk_mul_f32 v[16:17], v[22:23], v[14:15] op_sel_hi:[1,0]
	v_add_u32_e32 v15, 0x840, v53
	ds_write2_b32 v15, v16, v17 offset1:1
	v_pk_mul_f32 v[14:15], v[24:25], v[14:15] op_sel_hi:[1,0]
	v_add_u32_e32 v16, 0x848, v53
	ds_write2_b32 v16, v14, v15 offset1:1
	global_load_dword v14, v31, s[18:19] offset:96
	s_waitcnt vmcnt(0)
	v_pk_mul_f32 v[16:17], v[26:27], v[14:15] op_sel_hi:[1,0]
	v_add_u32_e32 v15, 0xc60, v53
	ds_write2_b32 v15, v16, v17 offset1:1
	v_pk_mul_f32 v[14:15], v[28:29], v[14:15] op_sel_hi:[1,0]
	v_add_u32_e32 v16, 0xc68, v53
	ds_write2_b32 v16, v14, v15 offset1:1
	global_load_dword v14, v31, s[18:19] offset:128
	v_mov_b32_e32 v53, v129
	s_waitcnt vmcnt(0)
	v_pk_mul_f32 v[16:17], v[64:65], v[14:15] op_sel_hi:[1,0]
	v_pk_mul_f32 v[14:15], v[66:67], v[14:15] op_sel_hi:[1,0]
	ds_write2_b32 v18, v14, v15 offset0:2 offset1:3
	global_load_dword v14, v31, s[18:19] offset:160
	ds_write2_b32 v18, v16, v17 offset1:1
	s_waitcnt vmcnt(0)
; #define LAS __attribute__((address_space(3)))
; DI unsigned cvtpk(float lo, float hi) { f32x2 v = {lo, hi}; bf16x2_t b = __builtin_convertvector(v, bf16x2_t); return __builtin_bit_cast(unsigned, b); }
; template <int KIND>
; DI void transpose_item(const float* W, int K, int N, bf16_t* WT, int ldk, const float* g0, const float* g1, const float* g2, LAS float* scr, int item, int lane) {
;     ...
;         if (KIND == 0 || KIND == 1 || KIND == 2 || KIND == 5 || KIND == 6) gn = g0[k];
;         if (KIND == 4) gn = k < 1024 ? g0[k] : (k < 1536 ? g1[k - 1024] : g2[k - 1536]);
;         LAS float* d = scr + kk * 33 + 4 * (lane & 7);
;         d[0] = tv[i][0] * gn; d[1] = tv[i][1] * gn; d[2] = tv[i][2] * gn; d[3] = tv[i][3] * gn;
;     }
;     asm volatile("s_waitcnt lgkmcnt(0)" ::: "memory");
;     int kd0 = k0;
;     if (KIND == 4) kd0 = k0 < 1024 ? k0 + 512 : (k0 < 1536 ? k0 - 1024 : k0);
;     const int c = lane & 7;
; #pragma unroll
;     for (int j = 0; j < 4; ++j) { const int n = (lane >> 3) + 8 * j; const LAS float* s = scr + (8 * c) * 33 + n;
;         u32x4 o; o.x = cvtpk(s[0 * 33], s[1 * 33]); o.y = cvtpk(s[2 * 33], s[3 * 33]); o.z = cvtpk(s[4 * 33], s[5 * 33]); o.w = cvtpk(s[6 * 33], s[7 * 33]);
;         *(u32x4*)(WT + (size_t)map_n<KIND>(n0 + n) * ldk + kd0 + 8 * c) = o; }
	v_pk_mul_f32 v[8:9], v[8:9], v[14:15] op_sel_hi:[1,0]
	v_add_u32_e32 v15, 0x420, v18
	ds_write2_b32 v15, v8, v9 offset1:1
	v_pk_mul_f32 v[8:9], v[10:11], v[14:15] op_sel_hi:[1,0]
	v_add_u32_e32 v10, 0x428, v18
	ds_write2_b32 v10, v8, v9 offset1:1
	global_load_dword v8, v31, s[18:19] offset:192
	s_waitcnt vmcnt(0)
	v_pk_mul_f32 v[4:5], v[4:5], v[8:9] op_sel_hi:[1,0]
	v_add_u32_e32 v9, 0x840, v18
	ds_write2_b32 v9, v4, v5 offset1:1
	v_pk_mul_f32 v[4:5], v[6:7], v[8:9] op_sel_hi:[1,0]
	v_add_u32_e32 v6, 0x848, v18
	ds_write2_b32 v6, v4, v5 offset1:1
	global_load_dword v4, v31, s[18:19] offset:224
	s_waitcnt vmcnt(0)
	v_pk_mul_f32 v[0:1], v[0:1], v[4:5] op_sel_hi:[1,0]
	v_add_u32_e32 v5, 0xc60, v18
	ds_write2_b32 v5, v0, v1 offset1:1
	v_pk_mul_f32 v[0:1], v[2:3], v[4:5] op_sel_hi:[1,0]
	v_add_u32_e32 v2, 0xc68, v18
	ds_write2_b32 v2, v0, v1 offset1:1
	s_waitcnt lgkmcnt(0)
	ds_read2_b32 v[4:5], v58 offset0:33 offset1:41
	ds_read2_b32 v[6:7], v58 offset1:8
	ds_read2_b32 v[8:9], v58 offset0:66 offset1:74
	ds_read2_b32 v[10:11], v58 offset0:99 offset1:107
	ds_read2_b32 v[14:15], v58 offset0:132 offset1:140
	ds_read2_b32 v[16:17], v58 offset0:165 offset1:173
	ds_read2_b32 v[18:19], v58 offset0:198 offset1:206
	ds_read2_b32 v[20:21], v58 offset0:231 offset1:239
	s_waitcnt lgkmcnt(6)
	v_cvt_pk_bf16_f32 v0, v6, v4
	v_or_b32_e32 v4, v32, v12
	v_lshlrev_b32_e32 v128, 13, v4
	v_lshl_add_u64 v[22:23], s[12:13], 0, v[128:129]
	v_lshlrev_b32_e32 v128, 1, v13
	v_lshl_add_u64 v[22:23], v[22:23], 0, v[128:129]
	v_lshl_add_u64 v[22:23], v[22:23], 0, v[52:53]
	v_add_co_u32_e32 v22, vcc, s4, v22
	s_waitcnt lgkmcnt(4)
	v_cvt_pk_bf16_f32 v1, v8, v10
	s_waitcnt lgkmcnt(2)
	v_cvt_pk_bf16_f32 v2, v14, v16
	s_waitcnt lgkmcnt(0)
	v_cvt_pk_bf16_f32 v3, v18, v20
	v_addc_co_u32_e32 v23, vcc, 0, v23, vcc
	v_or_b32_e32 v4, v51, v12
	global_store_dwordx4 v[22:23], v[0:3], off
	v_lshlrev_b32_e32 v4, 13, v4
	v_mov_b32_e32 v23, v129
	v_cvt_pk_bf16_f32 v0, v7, v5
	v_mov_b32_e32 v5, v129
	v_lshl_add_u64 v[4:5], s[12:13], 0, v[4:5]
	v_lshl_add_u64 v[4:5], v[4:5], 0, v[128:129]
	v_lshl_add_u64 v[4:5], v[4:5], 0, v[52:53]
	v_add_co_u32_e32 v4, vcc, s4, v4
	v_cvt_pk_bf16_f32 v1, v9, v11
	v_cvt_pk_bf16_f32 v2, v15, v17
	v_cvt_pk_bf16_f32 v3, v19, v21
	v_addc_co_u32_e32 v5, vcc, 0, v5, vcc
	global_store_dwordx4 v[4:5], v[0:3], off
	ds_read2_b32 v[4:5], v58 offset0:49 offset1:57
	ds_read2_b32 v[6:7], v58 offset0:16 offset1:24
	ds_read2_b32 v[8:9], v58 offset0:82 offset1:90
	ds_read2_b32 v[10:11], v58 offset0:115 offset1:123
	ds_read2_b32 v[14:15], v58 offset0:148 offset1:156
	ds_read2_b32 v[16:17], v58 offset0:181 offset1:189
	ds_read2_b32 v[18:19], v58 offset0:214 offset1:222
	ds_read2_b32 v[20:21], v58 offset0:247 offset1:255
	s_waitcnt lgkmcnt(6)
	v_cvt_pk_bf16_f32 v0, v6, v4
	v_or_b32_e32 v4, v56, v12
	v_lshlrev_b32_e32 v22, 13, v4
	v_lshl_add_u64 v[22:23], s[12:13], 0, v[22:23]
	v_lshl_add_u64 v[22:23], v[22:23], 0, v[128:129]
	v_lshl_add_u64 v[22:23], v[22:23], 0, v[52:53]
	v_add_co_u32_e32 v22, vcc, s4, v22
	s_waitcnt lgkmcnt(4)
	v_cvt_pk_bf16_f32 v1, v8, v10
	s_waitcnt lgkmcnt(2)
	v_cvt_pk_bf16_f32 v2, v14, v16
	s_waitcnt lgkmcnt(0)
	v_cvt_pk_bf16_f32 v3, v18, v20
	v_addc_co_u32_e32 v23, vcc, 0, v23, vcc
	v_or_b32_e32 v4, v57, v12
	global_store_dwordx4 v[22:23], v[0:3], off
	v_lshlrev_b32_e32 v4, 13, v4
	s_nop 0
	v_cvt_pk_bf16_f32 v0, v7, v5
	v_mov_b32_e32 v5, v129
	v_lshl_add_u64 v[4:5], s[12:13], 0, v[4:5]
	v_lshl_add_u64 v[4:5], v[4:5], 0, v[128:129]
	v_lshl_add_u64 v[4:5], v[4:5], 0, v[52:53]
	v_add_co_u32_e32 v4, vcc, 0x1000, v4
	v_cvt_pk_bf16_f32 v1, v9, v11
	v_cvt_pk_bf16_f32 v2, v15, v17
	v_cvt_pk_bf16_f32 v3, v19, v21
	v_addc_co_u32_e32 v5, vcc, 0, v5, vcc
	global_store_dwordx4 v[4:5], v[0:3], off
	s_waitcnt lgkmcnt(0)

; #define LAS __attribute__((address_space(3)))
; DI unsigned cvtpk(float lo, float hi) { f32x2 v = {lo, hi}; bf16x2_t b = __builtin_convertvector(v, bf16x2_t); return __builtin_bit_cast(unsigned, b); }
; template <int KIND>
; DI void transpose_item(const float* W, int K, int N, bf16_t* WT, int ldk, const float* g0, const float* g1, const float* g2, LAS float* scr, int item, int lane) {
;     const int nblk = N / 32, kb = item / nblk, nb = item % nblk, k0 = 64 * kb, n0 = 32 * nb;
;     f32x4 tv[8];
; #pragma unroll
;     for (int i = 0; i < 8; ++i) tv[i] = *(const f32x4*)(W + (size_t)(k0 + 8 * i + (lane >> 3)) * N + n0 + 4 * (lane & 7));
; #pragma unroll
;     for (int i = 0; i < 8; ++i) {
;         const int kk = 8 * i + (lane >> 3), k = k0 + kk;
;         float gn = 1.f;
;         if (KIND == 0 || KIND == 1 || KIND == 2 || KIND == 5 || KIND == 6) gn = g0[k];
;         if (KIND == 4) gn = k < 1024 ? g0[k] : (k < 1536 ? g1[k - 1024] : g2[k - 1536]);
;         LAS float* d = scr + kk * 33 + 4 * (lane & 7);
;         d[0] = tv[i][0] * gn; d[1] = tv[i][1] * gn; d[2] = tv[i][2] * gn; d[3] = tv[i][3] * gn;
;     }
;     asm volatile("s_waitcnt lgkmcnt(0)" ::: "memory");
;     int kd0 = k0;
;     if (KIND == 4) kd0 = k0 < 1024 ? k0 + 512 : (k0 < 1536 ? k0 - 1024 : k0);
;     const int c = lane & 7;
; #pragma unroll
;     for (int j = 0; j < 4; ++j) { const int n = (lane >> 3) + 8 * j; const LAS float* s = scr + (8 * c) * 33 + n;
;         u32x4 o; o.x = cvtpk(s[0 * 33], s[1 * 33]); o.y = cvtpk(s[2 * 33], s[3 * 33]); o.z = cvtpk(s[4 * 33], s[5 * 33]); o.w = cvtpk(s[6 * 33], s[7 * 33]);
;         *(u32x4*)(WT + (size_t)map_n<KIND>(n0 + n) * ldk + kd0 + 8 * c) = o; }
;     asm volatile("s_waitcnt lgkmcnt(0)" ::: "memory");
; }
.LBB0_635:
	s_andn2_saveexec_b64 s[14:15], s[14:15]
	s_cbranch_execz .LBB0_637
	s_load_dwordx4 s[16:19], s[8:9], 0xa8
	v_add_u16_e32 v0, 0xe940, v62
	v_mul_u32_u24_e32 v1, 0xba2f, v0
	v_lshrrev_b32_e32 v1, 23, v1
	v_mul_lo_u16_e32 v2, 0xb0, v1
	v_sub_u16_e32 v0, v0, v2
	s_waitcnt lgkmcnt(0)
	s_add_u32 s18, s18, s1
	v_lshlrev_b16_e32 v13, 6, v1
	v_lshlrev_b16_e32 v12, 5, v0
	s_addc_u32 s19, s19, s0
	v_or_b32_e32 v30, v32, v13
	v_lshlrev_b32_e32 v128, 2, v12
	s_lshl_b64 s[22:23], s[38:39], 2
	v_lshl_add_u64 v[0:1], s[18:19], 0, v[128:129]
	v_lshlrev_b32_e32 v128, 2, v34
	v_mul_u32_u24_e32 v2, 0x1600, v30
	s_add_u32 s16, s16, s22
	v_lshl_add_u64 v[0:1], v[0:1], 0, v[128:129]
	v_lshlrev_b32_e32 v128, 2, v2
	s_addc_u32 s17, s17, s23
	v_lshl_add_u64 v[0:1], v[0:1], 0, v[128:129]
	v_lshlrev_b32_e32 v31, 2, v30
	global_load_dwordx4 v[14:17], v[0:1], off nt
	global_load_dword v30, v31, s[16:17]
	s_mov_b32 s4, 0x2c000
	v_add_co_u32_e32 v2, vcc, s4, v0
	v_add_u32_e32 v53, v33, v35
	s_nop 0
	v_addc_co_u32_e32 v3, vcc, 0, v1, vcc
	global_load_dwordx4 v[18:21], v[2:3], off nt
	s_mov_b32 s4, 0x58000
	v_add_co_u32_e32 v2, vcc, s4, v0
	s_mov_b32 s4, 0x84000
	s_nop 0
	v_addc_co_u32_e32 v3, vcc, 0, v1, vcc
	global_load_dwordx4 v[22:25], v[2:3], off nt
	v_add_co_u32_e32 v2, vcc, s4, v0
	s_mov_b32 s4, 0xb0000
	s_nop 0
	v_addc_co_u32_e32 v3, vcc, 0, v1, vcc
	global_load_dwordx4 v[26:29], v[2:3], off nt
	v_add_co_u32_e32 v2, vcc, s4, v0
	s_mov_b32 s4, 0xdc000
	s_nop 0
	v_addc_co_u32_e32 v3, vcc, 0, v1, vcc
	global_load_dwordx4 v[64:67], v[2:3], off nt
	v_add_co_u32_e32 v2, vcc, s4, v0
	s_mov_b32 s4, 0x108000
	s_nop 0
	v_addc_co_u32_e32 v3, vcc, 0, v1, vcc
	global_load_dwordx4 v[8:11], v[2:3], off nt
	v_add_co_u32_e32 v2, vcc, s4, v0
	s_mov_b32 s4, 0x134000
	s_nop 0
	v_addc_co_u32_e32 v3, vcc, 0, v1, vcc
	global_load_dwordx4 v[4:7], v[2:3], off nt
	v_add_co_u32_e32 v0, vcc, s4, v0
	v_lshlrev_b32_e32 v128, 1, v13
	s_nop 0
	v_addc_co_u32_e32 v1, vcc, 0, v1, vcc
	global_load_dwordx4 v[0:3], v[0:1], off nt
	s_waitcnt vmcnt(7)
	v_pk_mul_f32 v[14:15], v[14:15], v[30:31] op_sel_hi:[1,0]
	ds_write2_b32 v53, v14, v15 offset1:1
	v_pk_mul_f32 v[14:15], v[16:17], v[30:31] op_sel_hi:[1,0]
	ds_write2_b32 v53, v14, v15 offset0:2 offset1:3
	global_load_dword v14, v31, s[16:17] offset:32
	s_waitcnt vmcnt(0)
	v_pk_mul_f32 v[16:17], v[18:19], v[14:15] op_sel_hi:[1,0]
	v_add_u32_e32 v15, 0x420, v53
	ds_write2_b32 v15, v16, v17 offset1:1
	v_pk_mul_f32 v[14:15], v[20:21], v[14:15] op_sel_hi:[1,0]
	v_add_u32_e32 v16, 0x428, v53
	ds_write2_b32 v16, v14, v15 offset1:1
	global_load_dword v14, v31, s[16:17] offset:64
	v_add_u32_e32 v18, v33, v59
	s_waitcnt vmcnt(0)
	v_pk_mul_f32 v[16:17], v[22:23], v[14:15] op_sel_hi:[1,0]
	v_add_u32_e32 v15, 0x840, v53
	ds_write2_b32 v15, v16, v17 offset1:1
	v_pk_mul_f32 v[14:15], v[24:25], v[14:15] op_sel_hi:[1,0]
	v_add_u32_e32 v16, 0x848, v53
	ds_write2_b32 v16, v14, v15 offset1:1
	global_load_dword v14, v31, s[16:17] offset:96
	s_waitcnt vmcnt(0)
	v_pk_mul_f32 v[16:17], v[26:27], v[14:15] op_sel_hi:[1,0]
	v_add_u32_e32 v15, 0xc60, v53
	ds_write2_b32 v15, v16, v17 offset1:1
	v_pk_mul_f32 v[14:15], v[28:29], v[14:15] op_sel_hi:[1,0]
	v_add_u32_e32 v16, 0xc68, v53
	ds_write2_b32 v16, v14, v15 offset1:1
	global_load_dword v14, v31, s[16:17] offset:128
	s_waitcnt vmcnt(0)
	v_pk_mul_f32 v[16:17], v[64:65], v[14:15] op_sel_hi:[1,0]
	v_pk_mul_f32 v[14:15], v[66:67], v[14:15] op_sel_hi:[1,0]
	ds_write2_b32 v18, v14, v15 offset0:2 offset1:3
	global_load_dword v14, v31, s[16:17] offset:160
	ds_write2_b32 v18, v16, v17 offset1:1
	s_waitcnt vmcnt(0)
	v_pk_mul_f32 v[8:9], v[8:9], v[14:15] op_sel_hi:[1,0]
	v_add_u32_e32 v15, 0x420, v18
	ds_write2_b32 v15, v8, v9 offset1:1
	v_pk_mul_f32 v[8:9], v[10:11], v[14:15] op_sel_hi:[1,0]
	v_add_u32_e32 v10, 0x428, v18
	ds_write2_b32 v10, v8, v9 offset1:1
	global_load_dword v8, v31, s[16:17] offset:192
	s_waitcnt vmcnt(0)
	v_pk_mul_f32 v[4:5], v[4:5], v[8:9] op_sel_hi:[1,0]
	v_add_u32_e32 v9, 0x840, v18
	ds_write2_b32 v9, v4, v5 offset1:1
	v_pk_mul_f32 v[4:5], v[6:7], v[8:9] op_sel_hi:[1,0]
	v_add_u32_e32 v6, 0x848, v18
	ds_write2_b32 v6, v4, v5 offset1:1
	global_load_dword v4, v31, s[16:17] offset:224
	s_waitcnt vmcnt(0)
	v_pk_mul_f32 v[0:1], v[0:1], v[4:5] op_sel_hi:[1,0]
	v_add_u32_e32 v5, 0xc60, v18
	ds_write2_b32 v5, v0, v1 offset1:1
	v_pk_mul_f32 v[0:1], v[2:3], v[4:5] op_sel_hi:[1,0]
	v_add_u32_e32 v2, 0xc68, v18
	ds_write2_b32 v2, v0, v1 offset1:1
	s_waitcnt lgkmcnt(0)
	ds_read2_b32 v[6:7], v58 offset0:33 offset1:41
	ds_read2_b32 v[8:9], v58 offset1:8
	ds_read2_b32 v[10:11], v58 offset0:66 offset1:74
	ds_read2_b32 v[14:15], v58 offset0:99 offset1:107
	ds_read2_b32 v[16:17], v58 offset0:132 offset1:140
	ds_read2_b32 v[18:19], v58 offset0:165 offset1:173
	ds_read2_b32 v[20:21], v58 offset0:198 offset1:206
	ds_read2_b32 v[22:23], v58 offset0:231 offset1:239
	v_lshl_add_u64 v[4:5], v[38:39], 0, v[128:129]
	s_waitcnt lgkmcnt(6)
	v_cvt_pk_bf16_f32 v0, v8, v6
	v_or_b32_e32 v6, v32, v12
	v_lshlrev_b32_e32 v128, 13, v6
	v_or_b32_e32 v6, v51, v12
	s_waitcnt lgkmcnt(4)
	v_cvt_pk_bf16_f32 v1, v10, v14
	s_waitcnt lgkmcnt(2)
	v_cvt_pk_bf16_f32 v2, v16, v18
	s_waitcnt lgkmcnt(0)
	v_cvt_pk_bf16_f32 v3, v20, v22
	v_lshl_add_u64 v[24:25], v[4:5], 0, v[128:129]
	v_lshlrev_b32_e32 v128, 13, v6
	global_store_dwordx4 v[24:25], v[0:3], off
	s_nop 1
	v_cvt_pk_bf16_f32 v0, v9, v7
	v_cvt_pk_bf16_f32 v1, v11, v15
	v_cvt_pk_bf16_f32 v2, v17, v19
	v_cvt_pk_bf16_f32 v3, v21, v23
	v_lshl_add_u64 v[6:7], v[4:5], 0, v[128:129]
	global_store_dwordx4 v[6:7], v[0:3], off
	ds_read2_b32 v[6:7], v58 offset0:49 offset1:57
	ds_read2_b32 v[8:9], v58 offset0:16 offset1:24
	ds_read2_b32 v[10:11], v58 offset0:82 offset1:90
	ds_read2_b32 v[14:15], v58 offset0:115 offset1:123
	ds_read2_b32 v[16:17], v58 offset0:148 offset1:156
	ds_read2_b32 v[18:19], v58 offset0:181 offset1:189
	ds_read2_b32 v[20:21], v58 offset0:214 offset1:222
	ds_read2_b32 v[22:23], v58 offset0:247 offset1:255
	s_waitcnt lgkmcnt(6)
	v_cvt_pk_bf16_f32 v0, v8, v6
	v_or_b32_e32 v6, v56, v12
	v_lshlrev_b32_e32 v128, 13, v6
	v_or_b32_e32 v6, v57, v12
	s_waitcnt lgkmcnt(4)
	v_cvt_pk_bf16_f32 v1, v10, v14
	s_waitcnt lgkmcnt(2)
	v_cvt_pk_bf16_f32 v2, v16, v18
	s_waitcnt lgkmcnt(0)
	v_cvt_pk_bf16_f32 v3, v20, v22
	v_lshl_add_u64 v[24:25], v[4:5], 0, v[128:129]
	v_lshlrev_b32_e32 v128, 13, v6
	global_store_dwordx4 v[24:25], v[0:3], off
	v_lshl_add_u64 v[4:5], v[4:5], 0, v[128:129]
	s_nop 0
	v_cvt_pk_bf16_f32 v0, v9, v7
	v_cvt_pk_bf16_f32 v1, v11, v15
	v_cvt_pk_bf16_f32 v2, v17, v19
	v_cvt_pk_bf16_f32 v3, v21, v23
	global_store_dwordx4 v[4:5], v[0:3], off
	s_waitcnt lgkmcnt(0)

; #define LAS __attribute__((address_space(3)))
; template <int KIND>
; DI void transpose_item(const float* W, int K, int N, bf16_t* WT, int ldk, const float* g0, const float* g1, const float* g2, LAS float* scr, int item, int lane) {
;     const int nblk = N / 32, kb = item / nblk, nb = item % nblk, k0 = 64 * kb, n0 = 32 * nb;
;     f32x4 tv[8];
; #pragma unroll
;     for (int i = 0; i < 8; ++i) tv[i] = *(const f32x4*)(W + (size_t)(k0 + 8 * i + (lane >> 3)) * N + n0 + 4 * (lane & 7));
; #pragma unroll
;     for (int i = 0; i < 8; ++i) {
;         const int kk = 8 * i + (lane >> 3), k = k0 + kk;
;         float gn = 1.f;
;         if (KIND == 0 || KIND == 1 || KIND == 2 || KIND == 5 || KIND == 6) gn = g0[k];
;         if (KIND == 4) gn = k < 1024 ? g0[k] : (k < 1536 ? g1[k - 1024] : g2[k - 1536]);
;         LAS float* d = scr + kk * 33 + 4 * (lane & 7);
;         d[0] = tv[i][0] * gn; d[1] = tv[i][1] * gn; d[2] = tv[i][2] * gn; d[3] = tv[i][3] * gn;
;     }
;     asm volatile("s_waitcnt lgkmcnt(0)" ::: "memory");
;     int kd0 = k0;
;     if (KIND == 4) kd0 = k0 < 1024 ? k0 + 512 : (k0 < 1536 ? k0 - 1024 : k0);
.LBB0_638:
	s_andn2_saveexec_b64 s[14:15], s[6:7]
	s_cbranch_execz .LBB0_704
	s_load_dwordx8 s[44:51], s[8:9], 0x88
	v_add_u32_e32 v0, 0xfffe2800, v50
	v_add_u32_e32 v63, 0xfffff140, v62
	v_and_b32_e32 v53, 0x7c0, v0
	v_and_b32_e32 v64, 0x7c0, v63
	s_waitcnt lgkmcnt(0)
	s_add_u32 s6, s50, s42
	s_addc_u32 s7, s51, s43
	v_lshlrev_b32_e32 v128, 2, v53
	v_or_b32_e32 v65, v64, v32
	v_lshl_add_u64 v[0:1], s[6:7], 0, v[128:129]
	v_lshlrev_b32_e32 v128, 2, v34
	v_lshl_add_u64 v[0:1], v[0:1], 0, v[128:129]
	v_lshlrev_b32_e32 v128, 13, v65
	v_lshl_add_u64 v[0:1], v[0:1], 0, v[128:129]
	s_mov_b32 s4, 0x10000
	v_add_co_u32_e32 v2, vcc, s4, v0
	s_mov_b32 s4, 0x20000
	s_nop 0
	v_addc_co_u32_e32 v3, vcc, 0, v1, vcc
	global_load_dwordx4 v[28:31], v[0:1], off nt
	global_load_dwordx4 v[24:27], v[2:3], off nt
	v_add_co_u32_e32 v2, vcc, s4, v0
	s_mov_b32 s4, 0x30000
	s_nop 0
	v_addc_co_u32_e32 v3, vcc, 0, v1, vcc
	v_add_co_u32_e32 v4, vcc, s4, v0
	s_add_u32 s16, s44, s58
	s_nop 0
	v_addc_co_u32_e32 v5, vcc, 0, v1, vcc
	global_load_dwordx4 v[20:23], v[2:3], off nt
	global_load_dwordx4 v[16:19], v[4:5], off nt
	v_add_co_u32_e32 v2, vcc, s89, v0
	s_addc_u32 s17, s45, s59
	s_nop 0
	v_addc_co_u32_e32 v3, vcc, 0, v1, vcc
	v_add_co_u32_e32 v4, vcc, 0x50000, v0
	s_lshl_b64 s[6:7], s[52:53], 2
	s_nop 0
	v_addc_co_u32_e32 v5, vcc, 0, v1, vcc
	global_load_dwordx4 v[12:15], v[2:3], off nt
	global_load_dwordx4 v[8:11], v[4:5], off nt
	v_add_co_u32_e32 v2, vcc, 0x60000, v0
	s_add_u32 s18, s46, s6
	s_nop 0
	v_addc_co_u32_e32 v3, vcc, 0, v1, vcc
	v_add_co_u32_e32 v0, vcc, 0x70000, v0
	s_addc_u32 s19, s47, s7
	s_nop 0
	v_addc_co_u32_e32 v1, vcc, 0, v1, vcc
	global_load_dwordx4 v[4:7], v[2:3], off nt
	s_nop 0
	global_load_dwordx4 v[0:3], v[0:1], off nt
	s_movk_i32 s4, 0x400
	s_add_u32 s22, s48, s6
	v_cmp_gt_u32_e32 vcc, s4, v63
	s_movk_i32 s4, 0x3ff
	s_addc_u32 s23, s49, s7
	v_cmp_lt_u32_e64 s[46:47], s4, v63
	s_and_saveexec_b64 s[6:7], s[46:47]
	s_xor_b64 s[34:35], exec, s[6:7]
	s_cbranch_execz .LBB0_645
	s_movk_i32 s4, 0x5ff
	v_cmp_lt_u32_e64 s[6:7], s4, v63
	s_and_saveexec_b64 s[40:41], s[6:7]
	s_xor_b64 s[6:7], exec, s[40:41]
	v_lshlrev_b32_e32 v128, 2, v65
	s_movk_i32 s40, 0xe800
	v_lshl_add_u64 v[54:55], s[22:23], 0, v[128:129]
	s_mov_b32 s41, -1
	v_lshl_add_u64 v[54:55], v[54:55], 0, s[40:41]
	s_andn2_saveexec_b64 s[6:7], s[6:7]
	v_lshlrev_b32_e32 v128, 2, v65
	s_movk_i32 s40, 0xf000
	v_lshl_add_u64 v[54:55], s[18:19], 0, v[128:129]
	s_mov_b32 s41, -1
	v_lshl_add_u64 v[54:55], v[54:55], 0, s[40:41]
	s_or_b64 exec, exec, s[6:7]

; #define LAS __attribute__((address_space(3)))
; DI unsigned cvtpk(float lo, float hi) { f32x2 v = {lo, hi}; bf16x2_t b = __builtin_convertvector(v, bf16x2_t); return __builtin_bit_cast(unsigned, b); }
; template <int KIND>
; DI void transpose_item(const float* W, int K, int N, bf16_t* WT, int ldk, const float* g0, const float* g1, const float* g2, LAS float* scr, int item, int lane) {
;     const int nblk = N / 32, kb = item / nblk, nb = item % nblk, k0 = 64 * kb, n0 = 32 * nb;
;     f32x4 tv[8];
; #pragma unroll
;     for (int i = 0; i < 8; ++i) tv[i] = *(const f32x4*)(W + (size_t)(k0 + 8 * i + (lane >> 3)) * N + n0 + 4 * (lane & 7));
; #pragma unroll
;     for (int i = 0; i < 8; ++i) {
;         const int kk = 8 * i + (lane >> 3), k = k0 + kk;
;         float gn = 1.f;
;         if (KIND == 0 || KIND == 1 || KIND == 2 || KIND == 5 || KIND == 6) gn = g0[k];
;         if (KIND == 4) gn = k < 1024 ? g0[k] : (k < 1536 ? g1[k - 1024] : g2[k - 1536]);
;         LAS float* d = scr + kk * 33 + 4 * (lane & 7);
;         d[0] = tv[i][0] * gn; d[1] = tv[i][1] * gn; d[2] = tv[i][2] * gn; d[3] = tv[i][3] * gn;
;     }
;     asm volatile("s_waitcnt lgkmcnt(0)" ::: "memory");
;     int kd0 = k0;
;     if (KIND == 4) kd0 = k0 < 1024 ? k0 + 512 : (k0 < 1536 ? k0 - 1024 : k0);
;     const int c = lane & 7;
; #pragma unroll
;     for (int j = 0; j < 4; ++j) { const int n = (lane >> 3) + 8 * j; const LAS float* s = scr + (8 * c) * 33 + n;
;         u32x4 o; o.x = cvtpk(s[0 * 33], s[1 * 33]); o.y = cvtpk(s[2 * 33], s[3 * 33]); o.z = cvtpk(s[4 * 33], s[5 * 33]); o.w = cvtpk(s[6 * 33], s[7 * 33]);
;         *(u32x4*)(WT + (size_t)map_n<KIND>(n0 + n) * ldk + kd0 + 8 * c) = o; }
;     asm volatile("s_waitcnt lgkmcnt(0)" ::: "memory");
; }
.LBB0_705:
	s_andn2_saveexec_b64 s[6:7], s[68:69]
	s_cbranch_execz .LBB0_707
	s_load_dwordx2 s[14:15], s[8:9], 0x78
	v_add_u32_e32 v0, 0xfffe4800, v50
	v_and_b32_e32 v54, 0x3c0, v0
	v_and_b32_e32 v53, 0x1c0, v61
	v_lshlrev_b32_e32 v128, 2, v54
	s_waitcnt lgkmcnt(0)
	s_add_u32 s14, s14, s54
	s_addc_u32 s15, s15, s55
	v_or_b32_e32 v2, v53, v32
	v_lshl_add_u64 v[0:1], s[14:15], 0, v[128:129]
	v_lshlrev_b32_e32 v128, 2, v34
	v_lshl_add_u64 v[0:1], v[0:1], 0, v[128:129]
	v_lshlrev_b32_e32 v128, 12, v2
	v_lshl_add_u64 v[28:29], v[0:1], 0, v[128:129]
	s_mov_b32 s4, 0x8000
	v_add_co_u32_e32 v4, vcc, s4, v28
	global_load_dwordx4 v[0:3], v[28:29], off nt
	s_nop 0
	v_addc_co_u32_e32 v5, vcc, 0, v29, vcc
	s_mov_b32 s4, 0x10000
	global_load_dwordx4 v[4:7], v[4:5], off nt
	v_add_co_u32_e32 v8, vcc, s4, v28
	s_mov_b32 s4, 0x18000
	s_nop 0
	v_addc_co_u32_e32 v9, vcc, 0, v29, vcc
	global_load_dwordx4 v[8:11], v[8:9], off nt
	v_add_co_u32_e32 v12, vcc, s4, v28
	s_mov_b32 s4, 0x20000
	s_nop 0
	v_addc_co_u32_e32 v13, vcc, 0, v29, vcc
	global_load_dwordx4 v[12:15], v[12:13], off nt
	v_add_co_u32_e32 v16, vcc, s4, v28
	s_mov_b32 s4, 0x28000
	s_nop 0
	v_addc_co_u32_e32 v17, vcc, 0, v29, vcc
	global_load_dwordx4 v[16:19], v[16:17], off nt
	v_add_co_u32_e32 v20, vcc, s4, v28
	s_mov_b32 s4, 0x30000
	s_nop 0
	v_addc_co_u32_e32 v21, vcc, 0, v29, vcc
	global_load_dwordx4 v[20:23], v[20:21], off nt
	v_add_co_u32_e32 v24, vcc, s4, v28
	s_mov_b32 s4, 0x38000
	s_nop 0
	v_addc_co_u32_e32 v25, vcc, 0, v29, vcc
	global_load_dwordx4 v[24:27], v[24:25], off nt
	v_add_co_u32_e32 v28, vcc, s4, v28
	v_add_u32_e32 v55, v33, v35
	s_nop 0
	v_addc_co_u32_e32 v29, vcc, 0, v29, vcc
	global_load_dwordx4 v[28:31], v[28:29], off nt
	s_movk_i32 s4, 0x200
	v_cmp_gt_u32_e32 vcc, s4, v54
	v_lshlrev_b32_e32 v128, 1, v53
	s_waitcnt vmcnt(7)
	ds_write2_b32 v55, v0, v1 offset1:1
	ds_write2_b32 v55, v2, v3 offset0:2 offset1:3
	v_add_u32_e32 v0, 0x420, v55
	s_waitcnt vmcnt(6)
	ds_write2_b32 v0, v4, v5 offset1:1
	v_add_u32_e32 v0, 0x428, v55
	ds_write2_b32 v0, v6, v7 offset1:1
	v_add_u32_e32 v0, 0x840, v55
	s_waitcnt vmcnt(5)
	ds_write2_b32 v0, v8, v9 offset1:1
	v_add_u32_e32 v0, 0x848, v55
	ds_write2_b32 v0, v10, v11 offset1:1
	v_add_u32_e32 v0, 0xc60, v55
	s_waitcnt vmcnt(4)
	ds_write2_b32 v0, v12, v13 offset1:1
	v_add_u32_e32 v0, 0xc68, v55
	ds_write2_b32 v0, v14, v15 offset1:1
	v_add_u32_e32 v0, 0x1080, v55
	s_waitcnt vmcnt(3)
	ds_write2_b32 v0, v16, v17 offset1:1
	v_add_u32_e32 v0, 0x1088, v55
	ds_write2_b32 v0, v18, v19 offset1:1
	v_add_u32_e32 v0, 0x14a0, v55
	s_waitcnt vmcnt(2)
	ds_write2_b32 v0, v20, v21 offset1:1
	v_add_u32_e32 v0, 0x14a8, v55
	ds_write2_b32 v0, v22, v23 offset1:1
	v_add_u32_e32 v0, 0x18c0, v55
	s_waitcnt vmcnt(1)
	ds_write2_b32 v0, v24, v25 offset1:1
	v_add_u32_e32 v0, 0x18c8, v55
	ds_write2_b32 v0, v26, v27 offset1:1
	v_add_u32_e32 v0, 0x1ce0, v55
	s_waitcnt vmcnt(0)
	ds_write2_b32 v0, v28, v29 offset1:1
	v_add_u32_e32 v0, 0x1ce8, v55
	ds_write2_b32 v0, v30, v31 offset1:1
	s_waitcnt lgkmcnt(0)
	ds_read2_b32 v[6:7], v58 offset0:33 offset1:41
	ds_read2_b32 v[8:9], v58 offset1:8
	ds_read2_b32 v[10:11], v58 offset0:66 offset1:74
	ds_read2_b32 v[12:13], v58 offset0:99 offset1:107
	ds_read2_b32 v[14:15], v58 offset0:132 offset1:140
	ds_read2_b32 v[16:17], v58 offset0:165 offset1:173
	ds_read2_b32 v[18:19], v58 offset0:198 offset1:206
	ds_read2_b32 v[20:21], v58 offset0:231 offset1:239
	v_lshl_add_u64 v[0:1], v[42:43], 0, v[128:129]
	s_waitcnt lgkmcnt(6)
	v_cvt_pk_bf16_f32 v2, v8, v6
	v_or_b32_e32 v6, v54, v32
	v_lshlrev_b32_e32 v6, 1, v6
	v_add_u32_e32 v8, 0xfffffc01, v6
	v_cndmask_b32_e32 v22, v8, v6, vcc
	v_ashrrev_i32_e32 v23, 31, v22
	v_lshlrev_b64 v[22:23], 10, v[22:23]
	v_or_b32_e32 v6, v54, v51
	s_waitcnt lgkmcnt(4)
	v_cvt_pk_bf16_f32 v3, v10, v12
	s_waitcnt lgkmcnt(2)
	v_cvt_pk_bf16_f32 v4, v14, v16
	s_waitcnt lgkmcnt(0)
	v_cvt_pk_bf16_f32 v5, v18, v20
	v_lshl_add_u64 v[22:23], v[0:1], 0, v[22:23]
	v_lshlrev_b32_e32 v6, 1, v6
	global_store_dwordx4 v[22:23], v[2:5], off
	s_nop 1
	v_cvt_pk_bf16_f32 v2, v9, v7
	v_add_u32_e32 v7, 0xfffffc01, v6
	v_cndmask_b32_e32 v6, v7, v6, vcc
	v_ashrrev_i32_e32 v7, 31, v6
	v_lshlrev_b64 v[6:7], 10, v[6:7]
	v_cvt_pk_bf16_f32 v3, v11, v13
	v_cvt_pk_bf16_f32 v4, v15, v17
	v_cvt_pk_bf16_f32 v5, v19, v21
	v_lshl_add_u64 v[6:7], v[0:1], 0, v[6:7]
	global_store_dwordx4 v[6:7], v[2:5], off
	ds_read2_b32 v[6:7], v58 offset0:49 offset1:57
	ds_read2_b32 v[8:9], v58 offset0:16 offset1:24
	ds_read2_b32 v[10:11], v58 offset0:82 offset1:90
	ds_read2_b32 v[12:13], v58 offset0:115 offset1:123
	ds_read2_b32 v[14:15], v58 offset0:148 offset1:156
	ds_read2_b32 v[16:17], v58 offset0:181 offset1:189
	ds_read2_b32 v[18:19], v58 offset0:214 offset1:222
	ds_read2_b32 v[20:21], v58 offset0:247 offset1:255
	s_waitcnt lgkmcnt(6)
	v_cvt_pk_bf16_f32 v2, v8, v6
	v_or_b32_e32 v6, v54, v56
	v_lshlrev_b32_e32 v6, 1, v6
	v_add_u32_e32 v8, 0xfffffc01, v6
	v_cndmask_b32_e32 v22, v8, v6, vcc
	v_ashrrev_i32_e32 v23, 31, v22
	v_lshlrev_b64 v[22:23], 10, v[22:23]
	v_or_b32_e32 v6, v54, v57
	s_waitcnt lgkmcnt(4)
	v_cvt_pk_bf16_f32 v3, v10, v12
	s_waitcnt lgkmcnt(2)
	v_cvt_pk_bf16_f32 v4, v14, v16
	s_waitcnt lgkmcnt(0)
	v_cvt_pk_bf16_f32 v5, v18, v20
	v_lshl_add_u64 v[22:23], v[0:1], 0, v[22:23]
	v_lshlrev_b32_e32 v6, 1, v6
	global_store_dwordx4 v[22:23], v[2:5], off
	s_nop 1
	v_cvt_pk_bf16_f32 v2, v9, v7
	v_add_u32_e32 v7, 0xfffffc01, v6
	v_cndmask_b32_e32 v6, v7, v6, vcc
	v_ashrrev_i32_e32 v7, 31, v6
	v_lshlrev_b64 v[6:7], 10, v[6:7]
	v_cvt_pk_bf16_f32 v3, v11, v13
	v_cvt_pk_bf16_f32 v4, v15, v17
	v_cvt_pk_bf16_f32 v5, v19, v21
	v_lshl_add_u64 v[0:1], v[0:1], 0, v[6:7]
	global_store_dwordx4 v[0:1], v[2:5], off
	s_waitcnt lgkmcnt(0)

; #define LAS __attribute__((address_space(3)))
; template <int KIND>
; DI void transpose_item(const float* W, int K, int N, bf16_t* WT, int ldk, const float* g0, const float* g1, const float* g2, LAS float* scr, int item, int lane) {
;     const int nblk = N / 32, kb = item / nblk, nb = item % nblk, k0 = 64 * kb, n0 = 32 * nb;
;     f32x4 tv[8];
; #pragma unroll
;     for (int i = 0; i < 8; ++i) tv[i] = *(const f32x4*)(W + (size_t)(k0 + 8 * i + (lane >> 3)) * N + n0 + 4 * (lane & 7));
; #pragma unroll
;     for (int i = 0; i < 8; ++i) {
;         const int kk = 8 * i + (lane >> 3), k = k0 + kk;
;         float gn = 1.f;
;         if (KIND == 0 || KIND == 1 || KIND == 2 || KIND == 5 || KIND == 6) gn = g0[k];
;         if (KIND == 4) gn = k < 1024 ? g0[k] : (k < 1536 ? g1[k - 1024] : g2[k - 1536]);
;         LAS float* d = scr + kk * 33 + 4 * (lane & 7);
;         d[0] = tv[i][0] * gn; d[1] = tv[i][1] * gn; d[2] = tv[i][2] * gn; d[3] = tv[i][3] * gn;
;     }
;     asm volatile("s_waitcnt lgkmcnt(0)" ::: "memory");
; DI void convert_weights(PP p, LAS unsigned char* lds, int l, int worker, int nworkers) {
;     ...
;         if (r < I_UKV) { transpose_item<2>(p->in[6] + (size_t)l * 256 * 2048, 256, 2048, (bf16_t*)(wl + W_UKV), 256, p->in[5] + l * 256, nullptr, nullptr, scr, r, lane); continue; } r -= I_UKV;
.LBB0_708:
	s_andn2_saveexec_b64 s[6:7], s[66:67]
	s_cbranch_execz .LBB0_710
	s_load_dwordx4 s[16:19], s[8:9], 0x28
	v_add_u32_e32 v0, 0xfffff340, v62
	v_and_b32_e32 v13, 0xc0, v0
	v_add_u32_e32 v0, 0xfffe6800, v50
	v_and_b32_e32 v12, 0x7c0, v0
	s_waitcnt lgkmcnt(0)
	s_add_u32 s18, s18, s54
	s_addc_u32 s19, s19, s55
	v_lshlrev_b32_e32 v128, 2, v12
	v_or_b32_e32 v30, v13, v32
	v_lshl_add_u64 v[0:1], s[18:19], 0, v[128:129]
	v_lshlrev_b32_e32 v128, 2, v34
	s_add_u32 s14, s16, s60
	v_lshl_add_u64 v[0:1], v[0:1], 0, v[128:129]
	v_lshlrev_b32_e32 v128, 13, v30
	s_addc_u32 s15, s17, s61
	v_lshl_add_u64 v[0:1], v[0:1], 0, v[128:129]
	v_lshlrev_b32_e32 v31, 2, v30
	global_load_dwordx4 v[14:17], v[0:1], off nt
	global_load_dword v30, v31, s[14:15]
	s_mov_b32 s4, 0x10000
	v_add_co_u32_e32 v2, vcc, s4, v0
	v_add_u32_e32 v53, v33, v35
	s_nop 0
	v_addc_co_u32_e32 v3, vcc, 0, v1, vcc
	global_load_dwordx4 v[18:21], v[2:3], off nt
	s_mov_b32 s4, 0x20000
	v_add_co_u32_e32 v2, vcc, s4, v0
	s_mov_b32 s4, 0x30000
	s_nop 0
	v_addc_co_u32_e32 v3, vcc, 0, v1, vcc
	global_load_dwordx4 v[22:25], v[2:3], off nt
	v_add_co_u32_e32 v2, vcc, s4, v0
	s_mov_b32 s4, 0x50000
	s_nop 0
	v_addc_co_u32_e32 v3, vcc, 0, v1, vcc
	global_load_dwordx4 v[26:29], v[2:3], off nt
	v_add_co_u32_e32 v2, vcc, s89, v0
	v_lshlrev_b32_e32 v128, 1, v13
	s_nop 0
	v_addc_co_u32_e32 v3, vcc, 0, v1, vcc
	global_load_dwordx4 v[64:67], v[2:3], off nt
	v_add_co_u32_e32 v2, vcc, s4, v0
	s_mov_b32 s4, 0x60000
	s_nop 0
	v_addc_co_u32_e32 v3, vcc, 0, v1, vcc
	global_load_dwordx4 v[8:11], v[2:3], off nt
	v_add_co_u32_e32 v2, vcc, s4, v0
	s_mov_b32 s4, 0x70000
	s_nop 0
	v_addc_co_u32_e32 v3, vcc, 0, v1, vcc
	global_load_dwordx4 v[4:7], v[2:3], off nt
	v_add_co_u32_e32 v0, vcc, s4, v0
	s_waitcnt vmcnt(6)
	v_pk_mul_f32 v[14:15], v[14:15], v[30:31] op_sel_hi:[1,0]
	ds_write2_b32 v53, v14, v15 offset1:1
	v_pk_mul_f32 v[14:15], v[16:17], v[30:31] op_sel_hi:[1,0]
	ds_write2_b32 v53, v14, v15 offset0:2 offset1:3
	global_load_dword v14, v31, s[14:15] offset:32
	v_addc_co_u32_e32 v1, vcc, 0, v1, vcc
	global_load_dwordx4 v[0:3], v[0:1], off nt
	s_waitcnt vmcnt(1)
	v_pk_mul_f32 v[16:17], v[18:19], v[14:15] op_sel_hi:[1,0]
	v_add_u32_e32 v15, 0x420, v53
	ds_write2_b32 v15, v16, v17 offset1:1
	v_pk_mul_f32 v[14:15], v[20:21], v[14:15] op_sel_hi:[1,0]
	v_add_u32_e32 v16, 0x428, v53
	ds_write2_b32 v16, v14, v15 offset1:1
	global_load_dword v14, v31, s[14:15] offset:64
	v_add_u32_e32 v18, v33, v59
	s_waitcnt vmcnt(0)
	v_pk_mul_f32 v[16:17], v[22:23], v[14:15] op_sel_hi:[1,0]
	v_add_u32_e32 v15, 0x840, v53
	ds_write2_b32 v15, v16, v17 offset1:1
	v_pk_mul_f32 v[14:15], v[24:25], v[14:15] op_sel_hi:[1,0]
	v_add_u32_e32 v16, 0x848, v53
	ds_write2_b32 v16, v14, v15 offset1:1
	global_load_dword v14, v31, s[14:15] offset:96
	s_waitcnt vmcnt(0)
	v_pk_mul_f32 v[16:17], v[26:27], v[14:15] op_sel_hi:[1,0]
	v_add_u32_e32 v15, 0xc60, v53
	ds_write2_b32 v15, v16, v17 offset1:1
	v_pk_mul_f32 v[14:15], v[28:29], v[14:15] op_sel_hi:[1,0]
	v_add_u32_e32 v16, 0xc68, v53
	ds_write2_b32 v16, v14, v15 offset1:1
	global_load_dword v14, v31, s[14:15] offset:128
	s_waitcnt vmcnt(0)
	v_pk_mul_f32 v[16:17], v[64:65], v[14:15] op_sel_hi:[1,0]
	v_pk_mul_f32 v[14:15], v[66:67], v[14:15] op_sel_hi:[1,0]
	ds_write2_b32 v18, v14, v15 offset0:2 offset1:3
	global_load_dword v14, v31, s[14:15] offset:160
	ds_write2_b32 v18, v16, v17 offset1:1
	s_waitcnt vmcnt(0)
	v_pk_mul_f32 v[8:9], v[8:9], v[14:15] op_sel_hi:[1,0]
	v_add_u32_e32 v15, 0x420, v18
	ds_write2_b32 v15, v8, v9 offset1:1
	v_pk_mul_f32 v[8:9], v[10:11], v[14:15] op_sel_hi:[1,0]
	v_add_u32_e32 v10, 0x428, v18
	ds_write2_b32 v10, v8, v9 offset1:1
	global_load_dword v8, v31, s[14:15] offset:192
	s_waitcnt vmcnt(0)
	v_pk_mul_f32 v[4:5], v[4:5], v[8:9] op_sel_hi:[1,0]
	v_add_u32_e32 v9, 0x840, v18
	ds_write2_b32 v9, v4, v5 offset1:1
	v_pk_mul_f32 v[4:5], v[6:7], v[8:9] op_sel_hi:[1,0]
	v_add_u32_e32 v6, 0x848, v18
	ds_write2_b32 v6, v4, v5 offset1:1
	global_load_dword v4, v31, s[14:15] offset:224
	s_waitcnt vmcnt(0)
	v_pk_mul_f32 v[0:1], v[0:1], v[4:5] op_sel_hi:[1,0]
	v_add_u32_e32 v5, 0xc60, v18
	ds_write2_b32 v5, v0, v1 offset1:1
	v_pk_mul_f32 v[0:1], v[2:3], v[4:5] op_sel_hi:[1,0]
	v_add_u32_e32 v2, 0xc68, v18
	ds_write2_b32 v2, v0, v1 offset1:1
	s_waitcnt lgkmcnt(0)
	ds_read2_b32 v[6:7], v58 offset0:33 offset1:41
	ds_read2_b32 v[8:9], v58 offset1:8
	ds_read2_b32 v[10:11], v58 offset0:66 offset1:74
	ds_read2_b32 v[14:15], v58 offset0:99 offset1:107
	ds_read2_b32 v[16:17], v58 offset0:132 offset1:140
	ds_read2_b32 v[18:19], v58 offset0:165 offset1:173
	ds_read2_b32 v[20:21], v58 offset0:198 offset1:206
	ds_read2_b32 v[22:23], v58 offset0:231 offset1:239
	v_lshl_add_u64 v[4:5], v[44:45], 0, v[128:129]
	s_waitcnt lgkmcnt(6)
	v_cvt_pk_bf16_f32 v0, v8, v6
	v_or_b32_e32 v6, v12, v32
	v_lshlrev_b32_e32 v128, 9, v6
	v_or_b32_e32 v6, v12, v51
	s_waitcnt lgkmcnt(4)
	v_cvt_pk_bf16_f32 v1, v10, v14
	s_waitcnt lgkmcnt(2)
	v_cvt_pk_bf16_f32 v2, v16, v18
	s_waitcnt lgkmcnt(0)
	v_cvt_pk_bf16_f32 v3, v20, v22
	v_lshl_add_u64 v[24:25], v[4:5], 0, v[128:129]
	v_lshlrev_b32_e32 v128, 9, v6
	global_store_dwordx4 v[24:25], v[0:3], off
	s_nop 1
	v_cvt_pk_bf16_f32 v0, v9, v7
	v_cvt_pk_bf16_f32 v1, v11, v15
	v_cvt_pk_bf16_f32 v2, v17, v19
	v_cvt_pk_bf16_f32 v3, v21, v23
	v_lshl_add_u64 v[6:7], v[4:5], 0, v[128:129]
	global_store_dwordx4 v[6:7], v[0:3], off
	ds_read2_b32 v[6:7], v58 offset0:49 offset1:57
	ds_read2_b32 v[8:9], v58 offset0:16 offset1:24
	ds_read2_b32 v[10:11], v58 offset0:82 offset1:90
	ds_read2_b32 v[14:15], v58 offset0:115 offset1:123
	ds_read2_b32 v[16:17], v58 offset0:148 offset1:156
	ds_read2_b32 v[18:19], v58 offset0:181 offset1:189
	ds_read2_b32 v[20:21], v58 offset0:214 offset1:222
	ds_read2_b32 v[22:23], v58 offset0:247 offset1:255
	s_waitcnt lgkmcnt(6)
	v_cvt_pk_bf16_f32 v0, v8, v6
	v_or_b32_e32 v6, v12, v56
	v_lshlrev_b32_e32 v128, 9, v6
	v_or_b32_e32 v6, v12, v57
	s_waitcnt lgkmcnt(4)
	v_cvt_pk_bf16_f32 v1, v10, v14
	s_waitcnt lgkmcnt(2)
	v_cvt_pk_bf16_f32 v2, v16, v18
	s_waitcnt lgkmcnt(0)
	v_cvt_pk_bf16_f32 v3, v20, v22
	v_lshl_add_u64 v[24:25], v[4:5], 0, v[128:129]
	v_lshlrev_b32_e32 v128, 9, v6
	global_store_dwordx4 v[24:25], v[0:3], off
	v_lshl_add_u64 v[4:5], v[4:5], 0, v[128:129]
	s_nop 0
	v_cvt_pk_bf16_f32 v0, v9, v7
	v_cvt_pk_bf16_f32 v1, v11, v15
	v_cvt_pk_bf16_f32 v2, v17, v19
	v_cvt_pk_bf16_f32 v3, v21, v23
	global_store_dwordx4 v[4:5], v[0:3], off
	s_waitcnt lgkmcnt(0)

; #define LAS __attribute__((address_space(3)))
; template <int KIND>
; DI void transpose_item(const float* W, int K, int N, bf16_t* WT, int ldk, const float* g0, const float* g1, const float* g2, LAS float* scr, int item, int lane) {
;     const int nblk = N / 32, kb = item / nblk, nb = item % nblk, k0 = 64 * kb, n0 = 32 * nb;
;     f32x4 tv[8];
; #pragma unroll
;     for (int i = 0; i < 8; ++i) tv[i] = *(const f32x4*)(W + (size_t)(k0 + 8 * i + (lane >> 3)) * N + n0 + 4 * (lane & 7));
; #pragma unroll
;     for (int i = 0; i < 8; ++i) {
;         const int kk = 8 * i + (lane >> 3), k = k0 + kk;
;         float gn = 1.f;
;         if (KIND == 0 || KIND == 1 || KIND == 2 || KIND == 5 || KIND == 6) gn = g0[k];
;         if (KIND == 4) gn = k < 1024 ? g0[k] : (k < 1536 ? g1[k - 1024] : g2[k - 1536]);
;         LAS float* d = scr + kk * 33 + 4 * (lane & 7);
;         d[0] = tv[i][0] * gn; d[1] = tv[i][1] * gn; d[2] = tv[i][2] * gn; d[3] = tv[i][3] * gn;
;     }
;     asm volatile("s_waitcnt lgkmcnt(0)" ::: "memory");
; DI void convert_weights(PP p, LAS unsigned char* lds, int l, int worker, int nworkers) {
;     ...
;         if (r < I_UQ) { transpose_item<1>(p->in[4] + (size_t)l * 512 * 1536, 512, 1536, (bf16_t*)(wl + W_UQ), 512, p->in[3] + l * 512, nullptr, nullptr, scr, r, lane); continue; } r -= I_UQ;
.LBB0_711:
	s_andn2_saveexec_b64 s[14:15], s[64:65]
	s_cbranch_execz .LBB0_713
	s_load_dwordx4 s[16:19], s[8:9], 0x18
	v_add_u16_e32 v0, 0xf4c0, v62
	v_mul_u32_u24_e32 v1, 0xaaab, v0
	v_lshrrev_b32_e32 v1, 21, v1
	v_readlane_b32 s6, v255, 1
	v_mul_lo_u16_e32 v2, 48, v1
	s_mul_i32 s4, s6, 0x300000
	v_sub_u16_e32 v0, v0, v2
	s_waitcnt lgkmcnt(0)
	s_add_u32 s18, s18, s4
	s_mul_hi_u32 s4, s6, 0x300000
	v_lshlrev_b16_e32 v13, 6, v1
	v_lshlrev_b16_e32 v12, 5, v0
	v_readlane_b32 s7, v255, 2
	s_addc_u32 s19, s19, s4
	v_or_b32_e32 v30, v32, v13
	v_lshlrev_b32_e32 v128, 2, v12
	s_lshl_b64 s[6:7], s[52:53], 2
	v_lshl_add_u64 v[0:1], s[18:19], 0, v[128:129]
	v_lshlrev_b32_e32 v128, 2, v34
	v_mul_u32_u24_e32 v2, 0x600, v30
	s_add_u32 s6, s16, s6
	v_lshl_add_u64 v[0:1], v[0:1], 0, v[128:129]
	v_lshlrev_b32_e32 v128, 2, v2
	s_addc_u32 s7, s17, s7
	v_lshl_add_u64 v[0:1], v[0:1], 0, v[128:129]
	v_lshlrev_b32_e32 v31, 2, v30
	global_load_dwordx4 v[14:17], v[0:1], off nt
	global_load_dword v30, v31, s[6:7]
	s_mov_b32 s4, 0xc000
	v_add_co_u32_e32 v2, vcc, s4, v0
	v_add_u32_e32 v53, v33, v35
	s_nop 0
	v_addc_co_u32_e32 v3, vcc, 0, v1, vcc
	global_load_dwordx4 v[18:21], v[2:3], off nt
	s_mov_b32 s4, 0x18000
	v_add_co_u32_e32 v2, vcc, s4, v0
	s_mov_b32 s4, 0x24000
	s_nop 0
	v_addc_co_u32_e32 v3, vcc, 0, v1, vcc
	global_load_dwordx4 v[22:25], v[2:3], off nt
	v_add_co_u32_e32 v2, vcc, s4, v0
	s_mov_b32 s4, 0x30000
	s_nop 0
	v_addc_co_u32_e32 v3, vcc, 0, v1, vcc
	global_load_dwordx4 v[26:29], v[2:3], off nt
	v_add_co_u32_e32 v2, vcc, s4, v0
	s_mov_b32 s4, 0x3c000
	s_nop 0
	v_addc_co_u32_e32 v3, vcc, 0, v1, vcc
	global_load_dwordx4 v[64:67], v[2:3], off nt
	v_add_co_u32_e32 v2, vcc, s4, v0
	s_mov_b32 s4, 0x48000
	s_nop 0
	v_addc_co_u32_e32 v3, vcc, 0, v1, vcc
	global_load_dwordx4 v[8:11], v[2:3], off nt
	v_add_co_u32_e32 v2, vcc, s4, v0
	s_mov_b32 s4, 0x54000
	s_nop 0
	v_addc_co_u32_e32 v3, vcc, 0, v1, vcc
	global_load_dwordx4 v[4:7], v[2:3], off nt
	v_add_co_u32_e32 v0, vcc, s4, v0
	s_movk_i32 s16, 0xa0
	s_nop 0
	v_addc_co_u32_e32 v1, vcc, 0, v1, vcc
	global_load_dwordx4 v[0:3], v[0:1], off nt
	v_lshlrev_b32_e32 v128, 1, v13
	s_movk_i32 s4, 0x80
	s_waitcnt vmcnt(7)
	v_pk_mul_f32 v[14:15], v[14:15], v[30:31] op_sel_hi:[1,0]
	ds_write2_b32 v53, v14, v15 offset1:1
	v_pk_mul_f32 v[14:15], v[16:17], v[30:31] op_sel_hi:[1,0]
	ds_write2_b32 v53, v14, v15 offset0:2 offset1:3
	global_load_dword v14, v31, s[6:7] offset:32
	s_waitcnt vmcnt(0)
	v_pk_mul_f32 v[16:17], v[18:19], v[14:15] op_sel_hi:[1,0]
	v_add_u32_e32 v15, 0x420, v53
	ds_write2_b32 v15, v16, v17 offset1:1
	v_pk_mul_f32 v[14:15], v[20:21], v[14:15] op_sel_hi:[1,0]
	v_add_u32_e32 v16, 0x428, v53
	ds_write2_b32 v16, v14, v15 offset1:1
	global_load_dword v14, v31, s[6:7] offset:64
	v_add_u32_e32 v18, v33, v59
	s_waitcnt vmcnt(0)
	v_pk_mul_f32 v[16:17], v[22:23], v[14:15] op_sel_hi:[1,0]
	v_add_u32_e32 v15, 0x840, v53
	ds_write2_b32 v15, v16, v17 offset1:1
	v_pk_mul_f32 v[14:15], v[24:25], v[14:15] op_sel_hi:[1,0]
	v_add_u32_e32 v16, 0x848, v53
	ds_write2_b32 v16, v14, v15 offset1:1
	global_load_dword v14, v31, s[6:7] offset:96
	s_waitcnt vmcnt(0)
	v_pk_mul_f32 v[16:17], v[26:27], v[14:15] op_sel_hi:[1,0]
	v_add_u32_e32 v15, 0xc60, v53
	ds_write2_b32 v15, v16, v17 offset1:1
	v_pk_mul_f32 v[14:15], v[28:29], v[14:15] op_sel_hi:[1,0]
	v_add_u32_e32 v16, 0xc68, v53
	ds_write2_b32 v16, v14, v15 offset1:1
	global_load_dword v14, v31, s[6:7] offset:128
	s_waitcnt vmcnt(0)
	v_pk_mul_f32 v[16:17], v[64:65], v[14:15] op_sel_hi:[1,0]
	v_pk_mul_f32 v[14:15], v[66:67], v[14:15] op_sel_hi:[1,0]
	ds_write2_b32 v18, v14, v15 offset0:2 offset1:3
	global_load_dword v14, v31, s[6:7] offset:160
	ds_write2_b32 v18, v16, v17 offset1:1
	s_waitcnt vmcnt(0)
	v_pk_mul_f32 v[8:9], v[8:9], v[14:15] op_sel_hi:[1,0]
	v_add_u32_e32 v15, 0x420, v18
	ds_write2_b32 v15, v8, v9 offset1:1
	v_pk_mul_f32 v[8:9], v[10:11], v[14:15] op_sel_hi:[1,0]
	v_add_u32_e32 v10, 0x428, v18
	ds_write2_b32 v10, v8, v9 offset1:1
	global_load_dword v8, v31, s[6:7] offset:192
	s_waitcnt vmcnt(0)
; #define LAS __attribute__((address_space(3)))
; DI unsigned cvtpk(float lo, float hi) { f32x2 v = {lo, hi}; bf16x2_t b = __builtin_convertvector(v, bf16x2_t); return __builtin_bit_cast(unsigned, b); }
; template <int KIND> DI int map_n(int n) {
;     ...
;     if (KIND == 1) {
;         const int hd = n / 192, w = n % 192;
;         if (w < 128) return n;
;         const int j = w - 128; return hd * 192 + 128 + (j < 32 ? 2 * j : 2 * (j - 32) + 1);
;     }
; template <int KIND>
; DI void transpose_item(const float* W, int K, int N, bf16_t* WT, int ldk, const float* g0, const float* g1, const float* g2, LAS float* scr, int item, int lane) {
;     ...
;         LAS float* d = scr + kk * 33 + 4 * (lane & 7);
;         d[0] = tv[i][0] * gn; d[1] = tv[i][1] * gn; d[2] = tv[i][2] * gn; d[3] = tv[i][3] * gn;
;     }
;     asm volatile("s_waitcnt lgkmcnt(0)" ::: "memory");
;     int kd0 = k0;
;     if (KIND == 4) kd0 = k0 < 1024 ? k0 + 512 : (k0 < 1536 ? k0 - 1024 : k0);
;     const int c = lane & 7;
; #pragma unroll
;     for (int j = 0; j < 4; ++j) { const int n = (lane >> 3) + 8 * j; const LAS float* s = scr + (8 * c) * 33 + n;
;         u32x4 o; o.x = cvtpk(s[0 * 33], s[1 * 33]); o.y = cvtpk(s[2 * 33], s[3 * 33]); o.z = cvtpk(s[4 * 33], s[5 * 33]); o.w = cvtpk(s[6 * 33], s[7 * 33]);
;         *(u32x4*)(WT + (size_t)map_n<KIND>(n0 + n) * ldk + kd0 + 8 * c) = o; }
	v_pk_mul_f32 v[4:5], v[4:5], v[8:9] op_sel_hi:[1,0]
	v_add_u32_e32 v9, 0x840, v18
	ds_write2_b32 v9, v4, v5 offset1:1
	v_pk_mul_f32 v[4:5], v[6:7], v[8:9] op_sel_hi:[1,0]
	v_add_u32_e32 v6, 0x848, v18
	ds_write2_b32 v6, v4, v5 offset1:1
	global_load_dword v4, v31, s[6:7] offset:224
	s_waitcnt vmcnt(0)
	v_pk_mul_f32 v[0:1], v[0:1], v[4:5] op_sel_hi:[1,0]
	v_add_u32_e32 v5, 0xc60, v18
	ds_write2_b32 v5, v0, v1 offset1:1
	v_pk_mul_f32 v[0:1], v[2:3], v[4:5] op_sel_hi:[1,0]
	v_add_u32_e32 v2, 0xc68, v18
	ds_write2_b32 v2, v0, v1 offset1:1
	s_waitcnt lgkmcnt(0)
	ds_read2_b32 v[6:7], v58 offset0:33 offset1:41
	ds_read2_b32 v[8:9], v58 offset1:8
	ds_read2_b32 v[10:11], v58 offset0:66 offset1:74
	ds_read2_b32 v[14:15], v58 offset0:99 offset1:107
	ds_read2_b32 v[16:17], v58 offset0:132 offset1:140
	ds_read2_b32 v[18:19], v58 offset0:165 offset1:173
	ds_read2_b32 v[20:21], v58 offset0:198 offset1:206
	ds_read2_b32 v[22:23], v58 offset0:231 offset1:239
	v_lshl_add_u64 v[4:5], v[46:47], 0, v[128:129]
	s_waitcnt lgkmcnt(6)
	v_cvt_pk_bf16_f32 v0, v8, v6
	v_or_b32_e32 v6, v32, v12
	v_mul_u32_u24_e32 v8, 0x2aab, v6
	v_lshrrev_b32_e32 v8, 21, v8
	v_mul_lo_u16_e32 v8, 0xc0, v8
	v_sub_u16_e32 v8, v6, v8
	v_cmp_gt_u16_e64 s[6:7], s16, v8
	v_sub_u32_e32 v13, v6, v8
	s_waitcnt lgkmcnt(4)
	v_cvt_pk_bf16_f32 v1, v10, v14
	v_cmp_gt_u16_e32 vcc, s4, v8
	v_cndmask_b32_e64 v10, v201, v202, s[6:7]
	v_lshl_add_u32 v8, v8, 1, v13
	v_add3_u32 v8, v8, v10, s4
	v_cndmask_b32_e32 v24, v8, v6, vcc
	v_ashrrev_i32_e32 v25, 31, v24
	v_lshlrev_b64 v[24:25], 10, v[24:25]
	s_waitcnt lgkmcnt(2)
	v_cvt_pk_bf16_f32 v2, v16, v18
	s_waitcnt lgkmcnt(0)
	v_cvt_pk_bf16_f32 v3, v20, v22
	v_lshl_add_u64 v[24:25], v[4:5], 0, v[24:25]
	v_or_b32_e32 v6, v51, v12
	global_store_dwordx4 v[24:25], v[0:3], off
	s_nop 1
	v_cvt_pk_bf16_f32 v0, v9, v7
	v_mul_u32_u24_e32 v7, 0x2aab, v6
	v_lshrrev_b32_e32 v7, 21, v7
	v_mul_lo_u16_e32 v7, 0xc0, v7
	v_sub_u16_e32 v7, v6, v7
	v_cmp_gt_u16_e64 s[6:7], s16, v7
	v_sub_u32_e32 v9, v6, v7
	v_cmp_gt_u16_e32 vcc, s4, v7
	v_cndmask_b32_e64 v8, v201, v202, s[6:7]
	v_lshl_add_u32 v7, v7, 1, v9
	v_add3_u32 v7, v7, v8, s4
	v_cndmask_b32_e32 v6, v7, v6, vcc
	v_ashrrev_i32_e32 v7, 31, v6
	v_lshlrev_b64 v[6:7], 10, v[6:7]
	v_cvt_pk_bf16_f32 v1, v11, v15
	v_cvt_pk_bf16_f32 v2, v17, v19
	v_cvt_pk_bf16_f32 v3, v21, v23
	v_lshl_add_u64 v[6:7], v[4:5], 0, v[6:7]
	global_store_dwordx4 v[6:7], v[0:3], off
	ds_read2_b32 v[6:7], v58 offset0:16 offset1:24
	ds_read2_b32 v[8:9], v58 offset0:49 offset1:57
	ds_read2_b32 v[10:11], v58 offset0:82 offset1:90
	ds_read2_b32 v[14:15], v58 offset0:115 offset1:123
	ds_read2_b32 v[16:17], v58 offset0:148 offset1:156
	ds_read2_b32 v[18:19], v58 offset0:181 offset1:189
	ds_read2_b32 v[20:21], v58 offset0:214 offset1:222
	ds_read2_b32 v[22:23], v58 offset0:247 offset1:255
	s_waitcnt lgkmcnt(6)
	v_cvt_pk_bf16_f32 v0, v6, v8
	v_or_b32_e32 v6, v56, v12
	v_mul_u32_u24_e32 v8, 0x2aab, v6
	v_lshrrev_b32_e32 v8, 21, v8
	v_mul_lo_u16_e32 v8, 0xc0, v8
	v_sub_u16_e32 v8, v6, v8
	v_cmp_gt_u16_e64 s[6:7], s16, v8
	v_sub_u32_e32 v13, v6, v8
	s_waitcnt lgkmcnt(4)
	v_cvt_pk_bf16_f32 v1, v10, v14
	v_cmp_gt_u16_e32 vcc, s4, v8
	v_cndmask_b32_e64 v10, v201, v202, s[6:7]
	v_lshl_add_u32 v8, v8, 1, v13
	v_add3_u32 v8, v8, v10, s4
	v_cndmask_b32_e32 v24, v8, v6, vcc
	v_ashrrev_i32_e32 v25, 31, v24
	v_lshlrev_b64 v[24:25], 10, v[24:25]
	s_waitcnt lgkmcnt(2)
	v_cvt_pk_bf16_f32 v2, v16, v18
	s_waitcnt lgkmcnt(0)
	v_cvt_pk_bf16_f32 v3, v20, v22
	v_lshl_add_u64 v[24:25], v[4:5], 0, v[24:25]
	v_or_b32_e32 v6, v57, v12
	global_store_dwordx4 v[24:25], v[0:3], off
	s_nop 1
	v_cvt_pk_bf16_f32 v0, v7, v9
	v_mul_u32_u24_e32 v7, 0x2aab, v6
	v_lshrrev_b32_e32 v7, 21, v7
	v_mul_lo_u16_e32 v7, 0xc0, v7
	v_sub_u16_e32 v7, v6, v7
	v_cmp_gt_u16_e64 s[6:7], s16, v7
	v_sub_u32_e32 v9, v6, v7
	v_cmp_gt_u16_e32 vcc, s4, v7
	v_cndmask_b32_e64 v8, v201, v202, s[6:7]
	v_lshl_add_u32 v7, v7, 1, v9
	v_add3_u32 v7, v7, v8, s4
	v_cndmask_b32_e32 v6, v7, v6, vcc
	v_ashrrev_i32_e32 v7, 31, v6
	v_lshlrev_b64 v[6:7], 10, v[6:7]
	v_cvt_pk_bf16_f32 v1, v11, v15
	v_cvt_pk_bf16_f32 v2, v17, v19
	v_cvt_pk_bf16_f32 v3, v21, v23
	v_lshl_add_u64 v[4:5], v[4:5], 0, v[6:7]
	global_store_dwordx4 v[4:5], v[0:3], off
	s_waitcnt lgkmcnt(0)

; #define LAS __attribute__((address_space(3)))
; template <int KIND>
; DI void transpose_item(const float* W, int K, int N, bf16_t* WT, int ldk, const float* g0, const float* g1, const float* g2, LAS float* scr, int item, int lane) {
;     const int nblk = N / 32, kb = item / nblk, nb = item % nblk, k0 = 64 * kb, n0 = 32 * nb;
;     f32x4 tv[8];
; #pragma unroll
;     for (int i = 0; i < 8; ++i) tv[i] = *(const f32x4*)(W + (size_t)(k0 + 8 * i + (lane >> 3)) * N + n0 + 4 * (lane & 7));
; #pragma unroll
;     for (int i = 0; i < 8; ++i) {
;         const int kk = 8 * i + (lane >> 3), k = k0 + kk;
;         float gn = 1.f;
;         if (KIND == 0 || KIND == 1 || KIND == 2 || KIND == 5 || KIND == 6) gn = g0[k];
;         if (KIND == 4) gn = k < 1024 ? g0[k] : (k < 1536 ? g1[k - 1024] : g2[k - 1536]);
;         LAS float* d = scr + kk * 33 + 4 * (lane & 7);
;         d[0] = tv[i][0] * gn; d[1] = tv[i][1] * gn; d[2] = tv[i][2] * gn; d[3] = tv[i][3] * gn;
;     }
;     asm volatile("s_waitcnt lgkmcnt(0)" ::: "memory");
; DI void convert_weights(PP p, LAS unsigned char* lds, int l, int worker, int nworkers) {
;     ...
;         if (r < I_IN) { transpose_item<0>(p->in[2] + (size_t)l * 2048 * 2880, 2048, 2880, (bf16_t*)(wl + W_IN), 2048, p->in[1] + l * 2048, nullptr, nullptr, scr, r, lane); continue; } r -= I_IN;
.LBB0_714:
	s_andn2_saveexec_b64 s[6:7], s[62:63]
	s_cbranch_execz .LBB0_623
	s_load_dwordx4 s[16:19], s[8:9], 0x8
	v_readlane_b32 s14, v255, 1
	s_mul_i32 s4, s14, 0x1680000
	v_readlane_b32 s15, v255, 2
	v_lshlrev_b32_e32 v128, 2, v34
	s_waitcnt lgkmcnt(0)
	s_add_u32 s18, s18, s4
	s_mul_hi_u32 s4, s14, 0x1680000
	s_addc_u32 s19, s19, s4
	s_mov_b32 s4, 0xb60b60b7
	v_mul_hi_i32 v0, v62, s4
	v_add_u32_e32 v0, v0, v62
	v_lshrrev_b32_e32 v1, 31, v0
	v_ashrrev_i32_e32 v0, 6, v0
	s_lshl_b64 s[14:15], s[38:39], 2
	v_add_u32_e32 v16, v0, v1
	s_movk_i32 s4, 0x5a
	s_add_u32 s14, s16, s14
	v_mul_lo_u32 v0, v16, s4
	s_movk_i32 s4, 0xf4c0
	s_addc_u32 s15, s17, s15
	v_mad_u64_u32 v[8:9], s[16:17], v16, s4, v[50:51]
	v_sub_u32_e32 v0, v62, v0
	v_lshlrev_b32_e32 v10, 6, v16
	v_ashrrev_i32_e32 v9, 31, v8
	v_lshlrev_b32_e32 v17, 5, v0
	v_or_b32_e32 v30, v10, v32
	v_lshl_add_u64 v[0:1], v[8:9], 2, s[18:19]
	v_lshl_add_u64 v[0:1], v[0:1], 0, v[128:129]
	v_ashrrev_i32_e32 v31, 31, v30
	s_movk_i32 s4, 0x2d00
	v_mad_i64_i32 v[2:3], s[16:17], v30, s4, v[0:1]
	v_lshl_add_u64 v[54:55], v[30:31], 2, s[14:15]
	global_load_dwordx4 v[12:15], v[2:3], off nt
	v_add_u32_e32 v9, v33, v35
	global_load_dword v54, v[54:55], off
	v_ashrrev_i32_e32 v11, 31, v10
	v_or_b32_e32 v2, 8, v30
	v_mov_b32_e32 v31, v11
	v_mad_i64_i32 v[2:3], s[16:17], v2, s4, v[0:1]
	global_load_dwordx4 v[18:21], v[2:3], off nt
	v_or_b32_e32 v2, 16, v30
	v_mad_i64_i32 v[2:3], s[16:17], v2, s4, v[0:1]
	global_load_dwordx4 v[22:25], v[2:3], off nt
	v_or_b32_e32 v2, 24, v30
	v_mad_i64_i32 v[2:3], s[16:17], v2, s4, v[0:1]
	global_load_dwordx4 v[26:29], v[2:3], off nt
	v_or_b32_e32 v2, 32, v30
	v_mad_i64_i32 v[2:3], s[16:17], v2, s4, v[0:1]
	global_load_dwordx4 v[64:67], v[2:3], off nt
	v_or_b32_e32 v2, 40, v30
	v_mad_i64_i32 v[2:3], s[16:17], v2, s4, v[0:1]
	global_load_dwordx4 v[68:71], v[2:3], off nt
	v_or_b32_e32 v2, 48, v30
	v_mad_i64_i32 v[2:3], s[16:17], v2, s4, v[0:1]
	global_load_dwordx4 v[4:7], v[2:3], off nt
	v_or_b32_e32 v2, 56, v30
	v_mad_i64_i32 v[0:1], s[16:17], v2, s4, v[0:1]
	global_load_dwordx4 v[0:3], v[0:1], off nt
	s_movk_i32 s4, 0x2ff
	s_waitcnt vmcnt(7)
	v_pk_mul_f32 v[12:13], v[12:13], v[54:55] op_sel_hi:[1,0]
	ds_write2_b32 v9, v12, v13 offset1:1
	v_pk_mul_f32 v[12:13], v[14:15], v[54:55] op_sel_hi:[1,0]
	ds_write2_b32 v9, v12, v13 offset0:2 offset1:3
	v_lshl_add_u64 v[12:13], v[30:31], 2, s[14:15]
	global_load_dword v14, v[12:13], off offset:32
	s_waitcnt vmcnt(0)
	v_pk_mul_f32 v[18:19], v[18:19], v[14:15] op_sel_hi:[1,0]
	v_add_u32_e32 v15, 0x420, v9
	ds_write2_b32 v15, v18, v19 offset1:1
	v_pk_mul_f32 v[14:15], v[20:21], v[14:15] op_sel_hi:[1,0]
	v_add_u32_e32 v18, 0x428, v9
	ds_write2_b32 v18, v14, v15 offset1:1
	global_load_dword v14, v[12:13], off offset:64
	s_waitcnt vmcnt(0)
	v_pk_mul_f32 v[18:19], v[22:23], v[14:15] op_sel_hi:[1,0]
	v_add_u32_e32 v15, 0x840, v9
	ds_write2_b32 v15, v18, v19 offset1:1
	v_pk_mul_f32 v[14:15], v[24:25], v[14:15] op_sel_hi:[1,0]
	v_add_u32_e32 v18, 0x848, v9
	ds_write2_b32 v18, v14, v15 offset1:1
	global_load_dword v14, v[12:13], off offset:96
	s_waitcnt vmcnt(0)
	v_pk_mul_f32 v[18:19], v[26:27], v[14:15] op_sel_hi:[1,0]
	v_add_u32_e32 v15, 0xc60, v9
	ds_write2_b32 v15, v18, v19 offset1:1
	v_pk_mul_f32 v[14:15], v[28:29], v[14:15] op_sel_hi:[1,0]
	v_add_u32_e32 v9, 0xc68, v9
	ds_write2_b32 v9, v14, v15 offset1:1
	global_load_dword v14, v[12:13], off offset:128
	v_add_u32_e32 v9, v33, v59
	s_waitcnt vmcnt(0)
	v_pk_mul_f32 v[18:19], v[64:65], v[14:15] op_sel_hi:[1,0]
	v_pk_mul_f32 v[14:15], v[66:67], v[14:15] op_sel_hi:[1,0]
	ds_write2_b32 v9, v14, v15 offset0:2 offset1:3
	global_load_dword v14, v[12:13], off offset:160
	ds_write2_b32 v9, v18, v19 offset1:1
	s_waitcnt vmcnt(0)
	v_pk_mul_f32 v[18:19], v[68:69], v[14:15] op_sel_hi:[1,0]
	v_add_u32_e32 v15, 0x420, v9
	ds_write2_b32 v15, v18, v19 offset1:1
	v_pk_mul_f32 v[14:15], v[70:71], v[14:15] op_sel_hi:[1,0]
	v_add_u32_e32 v18, 0x428, v9
	ds_write2_b32 v18, v14, v15 offset1:1
	global_load_dword v14, v[12:13], off offset:192
	s_waitcnt vmcnt(0)
	v_pk_mul_f32 v[4:5], v[4:5], v[14:15] op_sel_hi:[1,0]
	v_add_u32_e32 v15, 0x840, v9
	ds_write2_b32 v15, v4, v5 offset1:1
	v_pk_mul_f32 v[4:5], v[6:7], v[14:15] op_sel_hi:[1,0]
	v_add_u32_e32 v6, 0x848, v9
	ds_write2_b32 v6, v4, v5 offset1:1
	global_load_dword v4, v[12:13], off offset:224
	v_or_b32_e32 v14, v17, v32
	s_waitcnt vmcnt(0)
	v_pk_mul_f32 v[0:1], v[0:1], v[4:5] op_sel_hi:[1,0]
	v_add_u32_e32 v5, 0xc60, v9
	ds_write2_b32 v5, v0, v1 offset1:1
	v_pk_mul_f32 v[0:1], v[2:3], v[4:5] op_sel_hi:[1,0]
	v_add_u32_e32 v2, 0xc68, v9
	ds_write2_b32 v2, v0, v1 offset1:1
	s_waitcnt lgkmcnt(0)
	ds_read2_b32 v[2:3], v58 offset1:33
	ds_read2_b32 v[4:5], v58 offset0:66 offset1:99
	ds_read2_b32 v[6:7], v58 offset0:132 offset1:165
	ds_read2_b32 v[12:13], v58 offset0:198 offset1:231
	v_add_u32_e32 v9, v8, v32
	v_cmp_lt_i32_e32 vcc, s4, v9
	s_and_saveexec_b64 s[14:15], vcc
	s_cbranch_execz .LBB0_721
	s_movk_i32 s4, 0x33f
	v_cmp_lt_u32_e32 vcc, s4, v8
	s_and_saveexec_b64 s[16:17], vcc
	s_xor_b64 s[16:17], exec, s[16:17]
	v_subrev_u32_e32 v14, 64, v14
	s_andn2_saveexec_b64 s[16:17], s[16:17]
	s_movk_i32 s4, 0x320
	v_cmp_gt_u32_e32 vcc, s4, v8
	s_movk_i32 s4, 0x1680
	v_mul_lo_u32 v1, v16, s4
	v_cndmask_b32_e32 v0, v203, v204, vcc
	v_sub_u32_e32 v0, v0, v1
	s_movk_i32 s4, 0xffd0
	v_add3_u32 v14, v60, v0, s4
	s_or_b64 exec, exec, s[16:17]

; template <int KIND>
; DI void transpose_item(const float* W, int K, int N, bf16_t* WT, int ldk, const float* g0, const float* g1, const float* g2, LAS float* scr, int item, int lane) {
;     const int nblk = N / 32, kb = item / nblk, nb = item % nblk, k0 = 64 * kb, n0 = 32 * nb;
;     f32x4 tv[8];
; #pragma unroll
;     for (int i = 0; i < 8; ++i) tv[i] = *(const f32x4*)(W + (size_t)(k0 + 8 * i + (lane >> 3)) * N + n0 + 4 * (lane & 7));
; #pragma unroll
;     for (int i = 0; i < 8; ++i) {
;         const int kk = 8 * i + (lane >> 3), k = k0 + kk;
;         float gn = 1.f;
;         if (KIND == 0 || KIND == 1 || KIND == 2 || KIND == 5 || KIND == 6) gn = g0[k];
; DI void convert_weights(PP p, LAS unsigned char* lds, int l, int worker, int nworkers) {
;     ...
;     for (int it = worker; it < I_LAYER; it += nworkers) {
;         int r = it;
;         if (r < I_IN) { transpose_item<0>(p->in[2] + (size_t)l * 2048 * 2880, 2048, 2880, (bf16_t*)(wl + W_IN), 2048, p->in[1] + l * 2048, nullptr, nullptr, scr, r, lane); continue; } r -= I_IN;
;         if (r < I_UQ) { transpose_item<1>(p->in[4] + (size_t)l * 512 * 1536, 512, 1536, (bf16_t*)(wl + W_UQ), 512, p->in[3] + l * 512, nullptr, nullptr, scr, r, lane); continue; } r -= I_UQ;
;         if (r < I_UKV) { transpose_item<2>(p->in[6] + (size_t)l * 256 * 2048, 256, 2048, (bf16_t*)(wl + W_UKV), 256, p->in[5] + l * 256, nullptr, nullptr, scr, r, lane); continue; } r -= I_UKV;
;         if (r < I_GLU) { transpose_item<3>(p->in[15] + (size_t)l * 512 * 1024, 512, 1024, (bf16_t*)(wl + W_GLU), 512, nullptr, nullptr, nullptr, scr, r, lane); continue; } r -= I_GLU;
;         if (r < I_O) { transpose_item<4>(p->in[20] + (size_t)l * 2048 * 2048, 2048, 2048, (bf16_t*)(wl + W_O), 2048, p->in[17] + l * 1024, p->in[18] + l * 512, p->in[19] + l * 512, scr, r, lane); continue; } r -= I_O;
;         if (r < I_G) { transpose_item<5>(p->in[22] + (size_t)l * 2048 * DFF_, 2048, DFF_, (bf16_t*)(wl + W_GU), 2048, p->in[21] + l * 2048, nullptr, nullptr, scr, r, lane); continue; } r -= I_G;
;         if (r < I_G) { transpose_item<6>(p->in[23] + (size_t)l * 2048 * DFF_, 2048, DFF_, (bf16_t*)(wl + W_GU), 2048, p->in[21] + l * 2048, nullptr, nullptr, scr, r, lane); continue; } r -= I_G;
;         transpose_item<7>(p->in[24] + (size_t)l * DFF_ * 2048, DFF_, 2048, (bf16_t*)(wl + W_DN), DFF_, nullptr, nullptr, nullptr, scr, r, lane);
.LBB0_1379:
	s_movk_i32 s4, 0xb3f
	v_cmp_lt_i32_e32 vcc, s4, v62
	s_and_saveexec_b64 s[6:7], vcc
	s_xor_b64 s[64:65], exec, s[6:7]
	s_cbranch_execz .LBB0_1469
	s_movk_i32 s4, 0xcbf
	v_cmp_lt_u32_e32 vcc, s4, v62
	s_and_saveexec_b64 s[6:7], vcc
	s_xor_b64 s[66:67], exec, s[6:7]
	s_cbranch_execz .LBB0_1466
	s_movk_i32 s4, 0xdbf
	v_cmp_lt_u32_e32 vcc, s4, v62
	s_and_saveexec_b64 s[6:7], vcc
	s_xor_b64 s[68:69], exec, s[6:7]
	s_cbranch_execz .LBB0_1463
	s_movk_i32 s4, 0xebf
	v_cmp_lt_u32_e32 vcc, s4, v62
	s_and_saveexec_b64 s[6:7], vcc
	s_xor_b64 s[70:71], exec, s[6:7]
	s_cbranch_execz .LBB0_1460
	s_movk_i32 s4, 0x16bf
	v_cmp_lt_u32_e32 vcc, s4, v62
	s_and_saveexec_b64 s[6:7], vcc
	s_xor_b64 s[6:7], exec, s[6:7]
	s_cbranch_execz .LBB0_1393
	s_movk_i32 s4, 0x2cbf
	v_cmp_lt_u32_e32 vcc, s4, v62
	s_and_saveexec_b64 s[14:15], vcc
	s_xor_b64 s[14:15], exec, s[14:15]
	s_cbranch_execz .LBB0_1390
	s_movk_i32 s4, 0x42bf
	v_cmp_lt_u32_e32 vcc, s4, v62
	s_and_saveexec_b64 s[16:17], vcc
	s_xor_b64 s[16:17], exec, s[16:17]
	s_cbranch_execz .LBB0_1387
	s_load_dwordx2 s[18:19], s[8:9], 0xc0
	v_add_u32_e32 v0, 0xffffbd40, v62
	v_and_b32_e32 v53, 0x1fc0, v0
	v_add_u32_e32 v0, 0xfff7a800, v50
	v_and_b32_e32 v54, 0x7e0, v0
	s_waitcnt lgkmcnt(0)
	s_add_u32 s18, s18, s1
	s_addc_u32 s19, s19, s0
	v_lshlrev_b32_e32 v128, 2, v54
	v_or_b32_e32 v2, v53, v32
	v_lshl_add_u64 v[0:1], s[18:19], 0, v[128:129]
	v_lshlrev_b32_e32 v128, 2, v34
	v_lshl_add_u64 v[0:1], v[0:1], 0, v[128:129]
	v_lshlrev_b32_e32 v128, 13, v2
	v_lshl_add_u64 v[28:29], v[0:1], 0, v[128:129]
	s_mov_b32 s4, 0x10000
	v_add_co_u32_e32 v4, vcc, s4, v28
	global_load_dwordx4 v[0:3], v[28:29], off nt
	s_nop 0
	v_addc_co_u32_e32 v5, vcc, 0, v29, vcc
	s_mov_b32 s4, 0x20000
	global_load_dwordx4 v[4:7], v[4:5], off nt
	v_add_co_u32_e32 v8, vcc, s4, v28
	s_mov_b32 s4, 0x30000
	s_nop 0
	v_addc_co_u32_e32 v9, vcc, 0, v29, vcc
	global_load_dwordx4 v[8:11], v[8:9], off nt
	v_add_co_u32_e32 v12, vcc, s4, v28
	s_mov_b32 s4, 0x50000
	s_nop 0
	v_addc_co_u32_e32 v13, vcc, 0, v29, vcc
	global_load_dwordx4 v[12:15], v[12:13], off nt
	v_add_co_u32_e32 v16, vcc, s89, v28
	v_add_u32_e32 v55, v33, v35
	s_nop 0
	v_addc_co_u32_e32 v17, vcc, 0, v29, vcc
	global_load_dwordx4 v[16:19], v[16:17], off nt
	v_add_co_u32_e32 v20, vcc, s4, v28
	s_mov_b32 s4, 0x60000
	s_nop 0
	v_addc_co_u32_e32 v21, vcc, 0, v29, vcc
	global_load_dwordx4 v[20:23], v[20:21], off nt
	v_add_co_u32_e32 v24, vcc, s4, v28
	s_mov_b32 s4, 0x70000
	s_nop 0
	v_addc_co_u32_e32 v25, vcc, 0, v29, vcc
	global_load_dwordx4 v[24:27], v[24:25], off nt
	v_add_co_u32_e32 v28, vcc, s4, v28
	v_lshlrev_b32_e32 v128, 1, v53
	s_nop 0
	v_addc_co_u32_e32 v29, vcc, 0, v29, vcc
	global_load_dwordx4 v[28:31], v[28:29], off nt
	s_waitcnt vmcnt(7)
	ds_write2_b32 v55, v0, v1 offset1:1
	ds_write2_b32 v55, v2, v3 offset0:2 offset1:3
	v_add_u32_e32 v0, 0x420, v55
	s_waitcnt vmcnt(6)
	ds_write2_b32 v0, v4, v5 offset1:1
	v_add_u32_e32 v0, 0x428, v55
	ds_write2_b32 v0, v6, v7 offset1:1
	v_add_u32_e32 v0, 0x840, v55
	s_waitcnt vmcnt(5)
	ds_write2_b32 v0, v8, v9 offset1:1
	v_add_u32_e32 v0, 0x848, v55
	ds_write2_b32 v0, v10, v11 offset1:1
	v_add_u32_e32 v0, 0xc60, v55
	s_waitcnt vmcnt(4)
	ds_write2_b32 v0, v12, v13 offset1:1
	v_add_u32_e32 v0, 0xc68, v55
	ds_write2_b32 v0, v14, v15 offset1:1
	v_add_u32_e32 v0, 0x1080, v55
	s_waitcnt vmcnt(3)
	ds_write2_b32 v0, v16, v17 offset1:1
	v_add_u32_e32 v0, 0x1088, v55
	ds_write2_b32 v0, v18, v19 offset1:1
	v_add_u32_e32 v0, 0x14a0, v55
	s_waitcnt vmcnt(2)
	ds_write2_b32 v0, v20, v21 offset1:1
	v_add_u32_e32 v0, 0x14a8, v55
	ds_write2_b32 v0, v22, v23 offset1:1
	v_add_u32_e32 v0, 0x18c0, v55
	s_waitcnt vmcnt(1)
	ds_write2_b32 v0, v24, v25 offset1:1
	v_add_u32_e32 v0, 0x18c8, v55
	ds_write2_b32 v0, v26, v27 offset1:1
	v_add_u32_e32 v0, 0x1ce0, v55
	s_waitcnt vmcnt(0)
	ds_write2_b32 v0, v28, v29 offset1:1
	v_add_u32_e32 v0, 0x1ce8, v55
	ds_write2_b32 v0, v30, v31 offset1:1
	s_waitcnt lgkmcnt(0)
	ds_read2_b32 v[6:7], v58 offset0:33 offset1:41
	ds_read2_b32 v[8:9], v58 offset1:8
	ds_read2_b32 v[10:11], v58 offset0:66 offset1:74
	ds_read2_b32 v[12:13], v58 offset0:99 offset1:107
	ds_read2_b32 v[14:15], v58 offset0:132 offset1:140
	ds_read2_b32 v[16:17], v58 offset0:165 offset1:173
	ds_read2_b32 v[18:19], v58 offset0:198 offset1:206
	ds_read2_b32 v[20:21], v58 offset0:231 offset1:239
	v_lshl_add_u64 v[0:1], v[36:37], 0, v[128:129]
	s_waitcnt lgkmcnt(6)
	v_cvt_pk_bf16_f32 v2, v8, v6
	v_or_b32_e32 v6, v54, v32
	v_mul_u32_u24_e32 v128, 0x2c00, v6
	v_or_b32_e32 v6, v54, v51
	s_waitcnt lgkmcnt(4)
	v_cvt_pk_bf16_f32 v3, v10, v12
	s_waitcnt lgkmcnt(2)
	v_cvt_pk_bf16_f32 v4, v14, v16
	s_waitcnt lgkmcnt(0)
	v_cvt_pk_bf16_f32 v5, v18, v20
	v_lshl_add_u64 v[22:23], v[0:1], 0, v[128:129]
	v_mul_u32_u24_e32 v128, 0x2c00, v6
	global_store_dwordx4 v[22:23], v[2:5], off
	s_nop 1
	v_cvt_pk_bf16_f32 v2, v9, v7
	v_cvt_pk_bf16_f32 v3, v11, v13
	v_cvt_pk_bf16_f32 v4, v15, v17
	v_cvt_pk_bf16_f32 v5, v19, v21
	v_lshl_add_u64 v[6:7], v[0:1], 0, v[128:129]
	global_store_dwordx4 v[6:7], v[2:5], off
	ds_read2_b32 v[6:7], v58 offset0:16 offset1:24
	ds_read2_b32 v[8:9], v58 offset0:49 offset1:57
	ds_read2_b32 v[10:11], v58 offset0:82 offset1:90
	ds_read2_b32 v[12:13], v58 offset0:115 offset1:123
	ds_read2_b32 v[14:15], v58 offset0:148 offset1:156
	ds_read2_b32 v[16:17], v58 offset0:181 offset1:189
	ds_read2_b32 v[18:19], v58 offset0:214 offset1:222
	ds_read2_b32 v[20:21], v58 offset0:247 offset1:255
	s_waitcnt lgkmcnt(6)
	v_cvt_pk_bf16_f32 v2, v6, v8
	v_or_b32_e32 v6, v54, v56
	v_mul_u32_u24_e32 v128, 0x2c00, v6
	v_or_b32_e32 v6, v54, v57
	s_waitcnt lgkmcnt(4)
	v_cvt_pk_bf16_f32 v3, v10, v12
	s_waitcnt lgkmcnt(2)
	v_cvt_pk_bf16_f32 v4, v14, v16
	s_waitcnt lgkmcnt(0)
	v_cvt_pk_bf16_f32 v5, v18, v20
	v_lshl_add_u64 v[22:23], v[0:1], 0, v[128:129]
	v_mul_u32_u24_e32 v128, 0x2c00, v6
	global_store_dwordx4 v[22:23], v[2:5], off
	v_lshl_add_u64 v[0:1], v[0:1], 0, v[128:129]
	s_nop 0
	v_cvt_pk_bf16_f32 v2, v7, v9
	v_cvt_pk_bf16_f32 v3, v11, v13
	v_cvt_pk_bf16_f32 v4, v15, v17
	v_cvt_pk_bf16_f32 v5, v19, v21
	global_store_dwordx4 v[0:1], v[2:5], off
	s_waitcnt lgkmcnt(0)

; #define LAS __attribute__((address_space(3)))
; template <int KIND>
; DI void transpose_item(const float* W, int K, int N, bf16_t* WT, int ldk, const float* g0, const float* g1, const float* g2, LAS float* scr, int item, int lane) {
;     const int nblk = N / 32, kb = item / nblk, nb = item % nblk, k0 = 64 * kb, n0 = 32 * nb;
;     f32x4 tv[8];
; #pragma unroll
;     for (int i = 0; i < 8; ++i) tv[i] = *(const f32x4*)(W + (size_t)(k0 + 8 * i + (lane >> 3)) * N + n0 + 4 * (lane & 7));
;     ...
;         if (KIND == 4) gn = k < 1024 ? g0[k] : (k < 1536 ? g1[k - 1024] : g2[k - 1536]);
; DI void convert_weights(PP p, LAS unsigned char* lds, int l, int worker, int nworkers) {
;     ...
;         if (r < I_O) { transpose_item<4>(p->in[20] + (size_t)l * 2048 * 2048, 2048, 2048, (bf16_t*)(wl + W_O), 2048, p->in[17] + l * 1024, p->in[18] + l * 512, p->in[19] + l * 512, scr, r, lane); continue; } r -= I_O;
.LBB0_1393:
	s_andn2_saveexec_b64 s[14:15], s[6:7]
	s_cbranch_execz .LBB0_1459
	s_load_dwordx8 s[48:55], s[8:9], 0x88
	v_add_u32_e32 v0, 0xfffe2800, v50
	v_add_u32_e32 v63, 0xfffff140, v62
	v_and_b32_e32 v53, 0x7e0, v0
	v_and_b32_e32 v64, 0x7c0, v63
	s_waitcnt lgkmcnt(0)
	s_add_u32 s6, s54, s42
	s_addc_u32 s7, s55, s43
	v_lshlrev_b32_e32 v128, 2, v53
	v_or_b32_e32 v65, v64, v32
	v_lshl_add_u64 v[0:1], s[6:7], 0, v[128:129]
	v_lshlrev_b32_e32 v128, 2, v34
	v_lshl_add_u64 v[0:1], v[0:1], 0, v[128:129]
	v_lshlrev_b32_e32 v128, 13, v65
	v_lshl_add_u64 v[0:1], v[0:1], 0, v[128:129]
	s_mov_b32 s4, 0x10000
	v_add_co_u32_e32 v2, vcc, s4, v0
	s_mov_b32 s4, 0x20000
	s_nop 0
	v_addc_co_u32_e32 v3, vcc, 0, v1, vcc
	global_load_dwordx4 v[28:31], v[0:1], off nt
	global_load_dwordx4 v[24:27], v[2:3], off nt
	v_add_co_u32_e32 v2, vcc, s4, v0
	s_mov_b32 s4, 0x30000
	s_nop 0
	v_addc_co_u32_e32 v3, vcc, 0, v1, vcc
	v_add_co_u32_e32 v4, vcc, s4, v0
	s_add_u32 s16, s48, s60
	s_nop 0
	v_addc_co_u32_e32 v5, vcc, 0, v1, vcc
	global_load_dwordx4 v[20:23], v[2:3], off nt
	global_load_dwordx4 v[16:19], v[4:5], off nt
	v_add_co_u32_e32 v2, vcc, s89, v0
	s_addc_u32 s17, s49, s61
	s_nop 0
	v_addc_co_u32_e32 v3, vcc, 0, v1, vcc
	v_add_co_u32_e32 v4, vcc, 0x50000, v0
	s_lshl_b64 s[6:7], s[44:45], 2
	s_nop 0
	v_addc_co_u32_e32 v5, vcc, 0, v1, vcc
	global_load_dwordx4 v[12:15], v[2:3], off nt
	global_load_dwordx4 v[8:11], v[4:5], off nt
	v_add_co_u32_e32 v2, vcc, 0x60000, v0
	s_add_u32 s18, s50, s6
	s_nop 0
	v_addc_co_u32_e32 v3, vcc, 0, v1, vcc
	v_add_co_u32_e32 v0, vcc, 0x70000, v0
	s_addc_u32 s19, s51, s7
	s_nop 0
	v_addc_co_u32_e32 v1, vcc, 0, v1, vcc
	global_load_dwordx4 v[4:7], v[2:3], off nt
	s_nop 0
	global_load_dwordx4 v[0:3], v[0:1], off nt
	s_movk_i32 s4, 0x400
	s_add_u32 s22, s52, s6
	v_cmp_gt_u32_e32 vcc, s4, v63
	s_movk_i32 s4, 0x3ff
	s_addc_u32 s23, s53, s7
	v_cmp_lt_u32_e64 s[48:49], s4, v63
	s_and_saveexec_b64 s[6:7], s[48:49]
	s_xor_b64 s[34:35], exec, s[6:7]
	s_cbranch_execz .LBB0_1400
	s_movk_i32 s4, 0x5ff
	v_cmp_lt_u32_e64 s[6:7], s4, v63
	s_and_saveexec_b64 s[40:41], s[6:7]
	s_xor_b64 s[6:7], exec, s[40:41]
	v_lshlrev_b32_e32 v128, 2, v65
	s_movk_i32 s40, 0xe800
	v_lshl_add_u64 v[54:55], s[22:23], 0, v[128:129]
	s_mov_b32 s41, -1
	v_lshl_add_u64 v[54:55], v[54:55], 0, s[40:41]
	s_andn2_saveexec_b64 s[6:7], s[6:7]
	v_lshlrev_b32_e32 v128, 2, v65
	s_movk_i32 s40, 0xf000
	v_lshl_add_u64 v[54:55], s[18:19], 0, v[128:129]
	s_mov_b32 s41, -1
	v_lshl_add_u64 v[54:55], v[54:55], 0, s[40:41]
	s_or_b64 exec, exec, s[6:7]

; #define LAS __attribute__((address_space(3)))
; DI unsigned cvtpk(float lo, float hi) { f32x2 v = {lo, hi}; bf16x2_t b = __builtin_convertvector(v, bf16x2_t); return __builtin_bit_cast(unsigned, b); }
; template <int KIND> DI int map_n(int n) {
;     ...
;     if (KIND == 3) return n < 512 ? 2 * n : 2 * (n - 512) + 1;
; template <int KIND>
; DI void transpose_item(const float* W, int K, int N, bf16_t* WT, int ldk, const float* g0, const float* g1, const float* g2, LAS float* scr, int item, int lane) {
;     const int nblk = N / 32, kb = item / nblk, nb = item % nblk, k0 = 64 * kb, n0 = 32 * nb;
;     f32x4 tv[8];
; #pragma unroll
;     for (int i = 0; i < 8; ++i) tv[i] = *(const f32x4*)(W + (size_t)(k0 + 8 * i + (lane >> 3)) * N + n0 + 4 * (lane & 7));
; #pragma unroll
;     for (int i = 0; i < 8; ++i) {
;         const int kk = 8 * i + (lane >> 3), k = k0 + kk;
;         float gn = 1.f;
;         if (KIND == 0 || KIND == 1 || KIND == 2 || KIND == 5 || KIND == 6) gn = g0[k];
;         if (KIND == 4) gn = k < 1024 ? g0[k] : (k < 1536 ? g1[k - 1024] : g2[k - 1536]);
;         LAS float* d = scr + kk * 33 + 4 * (lane & 7);
;         d[0] = tv[i][0] * gn; d[1] = tv[i][1] * gn; d[2] = tv[i][2] * gn; d[3] = tv[i][3] * gn;
;     }
;     asm volatile("s_waitcnt lgkmcnt(0)" ::: "memory");
;     int kd0 = k0;
;     if (KIND == 4) kd0 = k0 < 1024 ? k0 + 512 : (k0 < 1536 ? k0 - 1024 : k0);
;     const int c = lane & 7;
; #pragma unroll
;     for (int j = 0; j < 4; ++j) { const int n = (lane >> 3) + 8 * j; const LAS float* s = scr + (8 * c) * 33 + n;
;         u32x4 o; o.x = cvtpk(s[0 * 33], s[1 * 33]); o.y = cvtpk(s[2 * 33], s[3 * 33]); o.z = cvtpk(s[4 * 33], s[5 * 33]); o.w = cvtpk(s[6 * 33], s[7 * 33]);
;         *(u32x4*)(WT + (size_t)map_n<KIND>(n0 + n) * ldk + kd0 + 8 * c) = o; }
;     asm volatile("s_waitcnt lgkmcnt(0)" ::: "memory");
; }
; DI void convert_weights(PP p, LAS unsigned char* lds, int l, int worker, int nworkers) {
;     ...
;         if (r < I_GLU) { transpose_item<3>(p->in[15] + (size_t)l * 512 * 1024, 512, 1024, (bf16_t*)(wl + W_GLU), 512, nullptr, nullptr, nullptr, scr, r, lane); continue; } r -= I_GLU;
.LBB0_1460:
	s_andn2_saveexec_b64 s[6:7], s[70:71]
	s_cbranch_execz .LBB0_1462
	s_load_dwordx2 s[14:15], s[8:9], 0x78
	v_add_u32_e32 v0, 0xfffe4800, v50
	v_and_b32_e32 v54, 0x3e0, v0
	v_and_b32_e32 v53, 0x1c0, v61
	v_lshlrev_b32_e32 v128, 2, v54
	s_waitcnt lgkmcnt(0)
	s_add_u32 s14, s14, s56
	s_addc_u32 s15, s15, s57
	v_or_b32_e32 v2, v53, v32
	v_lshl_add_u64 v[0:1], s[14:15], 0, v[128:129]
	v_lshlrev_b32_e32 v128, 2, v34
	v_lshl_add_u64 v[0:1], v[0:1], 0, v[128:129]
	v_lshlrev_b32_e32 v128, 12, v2
	v_lshl_add_u64 v[28:29], v[0:1], 0, v[128:129]
	s_mov_b32 s4, 0x8000
	v_add_co_u32_e32 v4, vcc, s4, v28
	global_load_dwordx4 v[0:3], v[28:29], off nt
	s_nop 0
	v_addc_co_u32_e32 v5, vcc, 0, v29, vcc
	s_mov_b32 s4, 0x10000
	global_load_dwordx4 v[4:7], v[4:5], off nt
	v_add_co_u32_e32 v8, vcc, s4, v28
	s_mov_b32 s4, 0x18000
	s_nop 0
	v_addc_co_u32_e32 v9, vcc, 0, v29, vcc
	global_load_dwordx4 v[8:11], v[8:9], off nt
	v_add_co_u32_e32 v12, vcc, s4, v28
	s_mov_b32 s4, 0x20000
	s_nop 0
	v_addc_co_u32_e32 v13, vcc, 0, v29, vcc
	global_load_dwordx4 v[12:15], v[12:13], off nt
	v_add_co_u32_e32 v16, vcc, s4, v28
	s_mov_b32 s4, 0x28000
	s_nop 0
	v_addc_co_u32_e32 v17, vcc, 0, v29, vcc
	global_load_dwordx4 v[16:19], v[16:17], off nt
	v_add_co_u32_e32 v20, vcc, s4, v28
	s_mov_b32 s4, 0x30000
	s_nop 0
	v_addc_co_u32_e32 v21, vcc, 0, v29, vcc
	global_load_dwordx4 v[20:23], v[20:21], off nt
	v_add_co_u32_e32 v24, vcc, s4, v28
	s_mov_b32 s4, 0x38000
	s_nop 0
	v_addc_co_u32_e32 v25, vcc, 0, v29, vcc
	global_load_dwordx4 v[24:27], v[24:25], off nt
	v_add_co_u32_e32 v28, vcc, s4, v28
	v_add_u32_e32 v55, v33, v35
	s_nop 0
	v_addc_co_u32_e32 v29, vcc, 0, v29, vcc
	global_load_dwordx4 v[28:31], v[28:29], off nt
	s_movk_i32 s4, 0x200
	v_cmp_gt_u32_e32 vcc, s4, v54
	v_lshlrev_b32_e32 v128, 1, v53
	s_waitcnt vmcnt(7)
	ds_write2_b32 v55, v0, v1 offset1:1
	ds_write2_b32 v55, v2, v3 offset0:2 offset1:3
	v_add_u32_e32 v0, 0x420, v55
	s_waitcnt vmcnt(6)
	ds_write2_b32 v0, v4, v5 offset1:1
	v_add_u32_e32 v0, 0x428, v55
	ds_write2_b32 v0, v6, v7 offset1:1
	v_add_u32_e32 v0, 0x840, v55
	s_waitcnt vmcnt(5)
	ds_write2_b32 v0, v8, v9 offset1:1
	v_add_u32_e32 v0, 0x848, v55
	ds_write2_b32 v0, v10, v11 offset1:1
	v_add_u32_e32 v0, 0xc60, v55
	s_waitcnt vmcnt(4)
	ds_write2_b32 v0, v12, v13 offset1:1
	v_add_u32_e32 v0, 0xc68, v55
	ds_write2_b32 v0, v14, v15 offset1:1
	v_add_u32_e32 v0, 0x1080, v55
	s_waitcnt vmcnt(3)
	ds_write2_b32 v0, v16, v17 offset1:1
	v_add_u32_e32 v0, 0x1088, v55
	ds_write2_b32 v0, v18, v19 offset1:1
	v_add_u32_e32 v0, 0x14a0, v55
	s_waitcnt vmcnt(2)
	ds_write2_b32 v0, v20, v21 offset1:1
	v_add_u32_e32 v0, 0x14a8, v55
	ds_write2_b32 v0, v22, v23 offset1:1
	v_add_u32_e32 v0, 0x18c0, v55
	s_waitcnt vmcnt(1)
	ds_write2_b32 v0, v24, v25 offset1:1
	v_add_u32_e32 v0, 0x18c8, v55
	ds_write2_b32 v0, v26, v27 offset1:1
	v_add_u32_e32 v0, 0x1ce0, v55
	s_waitcnt vmcnt(0)
	ds_write2_b32 v0, v28, v29 offset1:1
	v_add_u32_e32 v0, 0x1ce8, v55
	ds_write2_b32 v0, v30, v31 offset1:1
	s_waitcnt lgkmcnt(0)
	ds_read2_b32 v[6:7], v58 offset0:33 offset1:41
	ds_read2_b32 v[8:9], v58 offset1:8
	ds_read2_b32 v[10:11], v58 offset0:66 offset1:74
	ds_read2_b32 v[12:13], v58 offset0:99 offset1:107
	ds_read2_b32 v[14:15], v58 offset0:132 offset1:140
	ds_read2_b32 v[16:17], v58 offset0:165 offset1:173
	ds_read2_b32 v[18:19], v58 offset0:198 offset1:206
	ds_read2_b32 v[20:21], v58 offset0:231 offset1:239
	v_lshl_add_u64 v[0:1], v[42:43], 0, v[128:129]
	s_waitcnt lgkmcnt(6)
	v_cvt_pk_bf16_f32 v2, v8, v6
	v_or_b32_e32 v6, v54, v32
	v_lshlrev_b32_e32 v6, 1, v6
	v_add_u32_e32 v8, 0xfffffc01, v6
	v_cndmask_b32_e32 v22, v8, v6, vcc
	v_ashrrev_i32_e32 v23, 31, v22
	v_lshlrev_b64 v[22:23], 10, v[22:23]
	v_or_b32_e32 v6, v54, v51
	s_waitcnt lgkmcnt(4)
	v_cvt_pk_bf16_f32 v3, v10, v12
	s_waitcnt lgkmcnt(2)
	v_cvt_pk_bf16_f32 v4, v14, v16
	s_waitcnt lgkmcnt(0)
	v_cvt_pk_bf16_f32 v5, v18, v20
	v_lshl_add_u64 v[22:23], v[0:1], 0, v[22:23]
	v_lshlrev_b32_e32 v6, 1, v6
	global_store_dwordx4 v[22:23], v[2:5], off
	s_nop 1
	v_cvt_pk_bf16_f32 v2, v9, v7
	v_add_u32_e32 v7, 0xfffffc01, v6
	v_cndmask_b32_e32 v6, v7, v6, vcc
	v_ashrrev_i32_e32 v7, 31, v6
	v_lshlrev_b64 v[6:7], 10, v[6:7]
	v_cvt_pk_bf16_f32 v3, v11, v13
	v_cvt_pk_bf16_f32 v4, v15, v17
	v_cvt_pk_bf16_f32 v5, v19, v21
	v_lshl_add_u64 v[6:7], v[0:1], 0, v[6:7]
	global_store_dwordx4 v[6:7], v[2:5], off
	ds_read2_b32 v[6:7], v58 offset0:49 offset1:57
	ds_read2_b32 v[8:9], v58 offset0:16 offset1:24
	ds_read2_b32 v[10:11], v58 offset0:82 offset1:90
	ds_read2_b32 v[12:13], v58 offset0:115 offset1:123
	ds_read2_b32 v[14:15], v58 offset0:148 offset1:156
	ds_read2_b32 v[16:17], v58 offset0:181 offset1:189
	ds_read2_b32 v[18:19], v58 offset0:214 offset1:222
	ds_read2_b32 v[20:21], v58 offset0:247 offset1:255
	s_waitcnt lgkmcnt(6)
	v_cvt_pk_bf16_f32 v2, v8, v6
	v_or_b32_e32 v6, v54, v56
	v_lshlrev_b32_e32 v6, 1, v6
	v_add_u32_e32 v8, 0xfffffc01, v6
	v_cndmask_b32_e32 v22, v8, v6, vcc
	v_ashrrev_i32_e32 v23, 31, v22
	v_lshlrev_b64 v[22:23], 10, v[22:23]
	v_or_b32_e32 v6, v54, v57
	s_waitcnt lgkmcnt(4)
	v_cvt_pk_bf16_f32 v3, v10, v12
	s_waitcnt lgkmcnt(2)
	v_cvt_pk_bf16_f32 v4, v14, v16
	s_waitcnt lgkmcnt(0)
	v_cvt_pk_bf16_f32 v5, v18, v20
	v_lshl_add_u64 v[22:23], v[0:1], 0, v[22:23]
	v_lshlrev_b32_e32 v6, 1, v6
	global_store_dwordx4 v[22:23], v[2:5], off
	s_nop 1
	v_cvt_pk_bf16_f32 v2, v9, v7
	v_add_u32_e32 v7, 0xfffffc01, v6
	v_cndmask_b32_e32 v6, v7, v6, vcc
	v_ashrrev_i32_e32 v7, 31, v6
	v_lshlrev_b64 v[6:7], 10, v[6:7]
	v_cvt_pk_bf16_f32 v3, v11, v13
	v_cvt_pk_bf16_f32 v4, v15, v17
	v_cvt_pk_bf16_f32 v5, v19, v21
	v_lshl_add_u64 v[0:1], v[0:1], 0, v[6:7]
	global_store_dwordx4 v[0:1], v[2:5], off
	s_waitcnt lgkmcnt(0)

; #define LAS __attribute__((address_space(3)))
; DI unsigned cvtpk(float lo, float hi) { f32x2 v = {lo, hi}; bf16x2_t b = __builtin_convertvector(v, bf16x2_t); return __builtin_bit_cast(unsigned, b); }
; template <int KIND>
; DI void transpose_item(const float* W, int K, int N, bf16_t* WT, int ldk, const float* g0, const float* g1, const float* g2, LAS float* scr, int item, int lane) {
;     const int nblk = N / 32, kb = item / nblk, nb = item % nblk, k0 = 64 * kb, n0 = 32 * nb;
;     f32x4 tv[8];
; #pragma unroll
;     for (int i = 0; i < 8; ++i) tv[i] = *(const f32x4*)(W + (size_t)(k0 + 8 * i + (lane >> 3)) * N + n0 + 4 * (lane & 7));
; #pragma unroll
;     for (int i = 0; i < 8; ++i) {
;         const int kk = 8 * i + (lane >> 3), k = k0 + kk;
;         float gn = 1.f;
;         if (KIND == 0 || KIND == 1 || KIND == 2 || KIND == 5 || KIND == 6) gn = g0[k];
;         if (KIND == 4) gn = k < 1024 ? g0[k] : (k < 1536 ? g1[k - 1024] : g2[k - 1536]);
;         LAS float* d = scr + kk * 33 + 4 * (lane & 7);
;         d[0] = tv[i][0] * gn; d[1] = tv[i][1] * gn; d[2] = tv[i][2] * gn; d[3] = tv[i][3] * gn;
;     }
;     asm volatile("s_waitcnt lgkmcnt(0)" ::: "memory");
;     int kd0 = k0;
;     if (KIND == 4) kd0 = k0 < 1024 ? k0 + 512 : (k0 < 1536 ? k0 - 1024 : k0);
;     const int c = lane & 7;
; #pragma unroll
;     for (int j = 0; j < 4; ++j) { const int n = (lane >> 3) + 8 * j; const LAS float* s = scr + (8 * c) * 33 + n;
;         u32x4 o; o.x = cvtpk(s[0 * 33], s[1 * 33]); o.y = cvtpk(s[2 * 33], s[3 * 33]); o.z = cvtpk(s[4 * 33], s[5 * 33]); o.w = cvtpk(s[6 * 33], s[7 * 33]);
;         *(u32x4*)(WT + (size_t)map_n<KIND>(n0 + n) * ldk + kd0 + 8 * c) = o; }
;     asm volatile("s_waitcnt lgkmcnt(0)" ::: "memory");
; }
; DI void convert_weights(PP p, LAS unsigned char* lds, int l, int worker, int nworkers) {
;     ...
;         if (r < I_UKV) { transpose_item<2>(p->in[6] + (size_t)l * 256 * 2048, 256, 2048, (bf16_t*)(wl + W_UKV), 256, p->in[5] + l * 256, nullptr, nullptr, scr, r, lane); continue; } r -= I_UKV;
.LBB0_1463:
	s_andn2_saveexec_b64 s[6:7], s[68:69]
	s_cbranch_execz .LBB0_1465
	s_load_dwordx4 s[16:19], s[8:9], 0x28
	v_add_u32_e32 v0, 0xfffff340, v62
	v_and_b32_e32 v13, 0xc0, v0
	v_add_u32_e32 v0, 0xfffe6800, v50
	v_and_b32_e32 v12, 0x7e0, v0
	s_waitcnt lgkmcnt(0)
	s_add_u32 s18, s18, s56
	s_addc_u32 s19, s19, s57
	v_lshlrev_b32_e32 v128, 2, v12
	v_or_b32_e32 v30, v13, v32
	v_lshl_add_u64 v[0:1], s[18:19], 0, v[128:129]
	v_lshlrev_b32_e32 v128, 2, v34
	s_add_u32 s14, s16, s62
	v_lshl_add_u64 v[0:1], v[0:1], 0, v[128:129]
	v_lshlrev_b32_e32 v128, 13, v30
	s_addc_u32 s15, s17, s63
	v_lshl_add_u64 v[0:1], v[0:1], 0, v[128:129]
	v_lshlrev_b32_e32 v31, 2, v30
	global_load_dwordx4 v[14:17], v[0:1], off nt
	global_load_dword v30, v31, s[14:15]
	s_mov_b32 s4, 0x10000
	v_add_co_u32_e32 v2, vcc, s4, v0
	v_add_u32_e32 v53, v33, v35
	s_nop 0
	v_addc_co_u32_e32 v3, vcc, 0, v1, vcc
	global_load_dwordx4 v[18:21], v[2:3], off nt
	s_mov_b32 s4, 0x20000
	v_add_co_u32_e32 v2, vcc, s4, v0
	s_mov_b32 s4, 0x30000
	s_nop 0
	v_addc_co_u32_e32 v3, vcc, 0, v1, vcc
	global_load_dwordx4 v[22:25], v[2:3], off nt
	v_add_co_u32_e32 v2, vcc, s4, v0
	s_mov_b32 s4, 0x50000
	s_nop 0
	v_addc_co_u32_e32 v3, vcc, 0, v1, vcc
	global_load_dwordx4 v[26:29], v[2:3], off nt
	v_add_co_u32_e32 v2, vcc, s89, v0
	v_lshlrev_b32_e32 v128, 1, v13
	s_nop 0
	v_addc_co_u32_e32 v3, vcc, 0, v1, vcc
	global_load_dwordx4 v[64:67], v[2:3], off nt
	v_add_co_u32_e32 v2, vcc, s4, v0
	s_mov_b32 s4, 0x60000
	s_nop 0
	v_addc_co_u32_e32 v3, vcc, 0, v1, vcc
	global_load_dwordx4 v[8:11], v[2:3], off nt
	v_add_co_u32_e32 v2, vcc, s4, v0
	s_mov_b32 s4, 0x70000
	s_nop 0
	v_addc_co_u32_e32 v3, vcc, 0, v1, vcc
	global_load_dwordx4 v[4:7], v[2:3], off nt
	v_add_co_u32_e32 v0, vcc, s4, v0
	s_waitcnt vmcnt(6)
	v_pk_mul_f32 v[14:15], v[14:15], v[30:31] op_sel_hi:[1,0]
	ds_write2_b32 v53, v14, v15 offset1:1
	v_pk_mul_f32 v[14:15], v[16:17], v[30:31] op_sel_hi:[1,0]
	ds_write2_b32 v53, v14, v15 offset0:2 offset1:3
	global_load_dword v14, v31, s[14:15] offset:32
	v_addc_co_u32_e32 v1, vcc, 0, v1, vcc
	global_load_dwordx4 v[0:3], v[0:1], off nt
	s_waitcnt vmcnt(1)
	v_pk_mul_f32 v[16:17], v[18:19], v[14:15] op_sel_hi:[1,0]
	v_add_u32_e32 v15, 0x420, v53
	ds_write2_b32 v15, v16, v17 offset1:1
	v_pk_mul_f32 v[14:15], v[20:21], v[14:15] op_sel_hi:[1,0]
	v_add_u32_e32 v16, 0x428, v53
	ds_write2_b32 v16, v14, v15 offset1:1
	global_load_dword v14, v31, s[14:15] offset:64
	v_add_u32_e32 v18, v33, v59
	s_waitcnt vmcnt(0)
	v_pk_mul_f32 v[16:17], v[22:23], v[14:15] op_sel_hi:[1,0]
	v_add_u32_e32 v15, 0x840, v53
	ds_write2_b32 v15, v16, v17 offset1:1
	v_pk_mul_f32 v[14:15], v[24:25], v[14:15] op_sel_hi:[1,0]
	v_add_u32_e32 v16, 0x848, v53
	ds_write2_b32 v16, v14, v15 offset1:1
	global_load_dword v14, v31, s[14:15] offset:96
	s_waitcnt vmcnt(0)
	v_pk_mul_f32 v[16:17], v[26:27], v[14:15] op_sel_hi:[1,0]
	v_add_u32_e32 v15, 0xc60, v53
	ds_write2_b32 v15, v16, v17 offset1:1
	v_pk_mul_f32 v[14:15], v[28:29], v[14:15] op_sel_hi:[1,0]
	v_add_u32_e32 v16, 0xc68, v53
	ds_write2_b32 v16, v14, v15 offset1:1
	global_load_dword v14, v31, s[14:15] offset:128
	s_waitcnt vmcnt(0)
	v_pk_mul_f32 v[16:17], v[64:65], v[14:15] op_sel_hi:[1,0]
	v_pk_mul_f32 v[14:15], v[66:67], v[14:15] op_sel_hi:[1,0]
	ds_write2_b32 v18, v14, v15 offset0:2 offset1:3
	global_load_dword v14, v31, s[14:15] offset:160
	ds_write2_b32 v18, v16, v17 offset1:1
	s_waitcnt vmcnt(0)
	v_pk_mul_f32 v[8:9], v[8:9], v[14:15] op_sel_hi:[1,0]
	v_add_u32_e32 v15, 0x420, v18
	ds_write2_b32 v15, v8, v9 offset1:1
	v_pk_mul_f32 v[8:9], v[10:11], v[14:15] op_sel_hi:[1,0]
	v_add_u32_e32 v10, 0x428, v18
	ds_write2_b32 v10, v8, v9 offset1:1
	global_load_dword v8, v31, s[14:15] offset:192
	s_waitcnt vmcnt(0)
	v_pk_mul_f32 v[4:5], v[4:5], v[8:9] op_sel_hi:[1,0]
	v_add_u32_e32 v9, 0x840, v18
	ds_write2_b32 v9, v4, v5 offset1:1
	v_pk_mul_f32 v[4:5], v[6:7], v[8:9] op_sel_hi:[1,0]
	v_add_u32_e32 v6, 0x848, v18
	ds_write2_b32 v6, v4, v5 offset1:1
	global_load_dword v4, v31, s[14:15] offset:224
	s_waitcnt vmcnt(0)
	v_pk_mul_f32 v[0:1], v[0:1], v[4:5] op_sel_hi:[1,0]
	v_add_u32_e32 v5, 0xc60, v18
	ds_write2_b32 v5, v0, v1 offset1:1
	v_pk_mul_f32 v[0:1], v[2:3], v[4:5] op_sel_hi:[1,0]
	v_add_u32_e32 v2, 0xc68, v18
	ds_write2_b32 v2, v0, v1 offset1:1
	s_waitcnt lgkmcnt(0)
	ds_read2_b32 v[6:7], v58 offset0:33 offset1:41
	ds_read2_b32 v[8:9], v58 offset1:8
	ds_read2_b32 v[10:11], v58 offset0:66 offset1:74
	ds_read2_b32 v[14:15], v58 offset0:99 offset1:107
	ds_read2_b32 v[16:17], v58 offset0:132 offset1:140
	ds_read2_b32 v[18:19], v58 offset0:165 offset1:173
	ds_read2_b32 v[20:21], v58 offset0:198 offset1:206
	ds_read2_b32 v[22:23], v58 offset0:231 offset1:239
	v_lshl_add_u64 v[4:5], v[44:45], 0, v[128:129]
	s_waitcnt lgkmcnt(6)
	v_cvt_pk_bf16_f32 v0, v8, v6
	v_or_b32_e32 v6, v12, v32
	v_lshlrev_b32_e32 v128, 9, v6
	v_or_b32_e32 v6, v12, v51
	s_waitcnt lgkmcnt(4)
	v_cvt_pk_bf16_f32 v1, v10, v14
	s_waitcnt lgkmcnt(2)
	v_cvt_pk_bf16_f32 v2, v16, v18
	s_waitcnt lgkmcnt(0)
	v_cvt_pk_bf16_f32 v3, v20, v22
	v_lshl_add_u64 v[24:25], v[4:5], 0, v[128:129]
	v_lshlrev_b32_e32 v128, 9, v6
	global_store_dwordx4 v[24:25], v[0:3], off
	s_nop 1
	v_cvt_pk_bf16_f32 v0, v9, v7
	v_cvt_pk_bf16_f32 v1, v11, v15
	v_cvt_pk_bf16_f32 v2, v17, v19
	v_cvt_pk_bf16_f32 v3, v21, v23
	v_lshl_add_u64 v[6:7], v[4:5], 0, v[128:129]
	global_store_dwordx4 v[6:7], v[0:3], off
	ds_read2_b32 v[6:7], v58 offset0:49 offset1:57
	ds_read2_b32 v[8:9], v58 offset0:16 offset1:24
	ds_read2_b32 v[10:11], v58 offset0:82 offset1:90
	ds_read2_b32 v[14:15], v58 offset0:115 offset1:123
	ds_read2_b32 v[16:17], v58 offset0:148 offset1:156
	ds_read2_b32 v[18:19], v58 offset0:181 offset1:189
	ds_read2_b32 v[20:21], v58 offset0:214 offset1:222
	ds_read2_b32 v[22:23], v58 offset0:247 offset1:255
	s_waitcnt lgkmcnt(6)
	v_cvt_pk_bf16_f32 v0, v8, v6
	v_or_b32_e32 v6, v12, v56
	v_lshlrev_b32_e32 v128, 9, v6
	v_or_b32_e32 v6, v12, v57
	s_waitcnt lgkmcnt(4)
	v_cvt_pk_bf16_f32 v1, v10, v14
	s_waitcnt lgkmcnt(2)
	v_cvt_pk_bf16_f32 v2, v16, v18
	s_waitcnt lgkmcnt(0)
	v_cvt_pk_bf16_f32 v3, v20, v22
	v_lshl_add_u64 v[24:25], v[4:5], 0, v[128:129]
	v_lshlrev_b32_e32 v128, 9, v6
	global_store_dwordx4 v[24:25], v[0:3], off
	v_lshl_add_u64 v[4:5], v[4:5], 0, v[128:129]
	s_nop 0
	v_cvt_pk_bf16_f32 v0, v9, v7
	v_cvt_pk_bf16_f32 v1, v11, v15
	v_cvt_pk_bf16_f32 v2, v17, v19
	v_cvt_pk_bf16_f32 v3, v21, v23
	global_store_dwordx4 v[4:5], v[0:3], off
	s_waitcnt lgkmcnt(0)

; #define LAS __attribute__((address_space(3)))
; template <int KIND>
; DI void transpose_item(const float* W, int K, int N, bf16_t* WT, int ldk, const float* g0, const float* g1, const float* g2, LAS float* scr, int item, int lane) {
;     const int nblk = N / 32, kb = item / nblk, nb = item % nblk, k0 = 64 * kb, n0 = 32 * nb;
;     f32x4 tv[8];
; #pragma unroll
;     for (int i = 0; i < 8; ++i) tv[i] = *(const f32x4*)(W + (size_t)(k0 + 8 * i + (lane >> 3)) * N + n0 + 4 * (lane & 7));
; #pragma unroll
;     for (int i = 0; i < 8; ++i) {
;         const int kk = 8 * i + (lane >> 3), k = k0 + kk;
;         float gn = 1.f;
;         if (KIND == 0 || KIND == 1 || KIND == 2 || KIND == 5 || KIND == 6) gn = g0[k];
;         if (KIND == 4) gn = k < 1024 ? g0[k] : (k < 1536 ? g1[k - 1024] : g2[k - 1536]);
;         LAS float* d = scr + kk * 33 + 4 * (lane & 7);
;         d[0] = tv[i][0] * gn; d[1] = tv[i][1] * gn; d[2] = tv[i][2] * gn; d[3] = tv[i][3] * gn;
;     }
;     asm volatile("s_waitcnt lgkmcnt(0)" ::: "memory");
; DI void convert_weights(PP p, LAS unsigned char* lds, int l, int worker, int nworkers) {
;     ...
;         if (r < I_UQ) { transpose_item<1>(p->in[4] + (size_t)l * 512 * 1536, 512, 1536, (bf16_t*)(wl + W_UQ), 512, p->in[3] + l * 512, nullptr, nullptr, scr, r, lane); continue; } r -= I_UQ;
.LBB0_1466:
	s_andn2_saveexec_b64 s[14:15], s[66:67]
	s_cbranch_execz .LBB0_1468
	s_load_dwordx4 s[16:19], s[8:9], 0x18
	v_add_u16_e32 v0, 0xf4c0, v62
	v_mul_u32_u24_e32 v1, 0xaaab, v0
	v_lshrrev_b32_e32 v1, 21, v1
	v_readlane_b32 s6, v255, 1
	v_mul_lo_u16_e32 v2, 48, v1
	s_mul_i32 s4, s6, 0x300000
	v_sub_u16_e32 v0, v0, v2
	s_waitcnt lgkmcnt(0)
	s_add_u32 s18, s18, s4
	s_mul_hi_u32 s4, s6, 0x300000
	v_lshlrev_b16_e32 v13, 6, v1
	v_lshlrev_b16_e32 v12, 5, v0
	v_readlane_b32 s7, v255, 2
	s_addc_u32 s19, s19, s4
	v_or_b32_e32 v30, v32, v13
	v_lshlrev_b32_e32 v128, 2, v12
	s_lshl_b64 s[6:7], s[44:45], 2
	v_lshl_add_u64 v[0:1], s[18:19], 0, v[128:129]
	v_lshlrev_b32_e32 v128, 2, v34
	v_mul_u32_u24_e32 v2, 0x600, v30
	s_add_u32 s6, s16, s6
	v_lshl_add_u64 v[0:1], v[0:1], 0, v[128:129]
	v_lshlrev_b32_e32 v128, 2, v2
	s_addc_u32 s7, s17, s7
	v_lshl_add_u64 v[0:1], v[0:1], 0, v[128:129]
	v_lshlrev_b32_e32 v31, 2, v30
	global_load_dwordx4 v[14:17], v[0:1], off nt
	global_load_dword v30, v31, s[6:7]
	s_mov_b32 s4, 0xc000
	v_add_co_u32_e32 v2, vcc, s4, v0
	v_add_u32_e32 v53, v33, v35
	s_nop 0
	v_addc_co_u32_e32 v3, vcc, 0, v1, vcc
	global_load_dwordx4 v[18:21], v[2:3], off nt
	s_mov_b32 s4, 0x18000
	v_add_co_u32_e32 v2, vcc, s4, v0
	s_mov_b32 s4, 0x24000
	s_nop 0
	v_addc_co_u32_e32 v3, vcc, 0, v1, vcc
	global_load_dwordx4 v[22:25], v[2:3], off nt
	v_add_co_u32_e32 v2, vcc, s4, v0
	s_mov_b32 s4, 0x30000
	s_nop 0
	v_addc_co_u32_e32 v3, vcc, 0, v1, vcc
	global_load_dwordx4 v[26:29], v[2:3], off nt
	v_add_co_u32_e32 v2, vcc, s4, v0
	s_mov_b32 s4, 0x3c000
	s_nop 0
	v_addc_co_u32_e32 v3, vcc, 0, v1, vcc
	global_load_dwordx4 v[64:67], v[2:3], off nt
	v_add_co_u32_e32 v2, vcc, s4, v0
	s_mov_b32 s4, 0x48000
	s_nop 0
	v_addc_co_u32_e32 v3, vcc, 0, v1, vcc
	global_load_dwordx4 v[8:11], v[2:3], off nt
	v_add_co_u32_e32 v2, vcc, s4, v0
	s_mov_b32 s4, 0x54000
	s_nop 0
	v_addc_co_u32_e32 v3, vcc, 0, v1, vcc
	global_load_dwordx4 v[4:7], v[2:3], off nt
	v_add_co_u32_e32 v0, vcc, s4, v0
	s_movk_i32 s16, 0xa0
	s_nop 0
	v_addc_co_u32_e32 v1, vcc, 0, v1, vcc
	global_load_dwordx4 v[0:3], v[0:1], off nt
	v_lshlrev_b32_e32 v128, 1, v13
	s_movk_i32 s4, 0x80
	s_waitcnt vmcnt(7)
	v_pk_mul_f32 v[14:15], v[14:15], v[30:31] op_sel_hi:[1,0]
	ds_write2_b32 v53, v14, v15 offset1:1
	v_pk_mul_f32 v[14:15], v[16:17], v[30:31] op_sel_hi:[1,0]
	ds_write2_b32 v53, v14, v15 offset0:2 offset1:3
	global_load_dword v14, v31, s[6:7] offset:32
	s_waitcnt vmcnt(0)
	v_pk_mul_f32 v[16:17], v[18:19], v[14:15] op_sel_hi:[1,0]
	v_add_u32_e32 v15, 0x420, v53
	ds_write2_b32 v15, v16, v17 offset1:1
	v_pk_mul_f32 v[14:15], v[20:21], v[14:15] op_sel_hi:[1,0]
	v_add_u32_e32 v16, 0x428, v53
	ds_write2_b32 v16, v14, v15 offset1:1
	global_load_dword v14, v31, s[6:7] offset:64
	v_add_u32_e32 v18, v33, v59
	s_waitcnt vmcnt(0)
	v_pk_mul_f32 v[16:17], v[22:23], v[14:15] op_sel_hi:[1,0]
	v_add_u32_e32 v15, 0x840, v53
	ds_write2_b32 v15, v16, v17 offset1:1
	v_pk_mul_f32 v[14:15], v[24:25], v[14:15] op_sel_hi:[1,0]
	v_add_u32_e32 v16, 0x848, v53
	ds_write2_b32 v16, v14, v15 offset1:1
	global_load_dword v14, v31, s[6:7] offset:96
	s_waitcnt vmcnt(0)
	v_pk_mul_f32 v[16:17], v[26:27], v[14:15] op_sel_hi:[1,0]
	v_add_u32_e32 v15, 0xc60, v53
	ds_write2_b32 v15, v16, v17 offset1:1
	v_pk_mul_f32 v[14:15], v[28:29], v[14:15] op_sel_hi:[1,0]
	v_add_u32_e32 v16, 0xc68, v53
	ds_write2_b32 v16, v14, v15 offset1:1
	global_load_dword v14, v31, s[6:7] offset:128
	s_waitcnt vmcnt(0)
	v_pk_mul_f32 v[16:17], v[64:65], v[14:15] op_sel_hi:[1,0]
	v_pk_mul_f32 v[14:15], v[66:67], v[14:15] op_sel_hi:[1,0]
	ds_write2_b32 v18, v14, v15 offset0:2 offset1:3
	global_load_dword v14, v31, s[6:7] offset:160
	ds_write2_b32 v18, v16, v17 offset1:1
	s_waitcnt vmcnt(0)
	v_pk_mul_f32 v[8:9], v[8:9], v[14:15] op_sel_hi:[1,0]
	v_add_u32_e32 v15, 0x420, v18
	ds_write2_b32 v15, v8, v9 offset1:1
	v_pk_mul_f32 v[8:9], v[10:11], v[14:15] op_sel_hi:[1,0]
	v_add_u32_e32 v10, 0x428, v18
	ds_write2_b32 v10, v8, v9 offset1:1
	global_load_dword v8, v31, s[6:7] offset:192
	s_waitcnt vmcnt(0)
; #define LAS __attribute__((address_space(3)))
; DI unsigned cvtpk(float lo, float hi) { f32x2 v = {lo, hi}; bf16x2_t b = __builtin_convertvector(v, bf16x2_t); return __builtin_bit_cast(unsigned, b); }
; template <int KIND> DI int map_n(int n) {
;     ...
;     if (KIND == 1) {
;         const int hd = n / 192, w = n % 192;
;         if (w < 128) return n;
;         const int j = w - 128; return hd * 192 + 128 + (j < 32 ? 2 * j : 2 * (j - 32) + 1);
;     }
; template <int KIND>
; DI void transpose_item(const float* W, int K, int N, bf16_t* WT, int ldk, const float* g0, const float* g1, const float* g2, LAS float* scr, int item, int lane) {
;     ...
;         LAS float* d = scr + kk * 33 + 4 * (lane & 7);
;         d[0] = tv[i][0] * gn; d[1] = tv[i][1] * gn; d[2] = tv[i][2] * gn; d[3] = tv[i][3] * gn;
;     }
;     asm volatile("s_waitcnt lgkmcnt(0)" ::: "memory");
;     int kd0 = k0;
;     if (KIND == 4) kd0 = k0 < 1024 ? k0 + 512 : (k0 < 1536 ? k0 - 1024 : k0);
;     const int c = lane & 7;
; #pragma unroll
;     for (int j = 0; j < 4; ++j) { const int n = (lane >> 3) + 8 * j; const LAS float* s = scr + (8 * c) * 33 + n;
;         u32x4 o; o.x = cvtpk(s[0 * 33], s[1 * 33]); o.y = cvtpk(s[2 * 33], s[3 * 33]); o.z = cvtpk(s[4 * 33], s[5 * 33]); o.w = cvtpk(s[6 * 33], s[7 * 33]);
;         *(u32x4*)(WT + (size_t)map_n<KIND>(n0 + n) * ldk + kd0 + 8 * c) = o; }
	v_pk_mul_f32 v[4:5], v[4:5], v[8:9] op_sel_hi:[1,0]
	v_add_u32_e32 v9, 0x840, v18
	ds_write2_b32 v9, v4, v5 offset1:1
	v_pk_mul_f32 v[4:5], v[6:7], v[8:9] op_sel_hi:[1,0]
	v_add_u32_e32 v6, 0x848, v18
	ds_write2_b32 v6, v4, v5 offset1:1
	global_load_dword v4, v31, s[6:7] offset:224
	s_waitcnt vmcnt(0)
	v_pk_mul_f32 v[0:1], v[0:1], v[4:5] op_sel_hi:[1,0]
	v_add_u32_e32 v5, 0xc60, v18
	ds_write2_b32 v5, v0, v1 offset1:1
	v_pk_mul_f32 v[0:1], v[2:3], v[4:5] op_sel_hi:[1,0]
	v_add_u32_e32 v2, 0xc68, v18
	ds_write2_b32 v2, v0, v1 offset1:1
	s_waitcnt lgkmcnt(0)
	ds_read2_b32 v[6:7], v58 offset0:33 offset1:41
	ds_read2_b32 v[8:9], v58 offset1:8
	ds_read2_b32 v[10:11], v58 offset0:66 offset1:74
	ds_read2_b32 v[14:15], v58 offset0:99 offset1:107
	ds_read2_b32 v[16:17], v58 offset0:132 offset1:140
	ds_read2_b32 v[18:19], v58 offset0:165 offset1:173
	ds_read2_b32 v[20:21], v58 offset0:198 offset1:206
	ds_read2_b32 v[22:23], v58 offset0:231 offset1:239
	v_lshl_add_u64 v[4:5], v[46:47], 0, v[128:129]
	s_waitcnt lgkmcnt(6)
	v_cvt_pk_bf16_f32 v0, v8, v6
	v_or_b32_e32 v6, v32, v12
	v_mul_u32_u24_e32 v8, 0x2aab, v6
	v_lshrrev_b32_e32 v8, 21, v8
	v_mul_lo_u16_e32 v8, 0xc0, v8
	v_sub_u16_e32 v8, v6, v8
	v_cmp_gt_u16_e64 s[6:7], s16, v8
	v_sub_u32_e32 v13, v6, v8
	s_waitcnt lgkmcnt(4)
	v_cvt_pk_bf16_f32 v1, v10, v14
	v_cmp_gt_u16_e32 vcc, s4, v8
	v_cndmask_b32_e64 v10, v201, v202, s[6:7]
	v_lshl_add_u32 v8, v8, 1, v13
	v_add3_u32 v8, v8, v10, s4
	v_cndmask_b32_e32 v24, v8, v6, vcc
	v_ashrrev_i32_e32 v25, 31, v24
	v_lshlrev_b64 v[24:25], 10, v[24:25]
	s_waitcnt lgkmcnt(2)
	v_cvt_pk_bf16_f32 v2, v16, v18
	s_waitcnt lgkmcnt(0)
	v_cvt_pk_bf16_f32 v3, v20, v22
	v_lshl_add_u64 v[24:25], v[4:5], 0, v[24:25]
	v_or_b32_e32 v6, v51, v12
	global_store_dwordx4 v[24:25], v[0:3], off
	s_nop 1
	v_cvt_pk_bf16_f32 v0, v9, v7
	v_mul_u32_u24_e32 v7, 0x2aab, v6
	v_lshrrev_b32_e32 v7, 21, v7
	v_mul_lo_u16_e32 v7, 0xc0, v7
	v_sub_u16_e32 v7, v6, v7
	v_cmp_gt_u16_e64 s[6:7], s16, v7
	v_sub_u32_e32 v9, v6, v7
	v_cmp_gt_u16_e32 vcc, s4, v7
	v_cndmask_b32_e64 v8, v201, v202, s[6:7]
	v_lshl_add_u32 v7, v7, 1, v9
	v_add3_u32 v7, v7, v8, s4
	v_cndmask_b32_e32 v6, v7, v6, vcc
	v_ashrrev_i32_e32 v7, 31, v6
	v_lshlrev_b64 v[6:7], 10, v[6:7]
	v_cvt_pk_bf16_f32 v1, v11, v15
	v_cvt_pk_bf16_f32 v2, v17, v19
	v_cvt_pk_bf16_f32 v3, v21, v23
	v_lshl_add_u64 v[6:7], v[4:5], 0, v[6:7]
	global_store_dwordx4 v[6:7], v[0:3], off
	ds_read2_b32 v[6:7], v58 offset0:16 offset1:24
	ds_read2_b32 v[8:9], v58 offset0:49 offset1:57
	ds_read2_b32 v[10:11], v58 offset0:82 offset1:90
	ds_read2_b32 v[14:15], v58 offset0:115 offset1:123
	ds_read2_b32 v[16:17], v58 offset0:148 offset1:156
	ds_read2_b32 v[18:19], v58 offset0:181 offset1:189
	ds_read2_b32 v[20:21], v58 offset0:214 offset1:222
	ds_read2_b32 v[22:23], v58 offset0:247 offset1:255
	s_waitcnt lgkmcnt(6)
	v_cvt_pk_bf16_f32 v0, v6, v8
	v_or_b32_e32 v6, v56, v12
	v_mul_u32_u24_e32 v8, 0x2aab, v6
	v_lshrrev_b32_e32 v8, 21, v8
	v_mul_lo_u16_e32 v8, 0xc0, v8
	v_sub_u16_e32 v8, v6, v8
	v_cmp_gt_u16_e64 s[6:7], s16, v8
	v_sub_u32_e32 v13, v6, v8
	s_waitcnt lgkmcnt(4)
	v_cvt_pk_bf16_f32 v1, v10, v14
	v_cmp_gt_u16_e32 vcc, s4, v8
	v_cndmask_b32_e64 v10, v201, v202, s[6:7]
	v_lshl_add_u32 v8, v8, 1, v13
	v_add3_u32 v8, v8, v10, s4
	v_cndmask_b32_e32 v24, v8, v6, vcc
	v_ashrrev_i32_e32 v25, 31, v24
	v_lshlrev_b64 v[24:25], 10, v[24:25]
	s_waitcnt lgkmcnt(2)
	v_cvt_pk_bf16_f32 v2, v16, v18
	s_waitcnt lgkmcnt(0)
	v_cvt_pk_bf16_f32 v3, v20, v22
	v_lshl_add_u64 v[24:25], v[4:5], 0, v[24:25]
	v_or_b32_e32 v6, v57, v12
	global_store_dwordx4 v[24:25], v[0:3], off
	s_nop 1
	v_cvt_pk_bf16_f32 v0, v7, v9
	v_mul_u32_u24_e32 v7, 0x2aab, v6
	v_lshrrev_b32_e32 v7, 21, v7
	v_mul_lo_u16_e32 v7, 0xc0, v7
	v_sub_u16_e32 v7, v6, v7
	v_cmp_gt_u16_e64 s[6:7], s16, v7
	v_sub_u32_e32 v9, v6, v7
	v_cmp_gt_u16_e32 vcc, s4, v7
	v_cndmask_b32_e64 v8, v201, v202, s[6:7]
	v_lshl_add_u32 v7, v7, 1, v9
	v_add3_u32 v7, v7, v8, s4
	v_cndmask_b32_e32 v6, v7, v6, vcc
	v_ashrrev_i32_e32 v7, 31, v6
	v_lshlrev_b64 v[6:7], 10, v[6:7]
	v_cvt_pk_bf16_f32 v1, v11, v15
	v_cvt_pk_bf16_f32 v2, v17, v19
	v_cvt_pk_bf16_f32 v3, v21, v23
	v_lshl_add_u64 v[4:5], v[4:5], 0, v[6:7]
	global_store_dwordx4 v[4:5], v[0:3], off
	s_waitcnt lgkmcnt(0)

; #define LAS __attribute__((address_space(3)))
; template <int KIND>
; DI void transpose_item(const float* W, int K, int N, bf16_t* WT, int ldk, const float* g0, const float* g1, const float* g2, LAS float* scr, int item, int lane) {
;     const int nblk = N / 32, kb = item / nblk, nb = item % nblk, k0 = 64 * kb, n0 = 32 * nb;
;     f32x4 tv[8];
; #pragma unroll
;     for (int i = 0; i < 8; ++i) tv[i] = *(const f32x4*)(W + (size_t)(k0 + 8 * i + (lane >> 3)) * N + n0 + 4 * (lane & 7));
; #pragma unroll
;     for (int i = 0; i < 8; ++i) {
;         const int kk = 8 * i + (lane >> 3), k = k0 + kk;
;         float gn = 1.f;
;         if (KIND == 0 || KIND == 1 || KIND == 2 || KIND == 5 || KIND == 6) gn = g0[k];
;         if (KIND == 4) gn = k < 1024 ? g0[k] : (k < 1536 ? g1[k - 1024] : g2[k - 1536]);
;         LAS float* d = scr + kk * 33 + 4 * (lane & 7);
;         d[0] = tv[i][0] * gn; d[1] = tv[i][1] * gn; d[2] = tv[i][2] * gn; d[3] = tv[i][3] * gn;
;     }
;     asm volatile("s_waitcnt lgkmcnt(0)" ::: "memory");
; DI void convert_weights(PP p, LAS unsigned char* lds, int l, int worker, int nworkers) {
;     ...
;         if (r < I_IN) { transpose_item<0>(p->in[2] + (size_t)l * 2048 * 2880, 2048, 2880, (bf16_t*)(wl + W_IN), 2048, p->in[1] + l * 2048, nullptr, nullptr, scr, r, lane); continue; } r -= I_IN;
.LBB0_1469:
	s_andn2_saveexec_b64 s[6:7], s[64:65]
	s_cbranch_execz .LBB0_1378
	s_load_dwordx4 s[16:19], s[8:9], 0x8
	v_readlane_b32 s14, v255, 1
	s_mul_i32 s4, s14, 0x1680000
	v_readlane_b32 s15, v255, 2
	v_lshlrev_b32_e32 v128, 2, v34
	s_waitcnt lgkmcnt(0)
	s_add_u32 s18, s18, s4
	s_mul_hi_u32 s4, s14, 0x1680000
	s_addc_u32 s19, s19, s4
	s_mov_b32 s4, 0xb60b60b7
	v_mul_hi_i32 v0, v62, s4
	v_add_u32_e32 v0, v0, v62
	v_lshrrev_b32_e32 v1, 31, v0
	v_ashrrev_i32_e32 v0, 6, v0
	s_lshl_b64 s[14:15], s[38:39], 2
	v_add_u32_e32 v16, v0, v1
	s_movk_i32 s4, 0x5a
	s_add_u32 s14, s16, s14
	v_mul_lo_u32 v0, v16, s4
	s_movk_i32 s4, 0xf4c0
	s_addc_u32 s15, s17, s15
	v_mad_u64_u32 v[8:9], s[16:17], v16, s4, v[50:51]
	v_sub_u32_e32 v0, v62, v0
	v_lshlrev_b32_e32 v10, 6, v16
	v_ashrrev_i32_e32 v9, 31, v8
	v_lshlrev_b32_e32 v17, 5, v0
	v_or_b32_e32 v30, v10, v32
	v_lshl_add_u64 v[0:1], v[8:9], 2, s[18:19]
	v_lshl_add_u64 v[0:1], v[0:1], 0, v[128:129]
	v_ashrrev_i32_e32 v31, 31, v30
	s_movk_i32 s4, 0x2d00
	v_mad_i64_i32 v[2:3], s[16:17], v30, s4, v[0:1]
	v_lshl_add_u64 v[54:55], v[30:31], 2, s[14:15]
	global_load_dwordx4 v[12:15], v[2:3], off nt
	v_add_u32_e32 v9, v33, v35
	global_load_dword v54, v[54:55], off
	v_ashrrev_i32_e32 v11, 31, v10
	v_or_b32_e32 v2, 8, v30
	v_mov_b32_e32 v31, v11
	v_mad_i64_i32 v[2:3], s[16:17], v2, s4, v[0:1]
	global_load_dwordx4 v[18:21], v[2:3], off nt
	v_or_b32_e32 v2, 16, v30
	v_mad_i64_i32 v[2:3], s[16:17], v2, s4, v[0:1]
	global_load_dwordx4 v[22:25], v[2:3], off nt
	v_or_b32_e32 v2, 24, v30
	v_mad_i64_i32 v[2:3], s[16:17], v2, s4, v[0:1]
	global_load_dwordx4 v[26:29], v[2:3], off nt
	v_or_b32_e32 v2, 32, v30
	v_mad_i64_i32 v[2:3], s[16:17], v2, s4, v[0:1]
	global_load_dwordx4 v[64:67], v[2:3], off nt
	v_or_b32_e32 v2, 40, v30
	v_mad_i64_i32 v[2:3], s[16:17], v2, s4, v[0:1]
	global_load_dwordx4 v[68:71], v[2:3], off nt
	v_or_b32_e32 v2, 48, v30
	v_mad_i64_i32 v[2:3], s[16:17], v2, s4, v[0:1]
	global_load_dwordx4 v[4:7], v[2:3], off nt
	v_or_b32_e32 v2, 56, v30
	v_mad_i64_i32 v[0:1], s[16:17], v2, s4, v[0:1]
	global_load_dwordx4 v[0:3], v[0:1], off nt
	s_movk_i32 s4, 0x2ff
	s_waitcnt vmcnt(7)
	v_pk_mul_f32 v[12:13], v[12:13], v[54:55] op_sel_hi:[1,0]
	ds_write2_b32 v9, v12, v13 offset1:1
	v_pk_mul_f32 v[12:13], v[14:15], v[54:55] op_sel_hi:[1,0]
	ds_write2_b32 v9, v12, v13 offset0:2 offset1:3
	v_lshl_add_u64 v[12:13], v[30:31], 2, s[14:15]
	global_load_dword v14, v[12:13], off offset:32
	s_waitcnt vmcnt(0)
	v_pk_mul_f32 v[18:19], v[18:19], v[14:15] op_sel_hi:[1,0]
	v_add_u32_e32 v15, 0x420, v9
	ds_write2_b32 v15, v18, v19 offset1:1
	v_pk_mul_f32 v[14:15], v[20:21], v[14:15] op_sel_hi:[1,0]
	v_add_u32_e32 v18, 0x428, v9
	ds_write2_b32 v18, v14, v15 offset1:1
	global_load_dword v14, v[12:13], off offset:64
	s_waitcnt vmcnt(0)
	v_pk_mul_f32 v[18:19], v[22:23], v[14:15] op_sel_hi:[1,0]
	v_add_u32_e32 v15, 0x840, v9
	ds_write2_b32 v15, v18, v19 offset1:1
	v_pk_mul_f32 v[14:15], v[24:25], v[14:15] op_sel_hi:[1,0]
	v_add_u32_e32 v18, 0x848, v9
	ds_write2_b32 v18, v14, v15 offset1:1
	global_load_dword v14, v[12:13], off offset:96
	s_waitcnt vmcnt(0)
	v_pk_mul_f32 v[18:19], v[26:27], v[14:15] op_sel_hi:[1,0]
	v_add_u32_e32 v15, 0xc60, v9
	ds_write2_b32 v15, v18, v19 offset1:1
	v_pk_mul_f32 v[14:15], v[28:29], v[14:15] op_sel_hi:[1,0]
	v_add_u32_e32 v9, 0xc68, v9
	ds_write2_b32 v9, v14, v15 offset1:1
	global_load_dword v14, v[12:13], off offset:128
	v_add_u32_e32 v9, v33, v59
	s_waitcnt vmcnt(0)
	v_pk_mul_f32 v[18:19], v[64:65], v[14:15] op_sel_hi:[1,0]
	v_pk_mul_f32 v[14:15], v[66:67], v[14:15] op_sel_hi:[1,0]
	ds_write2_b32 v9, v14, v15 offset0:2 offset1:3
	global_load_dword v14, v[12:13], off offset:160
	ds_write2_b32 v9, v18, v19 offset1:1
	s_waitcnt vmcnt(0)
	v_pk_mul_f32 v[18:19], v[68:69], v[14:15] op_sel_hi:[1,0]
	v_add_u32_e32 v15, 0x420, v9
	ds_write2_b32 v15, v18, v19 offset1:1
	v_pk_mul_f32 v[14:15], v[70:71], v[14:15] op_sel_hi:[1,0]
	v_add_u32_e32 v18, 0x428, v9
	ds_write2_b32 v18, v14, v15 offset1:1
	global_load_dword v14, v[12:13], off offset:192
	s_waitcnt vmcnt(0)
	v_pk_mul_f32 v[4:5], v[4:5], v[14:15] op_sel_hi:[1,0]
	v_add_u32_e32 v15, 0x840, v9
	ds_write2_b32 v15, v4, v5 offset1:1
	v_pk_mul_f32 v[4:5], v[6:7], v[14:15] op_sel_hi:[1,0]
	v_add_u32_e32 v6, 0x848, v9
	ds_write2_b32 v6, v4, v5 offset1:1
	global_load_dword v4, v[12:13], off offset:224
	v_or_b32_e32 v14, v17, v32
	s_waitcnt vmcnt(0)
	v_pk_mul_f32 v[0:1], v[0:1], v[4:5] op_sel_hi:[1,0]
	v_add_u32_e32 v5, 0xc60, v9
	ds_write2_b32 v5, v0, v1 offset1:1
	v_pk_mul_f32 v[0:1], v[2:3], v[4:5] op_sel_hi:[1,0]
	v_add_u32_e32 v2, 0xc68, v9
	ds_write2_b32 v2, v0, v1 offset1:1
	s_waitcnt lgkmcnt(0)
	ds_read2_b32 v[2:3], v58 offset1:33
	ds_read2_b32 v[4:5], v58 offset0:66 offset1:99
	ds_read2_b32 v[6:7], v58 offset0:132 offset1:165
	ds_read2_b32 v[12:13], v58 offset0:198 offset1:231
	v_add_u32_e32 v9, v8, v32
	v_cmp_lt_i32_e32 vcc, s4, v9
	s_and_saveexec_b64 s[14:15], vcc
	s_cbranch_execz .LBB0_1476
	s_movk_i32 s4, 0x33f
	v_cmp_lt_u32_e32 vcc, s4, v8
	s_and_saveexec_b64 s[16:17], vcc
	s_xor_b64 s[16:17], exec, s[16:17]
	v_subrev_u32_e32 v14, 64, v14
	s_andn2_saveexec_b64 s[16:17], s[16:17]
	s_movk_i32 s4, 0x320
	v_cmp_gt_u32_e32 vcc, s4, v8
	s_movk_i32 s4, 0x1680
	v_mul_lo_u32 v1, v16, s4
	v_cndmask_b32_e32 v0, v203, v204, vcc
	v_sub_u32_e32 v0, v0, v1
	s_movk_i32 s4, 0xffd0
	v_add3_u32 v14, v60, v0, s4
	s_or_b64 exec, exec, s[16:17]
